# GEMM K-loops: 2 of the 6 LDS-DMA stage loads of the heavy load segment issued inside the following MFMA block (vmcnt 8->6 there)
# speedup vs baseline: 1.0186x; 1.0011x over previous
; #define PG8_STAGE(bufoff, gbase, voff) do { _Pragma("unroll") for (int _i = 0; _i < 2; ++_i) \
;         __builtin_amdgcn_global_load_lds((const unsigned*)((const char*)(gbase) + (voff)[_i]), (PG8_LAS unsigned*)(lds + (bufoff) + ldsw + _i * 8192), 16, 0, 0); } while (0)
; #define PG8_LDA(dst, b, h) do { _Pragma("unroll") for (int m = 0; m < 4; ++m) _Pragma("unroll") for (int k = 0; k < 2; ++k) dst[m][k] = *(const PG8_LAS bf16x8*)(lds + PG8_SA(b, h) + aoff + m * 2048 + k * 1024); } while (0)
; #define PG8_LDB(dst, b, h) do { _Pragma("unroll") for (int n = 0; n < 2; ++n) _Pragma("unroll") for (int k = 0; k < 2; ++k) dst[n][k] = *(const PG8_LAS bf16x8*)(lds + PG8_SB(b, h) + boff + n * 2048 + k * 1024); } while (0)
; #define PG8_MMA(ai, bj, At, Bt) do { __builtin_amdgcn_s_setprio(1); _Pragma("unroll") for (int m = 0; m < 4; ++m) _Pragma("unroll") for (int n = 0; n < 2; ++n) _Pragma("unroll") for (int k = 0; k < 2; ++k) \
;         acc[ai][bj][m][n] = __builtin_amdgcn_mfma_f32_16x16x32_bf16(Bt[n][k], At[m][k], acc[ai][bj][m][n], 0, 0, 0); __builtin_amdgcn_s_setprio(0); } while (0)
; #define PG8_WAIT_V(n) asm volatile("s_waitcnt vmcnt(" #n ")" ::: "memory")
; template <class Epi, class Sched, bool ALIGN_EPI = false, bool SP2 = false>
; __device__ __forceinline__ void gemm_phase(PG8_LAS unsigned char* lds, const Gemm g, const Sched& S, const Epi& E) {
;     ...
;         const char* nA = has_next ? (const char*)g.A + (size_t)nxt.pm * tstep : cA; const char* nB = has_next ? (const char*)g.Bt + (size_t)nxt.pn * tstep : cB;
;         for (int t = 0; t < nt; t += 2) {
;             const bool last = (t == nt - 2);
;             const char* a1 = cA + (size_t)(t + 1) * kstep;
;             const char* a2 = last ? nA : cA + (size_t)(t + 2) * kstep; const char* b2 = last ? nB : cB + (size_t)(t + 2) * kstep;
;             const char* a3 = a2 + kstep; const char* b3 = b2 + kstep;
;             if (last && has_next) S.a_ready(nxt);
;             if constexpr (SP2) {
;             PG8_LDB(B0, 0, 0); PG8_LDB(B1, 0, 1); PG8_SCHED; PG8_LDA(At, 0, 0); PG8_STAGE(PG8_SA(1, 1), a1 + hstep, voffA);
;             PG8_WAIT_V(8); PG8_WAIT_L(0); PG8_BAR; PG8_MMA(0, 0, At, B0); PG8_MMA(0, 1, At, B1); PG8_BAR; PG8_SCHED;
;             PG8_LDA(At, 0, 1); PG8_STAGE(PG8_SB(0, 0), b2, voffB); PG8_STAGE(PG8_SB(0, 1), b2 + hstep, voffB); PG8_STAGE(PG8_SA(0, 0), a2, voffA);
.LBB0_192:
	ds_read_b128 v[152:155], v149
	ds_read_b128 v[156:159], v149 offset:1024
	ds_read_b128 v[160:163], v149 offset:2048
	ds_read_b128 v[164:167], v149 offset:3072
	ds_read_b128 v[168:171], v150
	ds_read_b128 v[172:175], v150 offset:1024
	ds_read_b128 v[176:179], v150 offset:2048
	ds_read_b128 v[182:185], v150 offset:3072
	s_add_u32 s44, s42, 0xfffc0080
	s_addc_u32 s45, s43, -1
	s_cmp_eq_u32 s92, 12
	s_cselect_b32 s47, s23, s45
	s_cselect_b32 s46, s88, s44
	s_cselect_b32 s45, s21, s91
	s_cselect_b32 s44, s89, s90
	v_lshl_add_u64 v[144:145], s[42:43], 0, v[136:137]
	s_add_i32 m0, s41, 0xc000
	ds_read_b128 v[186:189], v151
	ds_read_b128 v[192:195], v151 offset:1024
	ds_read_b128 v[196:199], v151 offset:2048
	ds_read_b128 v[200:203], v151 offset:3072
	ds_read_b128 v[204:207], v151 offset:4096
	ds_read_b128 v[208:211], v151 offset:5120
	ds_read_b128 v[212:215], v151 offset:6144
	ds_read_b128 v[216:219], v151 offset:7168
	global_load_lds_dwordx4 v[144:145], off
	v_lshl_add_u64 v[144:145], s[42:43], 0, v[138:139]
	s_add_i32 m0, s41, 0xe000
	s_nop 0
	global_load_lds_dwordx4 v[144:145], off
	s_waitcnt vmcnt(8)
	s_waitcnt lgkmcnt(0)
	s_barrier
	s_setprio 1
	s_waitcnt lgkmcnt(0)
	v_mfma_f32_16x16x32_bf16 v[124:127], v[152:155], v[186:189], v[124:127]
	v_mfma_f32_16x16x32_bf16 v[116:119], v[160:163], v[186:189], v[116:119]
	v_mfma_f32_16x16x32_bf16 v[108:111], v[152:155], v[196:199], v[108:111]
	v_mfma_f32_16x16x32_bf16 v[100:103], v[160:163], v[196:199], v[100:103]
	v_mfma_f32_16x16x32_bf16 v[92:95], v[152:155], v[204:207], v[92:95]
	v_mfma_f32_16x16x32_bf16 v[84:87], v[160:163], v[204:207], v[84:87]
	v_mfma_f32_16x16x32_bf16 v[76:79], v[152:155], v[212:215], v[76:79]
	v_mfma_f32_16x16x32_bf16 v[68:71], v[160:163], v[212:215], v[68:71]
	v_mfma_f32_16x16x32_bf16 v[124:127], v[156:159], v[192:195], v[124:127]
	v_mfma_f32_16x16x32_bf16 v[116:119], v[164:167], v[192:195], v[116:119]
	v_mfma_f32_16x16x32_bf16 v[108:111], v[156:159], v[200:203], v[108:111]
	v_mfma_f32_16x16x32_bf16 v[100:103], v[164:167], v[200:203], v[100:103]
	v_mfma_f32_16x16x32_bf16 v[92:95], v[156:159], v[208:211], v[92:95]
	v_mfma_f32_16x16x32_bf16 v[84:87], v[164:167], v[208:211], v[84:87]
	v_mfma_f32_16x16x32_bf16 v[76:79], v[156:159], v[216:219], v[76:79]
	v_mfma_f32_16x16x32_bf16 v[68:71], v[164:167], v[216:219], v[68:71]
	s_setprio 0
	s_setprio 1
	v_mfma_f32_16x16x32_bf16 v[120:123], v[168:171], v[186:189], v[120:123]
	v_mfma_f32_16x16x32_bf16 v[112:115], v[176:179], v[186:189], v[112:115]
	v_mfma_f32_16x16x32_bf16 v[104:107], v[168:171], v[196:199], v[104:107]
	v_mfma_f32_16x16x32_bf16 v[96:99], v[176:179], v[196:199], v[96:99]
	v_mfma_f32_16x16x32_bf16 v[88:91], v[168:171], v[204:207], v[88:91]
	v_mfma_f32_16x16x32_bf16 v[80:83], v[176:179], v[204:207], v[80:83]
	v_mfma_f32_16x16x32_bf16 v[72:75], v[168:171], v[212:215], v[72:75]
	v_mfma_f32_16x16x32_bf16 v[64:67], v[176:179], v[212:215], v[64:67]
	v_mfma_f32_16x16x32_bf16 v[120:123], v[172:175], v[192:195], v[120:123]
	v_mfma_f32_16x16x32_bf16 v[112:115], v[182:185], v[192:195], v[112:115]
	v_mfma_f32_16x16x32_bf16 v[104:107], v[172:175], v[200:203], v[104:107]
	v_mfma_f32_16x16x32_bf16 v[96:99], v[182:185], v[200:203], v[96:99]
	v_mfma_f32_16x16x32_bf16 v[88:91], v[172:175], v[208:211], v[88:91]
	v_mfma_f32_16x16x32_bf16 v[80:83], v[182:185], v[208:211], v[80:83]
	v_mfma_f32_16x16x32_bf16 v[72:75], v[172:175], v[216:219], v[72:75]
	v_mfma_f32_16x16x32_bf16 v[64:67], v[182:185], v[216:219], v[64:67]
	s_setprio 0
	s_barrier
	s_add_i32 s93, s84, s48
	v_lshl_add_u64 v[144:145], s[44:45], 0, v[132:133]
	s_mov_b32 m0, s93
	ds_read_b128 v[186:189], v151 offset:16384
	ds_read_b128 v[192:195], v151 offset:17408
	ds_read_b128 v[196:199], v151 offset:18432
	ds_read_b128 v[200:203], v151 offset:19456
	ds_read_b128 v[204:207], v151 offset:20480
	ds_read_b128 v[208:211], v151 offset:21504
	ds_read_b128 v[212:215], v151 offset:22528
	ds_read_b128 v[216:219], v151 offset:23552
	global_load_lds_dwordx4 v[144:145], off
	s_add_i32 m0, s93, 0x2000
	s_add_u32 s94, s44, 0x40000
	v_lshl_add_u64 v[220:221], s[44:45], 0, v[128:129]
	s_addc_u32 s95, s45, 0
	s_add_i32 s93, s85, s48
	global_load_lds_dwordx4 v[220:221], off
	v_lshl_add_u64 v[222:223], s[94:95], 0, v[132:133]
	s_mov_b32 m0, s93
	v_lshl_add_u64 v[224:225], s[46:47], 0, v[130:131]
	global_load_lds_dwordx4 v[222:223], off
	v_lshl_add_u64 v[222:223], s[94:95], 0, v[128:129]
	s_add_i32 m0, s93, 0x2000
	s_nop 0
	global_load_lds_dwordx4 v[222:223], off
	s_waitcnt vmcnt(6)
	s_waitcnt lgkmcnt(0)
	s_barrier
; #define PG8_STAGE(bufoff, gbase, voff) do { _Pragma("unroll") for (int _i = 0; _i < 2; ++_i) \
;         __builtin_amdgcn_global_load_lds((const unsigned*)((const char*)(gbase) + (voff)[_i]), (PG8_LAS unsigned*)(lds + (bufoff) + ldsw + _i * 8192), 16, 0, 0); } while (0)
; #define PG8_LDA(dst, b, h) do { _Pragma("unroll") for (int m = 0; m < 4; ++m) _Pragma("unroll") for (int k = 0; k < 2; ++k) dst[m][k] = *(const PG8_LAS bf16x8*)(lds + PG8_SA(b, h) + aoff + m * 2048 + k * 1024); } while (0)
; #define PG8_LDB(dst, b, h) do { _Pragma("unroll") for (int n = 0; n < 2; ++n) _Pragma("unroll") for (int k = 0; k < 2; ++k) dst[n][k] = *(const PG8_LAS bf16x8*)(lds + PG8_SB(b, h) + boff + n * 2048 + k * 1024); } while (0)
; #define PG8_MMA(ai, bj, At, Bt) do { __builtin_amdgcn_s_setprio(1); _Pragma("unroll") for (int m = 0; m < 4; ++m) _Pragma("unroll") for (int n = 0; n < 2; ++n) _Pragma("unroll") for (int k = 0; k < 2; ++k) \
;         acc[ai][bj][m][n] = __builtin_amdgcn_mfma_f32_16x16x32_bf16(Bt[n][k], At[m][k], acc[ai][bj][m][n], 0, 0, 0); __builtin_amdgcn_s_setprio(0); } while (0)
; #define PG8_WAIT_V(n) asm volatile("s_waitcnt vmcnt(" #n ")" ::: "memory")
; #define PG8_WAIT_L(n) asm volatile("s_waitcnt lgkmcnt(" #n ")" ::: "memory")
; #define PG8_BAR __builtin_amdgcn_s_barrier()
; #define PG8_SCHED __builtin_amdgcn_sched_barrier(0)
; template <class Epi, class Sched, bool ALIGN_EPI = false, bool SP2 = false>
; __device__ __forceinline__ void gemm_phase(PG8_LAS unsigned char* lds, const Gemm g, const Sched& S, const Epi& E) {
;     ...
;             PG8_WAIT_V(8); PG8_WAIT_L(0); PG8_BAR; PG8_MMA(0, 0, At, B0); PG8_MMA(0, 1, At, B1); PG8_BAR; PG8_SCHED;
;             PG8_LDA(At, 0, 1); PG8_STAGE(PG8_SB(0, 0), b2, voffB); PG8_STAGE(PG8_SB(0, 1), b2 + hstep, voffB); PG8_STAGE(PG8_SA(0, 0), a2, voffA);
;             PG8_WAIT_V(8); PG8_WAIT_L(0); PG8_BAR; PG8_MMA(1, 0, At, B0); PG8_MMA(1, 1, At, B1); PG8_BAR; PG8_SCHED;
;             PG8_LDB(B0, 1, 0); PG8_LDB(B1, 1, 1); PG8_SCHED; PG8_LDA(At, 1, 0); PG8_STAGE(PG8_SA(0, 1), a2 + hstep, voffA);
;             PG8_WAIT_V(8); PG8_WAIT_L(0); PG8_BAR; PG8_MMA(0, 0, At, B0); PG8_MMA(0, 1, At, B1); PG8_BAR; PG8_SCHED;
	s_setprio 1
	s_waitcnt lgkmcnt(0)
	v_mfma_f32_16x16x32_bf16 v[60:63], v[152:155], v[186:189], v[60:63]
	v_mfma_f32_16x16x32_bf16 v[52:55], v[160:163], v[186:189], v[52:55]
	v_mfma_f32_16x16x32_bf16 v[44:47], v[152:155], v[196:199], v[44:47]
	v_mfma_f32_16x16x32_bf16 v[36:39], v[160:163], v[196:199], v[36:39]
	v_mfma_f32_16x16x32_bf16 v[28:31], v[152:155], v[204:207], v[28:31]
	v_mfma_f32_16x16x32_bf16 v[20:23], v[160:163], v[204:207], v[20:23]
	v_lshl_add_u64 v[222:223], s[46:47], 0, v[134:135]
	s_mov_b32 m0, s41
	s_nop 0
	global_load_lds_dwordx4 v[222:223], off
	v_mfma_f32_16x16x32_bf16 v[12:15], v[152:155], v[212:215], v[12:15]
	v_mfma_f32_16x16x32_bf16 v[4:7], v[160:163], v[212:215], v[4:7]
	v_mfma_f32_16x16x32_bf16 v[60:63], v[156:159], v[192:195], v[60:63]
	v_mfma_f32_16x16x32_bf16 v[52:55], v[164:167], v[192:195], v[52:55]
	v_mfma_f32_16x16x32_bf16 v[44:47], v[156:159], v[200:203], v[44:47]
	v_mfma_f32_16x16x32_bf16 v[36:39], v[164:167], v[200:203], v[36:39]
	v_mfma_f32_16x16x32_bf16 v[28:31], v[156:159], v[208:211], v[28:31]
	v_mfma_f32_16x16x32_bf16 v[20:23], v[164:167], v[208:211], v[20:23]
	v_mfma_f32_16x16x32_bf16 v[12:15], v[156:159], v[216:219], v[12:15]
	v_mfma_f32_16x16x32_bf16 v[4:7], v[164:167], v[216:219], v[4:7]
	s_setprio 0
	s_setprio 1
	v_mfma_f32_16x16x32_bf16 v[56:59], v[168:171], v[186:189], v[56:59]
	v_mfma_f32_16x16x32_bf16 v[48:51], v[176:179], v[186:189], v[48:51]
	v_mfma_f32_16x16x32_bf16 v[40:43], v[168:171], v[196:199], v[40:43]
	v_mfma_f32_16x16x32_bf16 v[32:35], v[176:179], v[196:199], v[32:35]
	v_mfma_f32_16x16x32_bf16 v[24:27], v[168:171], v[204:207], v[24:27]
	v_mfma_f32_16x16x32_bf16 v[16:19], v[176:179], v[204:207], v[16:19]
	s_mov_b32 m0, s61
	s_nop 0
	global_load_lds_dwordx4 v[224:225], off
	v_mfma_f32_16x16x32_bf16 v[8:11], v[168:171], v[212:215], v[8:11]
	v_mfma_f32_16x16x32_bf16 v[0:3], v[176:179], v[212:215], v[0:3]
	v_mfma_f32_16x16x32_bf16 v[56:59], v[172:175], v[192:195], v[56:59]
	v_mfma_f32_16x16x32_bf16 v[48:51], v[182:185], v[192:195], v[48:51]
	v_mfma_f32_16x16x32_bf16 v[40:43], v[172:175], v[200:203], v[40:43]
	v_mfma_f32_16x16x32_bf16 v[32:35], v[182:185], v[200:203], v[32:35]
	v_mfma_f32_16x16x32_bf16 v[24:27], v[172:175], v[208:211], v[24:27]
	v_mfma_f32_16x16x32_bf16 v[16:19], v[182:185], v[208:211], v[16:19]
	v_mfma_f32_16x16x32_bf16 v[8:11], v[172:175], v[216:219], v[8:11]
	v_mfma_f32_16x16x32_bf16 v[0:3], v[182:185], v[216:219], v[0:3]
	s_setprio 0
	s_barrier
	s_add_i32 s93, 0, 0x18000
	s_add_i32 s94, 0, 0x1c000
	v_add_u32_e32 v164, s93, v147
	v_add_u32_e32 v181, s94, v147
	ds_read_b128 v[152:155], v164
	ds_read_b128 v[156:159], v164 offset:1024
	ds_read_b128 v[160:163], v164 offset:2048
	ds_read_b128 v[164:167], v164 offset:3072
	ds_read_b128 v[168:171], v181
	ds_read_b128 v[172:175], v181 offset:1024
	ds_read_b128 v[176:179], v181 offset:2048
	ds_read_b128 v[182:185], v181 offset:3072
	s_add_u32 s46, s46, 0x40000
	s_addc_u32 s47, s47, 0
	s_mov_b32 m0, s78
	v_lshl_add_u64 v[226:227], s[46:47], 0, v[134:135]
	ds_read_b128 v[186:189], v151 offset:32768
	ds_read_b128 v[192:195], v151 offset:33792
	ds_read_b128 v[196:199], v151 offset:34816
	ds_read_b128 v[200:203], v151 offset:35840
	ds_read_b128 v[204:207], v151 offset:36864
	ds_read_b128 v[208:211], v151 offset:37888
	ds_read_b128 v[212:215], v151 offset:38912
	ds_read_b128 v[216:219], v151 offset:39936
	global_load_lds_dwordx4 v[226:227], off
	v_lshl_add_u64 v[226:227], s[46:47], 0, v[130:131]
	s_mov_b32 m0, s79
	s_nop 0
	global_load_lds_dwordx4 v[226:227], off
	s_waitcnt vmcnt(8)
	s_waitcnt lgkmcnt(0)
	s_barrier
	s_setprio 1
	s_waitcnt lgkmcnt(0)
	v_mfma_f32_16x16x32_bf16 v[124:127], v[152:155], v[186:189], v[124:127]
	v_mfma_f32_16x16x32_bf16 v[116:119], v[160:163], v[186:189], v[116:119]
	v_mfma_f32_16x16x32_bf16 v[108:111], v[152:155], v[196:199], v[108:111]
	v_mfma_f32_16x16x32_bf16 v[100:103], v[160:163], v[196:199], v[100:103]
	v_mfma_f32_16x16x32_bf16 v[92:95], v[152:155], v[204:207], v[92:95]
	v_mfma_f32_16x16x32_bf16 v[84:87], v[160:163], v[204:207], v[84:87]
	v_mfma_f32_16x16x32_bf16 v[76:79], v[152:155], v[212:215], v[76:79]
	v_mfma_f32_16x16x32_bf16 v[68:71], v[160:163], v[212:215], v[68:71]
	v_mfma_f32_16x16x32_bf16 v[124:127], v[156:159], v[192:195], v[124:127]
	v_mfma_f32_16x16x32_bf16 v[116:119], v[164:167], v[192:195], v[116:119]
	v_mfma_f32_16x16x32_bf16 v[108:111], v[156:159], v[200:203], v[108:111]
	v_mfma_f32_16x16x32_bf16 v[100:103], v[164:167], v[200:203], v[100:103]
	v_mfma_f32_16x16x32_bf16 v[92:95], v[156:159], v[208:211], v[92:95]
	v_mfma_f32_16x16x32_bf16 v[84:87], v[164:167], v[208:211], v[84:87]
	v_mfma_f32_16x16x32_bf16 v[76:79], v[156:159], v[216:219], v[76:79]
	v_mfma_f32_16x16x32_bf16 v[68:71], v[164:167], v[216:219], v[68:71]
	s_setprio 0
	s_setprio 1
	v_mfma_f32_16x16x32_bf16 v[120:123], v[168:171], v[186:189], v[120:123]
	v_mfma_f32_16x16x32_bf16 v[112:115], v[176:179], v[186:189], v[112:115]
	v_mfma_f32_16x16x32_bf16 v[104:107], v[168:171], v[196:199], v[104:107]
	v_mfma_f32_16x16x32_bf16 v[96:99], v[176:179], v[196:199], v[96:99]
	v_mfma_f32_16x16x32_bf16 v[88:91], v[168:171], v[204:207], v[88:91]
	v_mfma_f32_16x16x32_bf16 v[80:83], v[176:179], v[204:207], v[80:83]
	v_mfma_f32_16x16x32_bf16 v[72:75], v[168:171], v[212:215], v[72:75]
	v_mfma_f32_16x16x32_bf16 v[64:67], v[176:179], v[212:215], v[64:67]
	v_mfma_f32_16x16x32_bf16 v[120:123], v[172:175], v[192:195], v[120:123]
	v_mfma_f32_16x16x32_bf16 v[112:115], v[182:185], v[192:195], v[112:115]
	v_mfma_f32_16x16x32_bf16 v[104:107], v[172:175], v[200:203], v[104:107]
	v_mfma_f32_16x16x32_bf16 v[96:99], v[182:185], v[200:203], v[96:99]
	v_mfma_f32_16x16x32_bf16 v[88:91], v[172:175], v[208:211], v[88:91]
	v_mfma_f32_16x16x32_bf16 v[80:83], v[182:185], v[208:211], v[80:83]
	v_mfma_f32_16x16x32_bf16 v[72:75], v[172:175], v[216:219], v[72:75]
	v_mfma_f32_16x16x32_bf16 v[64:67], v[182:185], v[216:219], v[64:67]
	s_setprio 0
	s_barrier
; #define PG8_STAGE(bufoff, gbase, voff) do { _Pragma("unroll") for (int _i = 0; _i < 2; ++_i) \
;         __builtin_amdgcn_global_load_lds((const unsigned*)((const char*)(gbase) + (voff)[_i]), (PG8_LAS unsigned*)(lds + (bufoff) + ldsw + _i * 8192), 16, 0, 0); } while (0)
; #define PG8_LDA(dst, b, h) do { _Pragma("unroll") for (int m = 0; m < 4; ++m) _Pragma("unroll") for (int k = 0; k < 2; ++k) dst[m][k] = *(const PG8_LAS bf16x8*)(lds + PG8_SA(b, h) + aoff + m * 2048 + k * 1024); } while (0)
; #define PG8_MMA(ai, bj, At, Bt) do { __builtin_amdgcn_s_setprio(1); _Pragma("unroll") for (int m = 0; m < 4; ++m) _Pragma("unroll") for (int n = 0; n < 2; ++n) _Pragma("unroll") for (int k = 0; k < 2; ++k) \
;         acc[ai][bj][m][n] = __builtin_amdgcn_mfma_f32_16x16x32_bf16(Bt[n][k], At[m][k], acc[ai][bj][m][n], 0, 0, 0); __builtin_amdgcn_s_setprio(0); } while (0)
; #define PG8_WAIT_V(n) asm volatile("s_waitcnt vmcnt(" #n ")" ::: "memory")
; #define PG8_WAIT_L(n) asm volatile("s_waitcnt lgkmcnt(" #n ")" ::: "memory")
; #define PG8_BAR __builtin_amdgcn_s_barrier()
; #define PG8_SCHED __builtin_amdgcn_sched_barrier(0)
; template <class Epi, class Sched, bool ALIGN_EPI = false, bool SP2 = false>
; __device__ __forceinline__ void gemm_phase(PG8_LAS unsigned char* lds, const Gemm g, const Sched& S, const Epi& E) {
;     ...
;             PG8_LDA(At, 1, 1); PG8_STAGE(PG8_SB(1, 0), b3, voffB); PG8_STAGE(PG8_SB(1, 1), b3 + hstep, voffB); PG8_STAGE(PG8_SA(1, 0), a3, voffA);
;             PG8_WAIT_V(8); PG8_WAIT_L(0); PG8_BAR; PG8_MMA(1, 0, At, B0); PG8_MMA(1, 1, At, B1); PG8_BAR; PG8_SCHED;
;     ...
;         if constexpr (ALIGN_EPI) { if (wr == 0) PG8_BAR; }
	s_add_i32 s46, s93, s48
	v_lshl_add_u64 v[144:145], v[144:145], 0, s[6:7]
	s_mov_b32 m0, s46
	ds_read_b128 v[186:189], v151 offset:49152
	ds_read_b128 v[192:195], v151 offset:50176
	ds_read_b128 v[196:199], v151 offset:51200
	ds_read_b128 v[200:203], v151 offset:52224
	ds_read_b128 v[204:207], v151 offset:53248
	ds_read_b128 v[208:211], v151 offset:54272
	ds_read_b128 v[212:215], v151 offset:55296
	ds_read_b128 v[216:219], v151 offset:56320
	global_load_lds_dwordx4 v[144:145], off
	s_add_i32 m0, s46, 0x2000
	s_add_u32 s44, s44, 0x40080
	v_lshl_add_u64 v[144:145], v[220:221], 0, s[6:7]
	s_addc_u32 s45, s45, 0
	s_add_i32 s46, s94, s48
	global_load_lds_dwordx4 v[144:145], off
	v_lshl_add_u64 v[144:145], s[44:45], 0, v[132:133]
	s_mov_b32 m0, s46
	s_nop 0
	global_load_lds_dwordx4 v[144:145], off
	v_lshl_add_u64 v[144:145], s[44:45], 0, v[128:129]
	s_add_i32 m0, s46, 0x2000
	s_nop 0
	global_load_lds_dwordx4 v[144:145], off
	s_waitcnt vmcnt(6)
	s_waitcnt lgkmcnt(0)
	s_barrier
	s_setprio 1
	s_waitcnt lgkmcnt(0)
	v_mfma_f32_16x16x32_bf16 v[60:63], v[152:155], v[186:189], v[60:63]
	v_mfma_f32_16x16x32_bf16 v[52:55], v[160:163], v[186:189], v[52:55]
	v_mfma_f32_16x16x32_bf16 v[44:47], v[152:155], v[196:199], v[44:47]
	v_mfma_f32_16x16x32_bf16 v[36:39], v[160:163], v[196:199], v[36:39]
	v_mfma_f32_16x16x32_bf16 v[28:31], v[152:155], v[204:207], v[28:31]
	v_mfma_f32_16x16x32_bf16 v[20:23], v[160:163], v[204:207], v[20:23]
	v_lshl_add_u64 v[144:145], v[222:223], 0, s[6:7]
	s_mov_b32 m0, s81
	s_nop 0
	global_load_lds_dwordx4 v[144:145], off
	v_mfma_f32_16x16x32_bf16 v[12:15], v[152:155], v[212:215], v[12:15]
	v_mfma_f32_16x16x32_bf16 v[4:7], v[160:163], v[212:215], v[4:7]
	v_mfma_f32_16x16x32_bf16 v[60:63], v[156:159], v[192:195], v[60:63]
	v_mfma_f32_16x16x32_bf16 v[52:55], v[164:167], v[192:195], v[52:55]
	v_mfma_f32_16x16x32_bf16 v[44:47], v[156:159], v[200:203], v[44:47]
	v_mfma_f32_16x16x32_bf16 v[36:39], v[164:167], v[200:203], v[36:39]
	v_mfma_f32_16x16x32_bf16 v[28:31], v[156:159], v[208:211], v[28:31]
	v_mfma_f32_16x16x32_bf16 v[20:23], v[164:167], v[208:211], v[20:23]
	v_mfma_f32_16x16x32_bf16 v[12:15], v[156:159], v[216:219], v[12:15]
	v_mfma_f32_16x16x32_bf16 v[4:7], v[164:167], v[216:219], v[4:7]
	s_setprio 0
	s_setprio 1
	v_mfma_f32_16x16x32_bf16 v[56:59], v[168:171], v[186:189], v[56:59]
	v_mfma_f32_16x16x32_bf16 v[48:51], v[176:179], v[186:189], v[48:51]
	v_mfma_f32_16x16x32_bf16 v[40:43], v[168:171], v[196:199], v[40:43]
	v_mfma_f32_16x16x32_bf16 v[32:35], v[176:179], v[196:199], v[32:35]
	v_mfma_f32_16x16x32_bf16 v[24:27], v[168:171], v[204:207], v[24:27]
	v_mfma_f32_16x16x32_bf16 v[16:19], v[176:179], v[204:207], v[16:19]
	v_lshl_add_u64 v[144:145], v[224:225], 0, s[6:7]
	s_mov_b32 m0, s82
	s_nop 0
	global_load_lds_dwordx4 v[144:145], off
	v_mfma_f32_16x16x32_bf16 v[8:11], v[168:171], v[212:215], v[8:11]
	v_mfma_f32_16x16x32_bf16 v[0:3], v[176:179], v[212:215], v[0:3]
	v_mfma_f32_16x16x32_bf16 v[56:59], v[172:175], v[192:195], v[56:59]
	v_mfma_f32_16x16x32_bf16 v[48:51], v[182:185], v[192:195], v[48:51]
	v_mfma_f32_16x16x32_bf16 v[40:43], v[172:175], v[200:203], v[40:43]
	v_mfma_f32_16x16x32_bf16 v[32:35], v[182:185], v[200:203], v[32:35]
	v_mfma_f32_16x16x32_bf16 v[24:27], v[172:175], v[208:211], v[24:27]
	v_mfma_f32_16x16x32_bf16 v[16:19], v[182:185], v[208:211], v[16:19]
	v_mfma_f32_16x16x32_bf16 v[8:11], v[172:175], v[216:219], v[8:11]
	v_mfma_f32_16x16x32_bf16 v[0:3], v[182:185], v[216:219], v[0:3]
	s_setprio 0
	s_barrier
	s_add_i32 s92, s92, 2
	s_add_u32 s42, s42, 0x100
	s_addc_u32 s43, s43, 0
	s_add_u32 s90, s90, 0x100
	s_addc_u32 s91, s91, 0
	s_cmp_gt_u32 s92, 13
	s_cbranch_scc0 .LBB0_192
	s_and_b64 vcc, exec, s[18:19]
	s_cbranch_vccz .LBB0_195
	s_barrier

; #define PG8_STAGE(bufoff, gbase, voff) do { _Pragma("unroll") for (int _i = 0; _i < 2; ++_i) \
;         __builtin_amdgcn_global_load_lds((const unsigned*)((const char*)(gbase) + (voff)[_i]), (PG8_LAS unsigned*)(lds + (bufoff) + ldsw + _i * 8192), 16, 0, 0); } while (0)
; #define PG8_LDA(dst, b, h) do { _Pragma("unroll") for (int m = 0; m < 4; ++m) _Pragma("unroll") for (int k = 0; k < 2; ++k) dst[m][k] = *(const PG8_LAS bf16x8*)(lds + PG8_SA(b, h) + aoff + m * 2048 + k * 1024); } while (0)
; #define PG8_LDB(dst, b, h) do { _Pragma("unroll") for (int n = 0; n < 2; ++n) _Pragma("unroll") for (int k = 0; k < 2; ++k) dst[n][k] = *(const PG8_LAS bf16x8*)(lds + PG8_SB(b, h) + boff + n * 2048 + k * 1024); } while (0)
; #define PG8_MMA(ai, bj, At, Bt) do { __builtin_amdgcn_s_setprio(1); _Pragma("unroll") for (int m = 0; m < 4; ++m) _Pragma("unroll") for (int n = 0; n < 2; ++n) _Pragma("unroll") for (int k = 0; k < 2; ++k) \
;         acc[ai][bj][m][n] = __builtin_amdgcn_mfma_f32_16x16x32_bf16(Bt[n][k], At[m][k], acc[ai][bj][m][n], 0, 0, 0); __builtin_amdgcn_s_setprio(0); } while (0)
; #define PG8_WAIT_V(n) asm volatile("s_waitcnt vmcnt(" #n ")" ::: "memory")
; template <class Epi, class Sched, bool ALIGN_EPI = false, bool SP2 = false>
; __device__ __forceinline__ void gemm_phase(PG8_LAS unsigned char* lds, const Gemm g, const Sched& S, const Epi& E) {
;     ...
;         const char* nA = has_next ? (const char*)g.A + (size_t)nxt.pm * tstep : cA; const char* nB = has_next ? (const char*)g.Bt + (size_t)nxt.pn * tstep : cB;
;         for (int t = 0; t < nt; t += 2) {
;             const bool last = (t == nt - 2);
;             const char* a1 = cA + (size_t)(t + 1) * kstep;
;             const char* a2 = last ? nA : cA + (size_t)(t + 2) * kstep; const char* b2 = last ? nB : cB + (size_t)(t + 2) * kstep;
;             const char* a3 = a2 + kstep; const char* b3 = b2 + kstep;
;             if (last && has_next) S.a_ready(nxt);
;             if constexpr (SP2) {
;             PG8_LDB(B0, 0, 0); PG8_LDB(B1, 0, 1); PG8_SCHED; PG8_LDA(At, 0, 0); PG8_STAGE(PG8_SA(1, 1), a1 + hstep, voffA);
;             PG8_WAIT_V(8); PG8_WAIT_L(0); PG8_BAR; PG8_MMA(0, 0, At, B0); PG8_MMA(0, 1, At, B1); PG8_BAR; PG8_SCHED;
;             PG8_LDA(At, 0, 1); PG8_STAGE(PG8_SB(0, 0), b2, voffB); PG8_STAGE(PG8_SB(0, 1), b2 + hstep, voffB); PG8_STAGE(PG8_SA(0, 0), a2, voffA);
.LBB0_266:
	ds_read_b128 v[128:131], v171
	ds_read_b128 v[132:135], v171 offset:1024
	ds_read_b128 v[136:139], v171 offset:2048
	ds_read_b128 v[140:143], v171 offset:3072
	ds_read_b128 v[160:163], v172
	ds_read_b128 v[164:167], v172 offset:1024
	ds_read_b128 v[176:179], v172 offset:2048
	ds_read_b128 v[182:185], v172 offset:3072
	s_add_u32 s22, s20, 0xfff50080
	s_addc_u32 s23, s21, -1
	s_cmp_eq_u32 s86, 40
	s_cselect_b32 s25, s1, s23
	s_cselect_b32 s24, s0, s22
	s_cselect_b32 s23, s7, s85
	s_cselect_b32 s22, s6, s84
	v_lshl_add_u64 v[220:221], s[20:21], 0, v[152:153]
	s_add_i32 m0, s40, 0xc000
	ds_read_b128 v[186:189], v173
	ds_read_b128 v[192:195], v173 offset:1024
	ds_read_b128 v[196:199], v173 offset:2048
	ds_read_b128 v[200:203], v173 offset:3072
	ds_read_b128 v[204:207], v173 offset:4096
	ds_read_b128 v[208:211], v173 offset:5120
	ds_read_b128 v[212:215], v173 offset:6144
	ds_read_b128 v[216:219], v173 offset:7168
	global_load_lds_dwordx4 v[220:221], off
	v_lshl_add_u64 v[220:221], s[20:21], 0, v[154:155]
	s_add_i32 m0, s40, 0xe000
	s_nop 0
	global_load_lds_dwordx4 v[220:221], off
	s_waitcnt vmcnt(8)
	s_waitcnt lgkmcnt(0)
	s_barrier
	s_setprio 1
	s_waitcnt lgkmcnt(0)
	v_mfma_f32_16x16x32_bf16 v[124:127], v[128:131], v[186:189], v[124:127]
	v_mfma_f32_16x16x32_bf16 v[120:123], v[136:139], v[186:189], v[120:123]
	v_mfma_f32_16x16x32_bf16 v[108:111], v[128:131], v[196:199], v[108:111]
	v_mfma_f32_16x16x32_bf16 v[104:107], v[136:139], v[196:199], v[104:107]
	v_mfma_f32_16x16x32_bf16 v[92:95], v[128:131], v[204:207], v[92:95]
	v_mfma_f32_16x16x32_bf16 v[88:91], v[136:139], v[204:207], v[88:91]
	v_mfma_f32_16x16x32_bf16 v[76:79], v[128:131], v[212:215], v[76:79]
	v_mfma_f32_16x16x32_bf16 v[72:75], v[136:139], v[212:215], v[72:75]
	v_mfma_f32_16x16x32_bf16 v[124:127], v[132:135], v[192:195], v[124:127]
	v_mfma_f32_16x16x32_bf16 v[120:123], v[140:143], v[192:195], v[120:123]
	v_mfma_f32_16x16x32_bf16 v[108:111], v[132:135], v[200:203], v[108:111]
	v_mfma_f32_16x16x32_bf16 v[104:107], v[140:143], v[200:203], v[104:107]
	v_mfma_f32_16x16x32_bf16 v[92:95], v[132:135], v[208:211], v[92:95]
	v_mfma_f32_16x16x32_bf16 v[88:91], v[140:143], v[208:211], v[88:91]
	v_mfma_f32_16x16x32_bf16 v[76:79], v[132:135], v[216:219], v[76:79]
	v_mfma_f32_16x16x32_bf16 v[72:75], v[140:143], v[216:219], v[72:75]
	s_setprio 0
	s_setprio 1
	v_mfma_f32_16x16x32_bf16 v[116:119], v[160:163], v[186:189], v[116:119]
	v_mfma_f32_16x16x32_bf16 v[112:115], v[176:179], v[186:189], v[112:115]
	v_mfma_f32_16x16x32_bf16 v[100:103], v[160:163], v[196:199], v[100:103]
	v_mfma_f32_16x16x32_bf16 v[96:99], v[176:179], v[196:199], v[96:99]
	v_mfma_f32_16x16x32_bf16 v[84:87], v[160:163], v[204:207], v[84:87]
	v_mfma_f32_16x16x32_bf16 v[80:83], v[176:179], v[204:207], v[80:83]
	v_mfma_f32_16x16x32_bf16 v[68:71], v[160:163], v[212:215], v[68:71]
	v_mfma_f32_16x16x32_bf16 v[64:67], v[176:179], v[212:215], v[64:67]
	v_mfma_f32_16x16x32_bf16 v[116:119], v[164:167], v[192:195], v[116:119]
	v_mfma_f32_16x16x32_bf16 v[112:115], v[182:185], v[192:195], v[112:115]
	v_mfma_f32_16x16x32_bf16 v[100:103], v[164:167], v[200:203], v[100:103]
	v_mfma_f32_16x16x32_bf16 v[96:99], v[182:185], v[200:203], v[96:99]
	v_mfma_f32_16x16x32_bf16 v[84:87], v[164:167], v[208:211], v[84:87]
	v_mfma_f32_16x16x32_bf16 v[80:83], v[182:185], v[208:211], v[80:83]
	v_mfma_f32_16x16x32_bf16 v[68:71], v[164:167], v[216:219], v[68:71]
	v_mfma_f32_16x16x32_bf16 v[64:67], v[182:185], v[216:219], v[64:67]
	s_setprio 0
	s_barrier
	s_add_i32 s87, s78, s27
	v_lshl_add_u64 v[220:221], s[22:23], 0, v[146:147]
	s_mov_b32 m0, s87
	ds_read_b128 v[186:189], v173 offset:16384
	ds_read_b128 v[192:195], v173 offset:17408
	ds_read_b128 v[196:199], v173 offset:18432
	ds_read_b128 v[200:203], v173 offset:19456
	ds_read_b128 v[204:207], v173 offset:20480
	ds_read_b128 v[208:211], v173 offset:21504
	ds_read_b128 v[212:215], v173 offset:22528
	ds_read_b128 v[216:219], v173 offset:23552
	global_load_lds_dwordx4 v[220:221], off
	s_add_i32 m0, s87, 0x2000
	s_add_u32 s88, s22, 0xb0000
	v_lshl_add_u64 v[222:223], s[22:23], 0, v[150:151]
	s_addc_u32 s89, s23, 0
	s_add_i32 s87, s79, s27
	global_load_lds_dwordx4 v[222:223], off
	v_lshl_add_u64 v[224:225], s[88:89], 0, v[146:147]
	s_mov_b32 m0, s87
	v_lshl_add_u64 v[226:227], s[24:25], 0, v[148:149]
	global_load_lds_dwordx4 v[224:225], off
	v_lshl_add_u64 v[224:225], s[88:89], 0, v[150:151]
	s_add_i32 m0, s87, 0x2000
	s_nop 0
	global_load_lds_dwordx4 v[224:225], off
	s_waitcnt vmcnt(6)
	s_waitcnt lgkmcnt(0)
	s_barrier
; #define PG8_STAGE(bufoff, gbase, voff) do { _Pragma("unroll") for (int _i = 0; _i < 2; ++_i) \
;         __builtin_amdgcn_global_load_lds((const unsigned*)((const char*)(gbase) + (voff)[_i]), (PG8_LAS unsigned*)(lds + (bufoff) + ldsw + _i * 8192), 16, 0, 0); } while (0)
; #define PG8_LDA(dst, b, h) do { _Pragma("unroll") for (int m = 0; m < 4; ++m) _Pragma("unroll") for (int k = 0; k < 2; ++k) dst[m][k] = *(const PG8_LAS bf16x8*)(lds + PG8_SA(b, h) + aoff + m * 2048 + k * 1024); } while (0)
; #define PG8_LDB(dst, b, h) do { _Pragma("unroll") for (int n = 0; n < 2; ++n) _Pragma("unroll") for (int k = 0; k < 2; ++k) dst[n][k] = *(const PG8_LAS bf16x8*)(lds + PG8_SB(b, h) + boff + n * 2048 + k * 1024); } while (0)
; #define PG8_MMA(ai, bj, At, Bt) do { __builtin_amdgcn_s_setprio(1); _Pragma("unroll") for (int m = 0; m < 4; ++m) _Pragma("unroll") for (int n = 0; n < 2; ++n) _Pragma("unroll") for (int k = 0; k < 2; ++k) \
;         acc[ai][bj][m][n] = __builtin_amdgcn_mfma_f32_16x16x32_bf16(Bt[n][k], At[m][k], acc[ai][bj][m][n], 0, 0, 0); __builtin_amdgcn_s_setprio(0); } while (0)
; #define PG8_WAIT_V(n) asm volatile("s_waitcnt vmcnt(" #n ")" ::: "memory")
; #define PG8_WAIT_L(n) asm volatile("s_waitcnt lgkmcnt(" #n ")" ::: "memory")
; #define PG8_BAR __builtin_amdgcn_s_barrier()
; #define PG8_SCHED __builtin_amdgcn_sched_barrier(0)
; template <class Epi, class Sched, bool ALIGN_EPI = false, bool SP2 = false>
; __device__ __forceinline__ void gemm_phase(PG8_LAS unsigned char* lds, const Gemm g, const Sched& S, const Epi& E) {
;     ...
;             PG8_WAIT_V(8); PG8_WAIT_L(0); PG8_BAR; PG8_MMA(1, 0, At, B0); PG8_MMA(1, 1, At, B1); PG8_BAR; PG8_SCHED;
;             PG8_LDB(B0, 1, 0); PG8_LDB(B1, 1, 1); PG8_SCHED; PG8_LDA(At, 1, 0); PG8_STAGE(PG8_SA(0, 1), a2 + hstep, voffA);
;             PG8_WAIT_V(8); PG8_WAIT_L(0); PG8_BAR; PG8_MMA(0, 0, At, B0); PG8_MMA(0, 1, At, B1); PG8_BAR; PG8_SCHED;
	s_setprio 1
	s_waitcnt lgkmcnt(0)
	v_mfma_f32_16x16x32_bf16 v[60:63], v[128:131], v[186:189], v[60:63]
	v_mfma_f32_16x16x32_bf16 v[56:59], v[136:139], v[186:189], v[56:59]
	v_mfma_f32_16x16x32_bf16 v[44:47], v[128:131], v[196:199], v[44:47]
	v_mfma_f32_16x16x32_bf16 v[40:43], v[136:139], v[196:199], v[40:43]
	v_mfma_f32_16x16x32_bf16 v[28:31], v[128:131], v[204:207], v[28:31]
	v_mfma_f32_16x16x32_bf16 v[24:27], v[136:139], v[204:207], v[24:27]
	v_lshl_add_u64 v[224:225], s[24:25], 0, v[144:145]
	s_mov_b32 m0, s40
	s_nop 0
	global_load_lds_dwordx4 v[224:225], off
	v_mfma_f32_16x16x32_bf16 v[12:15], v[128:131], v[212:215], v[12:15]
	v_mfma_f32_16x16x32_bf16 v[8:11], v[136:139], v[212:215], v[8:11]
	v_mfma_f32_16x16x32_bf16 v[60:63], v[132:135], v[192:195], v[60:63]
	v_mfma_f32_16x16x32_bf16 v[56:59], v[140:143], v[192:195], v[56:59]
	v_mfma_f32_16x16x32_bf16 v[44:47], v[132:135], v[200:203], v[44:47]
	v_mfma_f32_16x16x32_bf16 v[40:43], v[140:143], v[200:203], v[40:43]
	v_mfma_f32_16x16x32_bf16 v[28:31], v[132:135], v[208:211], v[28:31]
	v_mfma_f32_16x16x32_bf16 v[24:27], v[140:143], v[208:211], v[24:27]
	v_mfma_f32_16x16x32_bf16 v[12:15], v[132:135], v[216:219], v[12:15]
	v_mfma_f32_16x16x32_bf16 v[8:11], v[140:143], v[216:219], v[8:11]
	s_setprio 0
	s_setprio 1
	v_mfma_f32_16x16x32_bf16 v[52:55], v[160:163], v[186:189], v[52:55]
	v_mfma_f32_16x16x32_bf16 v[48:51], v[176:179], v[186:189], v[48:51]
	v_mfma_f32_16x16x32_bf16 v[36:39], v[160:163], v[196:199], v[36:39]
	v_mfma_f32_16x16x32_bf16 v[32:35], v[176:179], v[196:199], v[32:35]
	v_mfma_f32_16x16x32_bf16 v[20:23], v[160:163], v[204:207], v[20:23]
	v_mfma_f32_16x16x32_bf16 v[16:19], v[176:179], v[204:207], v[16:19]
	s_mov_b32 m0, s41
	s_nop 0
	global_load_lds_dwordx4 v[226:227], off
	v_mfma_f32_16x16x32_bf16 v[4:7], v[160:163], v[212:215], v[4:7]
	v_mfma_f32_16x16x32_bf16 v[0:3], v[176:179], v[212:215], v[0:3]
	v_mfma_f32_16x16x32_bf16 v[52:55], v[164:167], v[192:195], v[52:55]
	v_mfma_f32_16x16x32_bf16 v[48:51], v[182:185], v[192:195], v[48:51]
	v_mfma_f32_16x16x32_bf16 v[36:39], v[164:167], v[200:203], v[36:39]
	v_mfma_f32_16x16x32_bf16 v[32:35], v[182:185], v[200:203], v[32:35]
	v_mfma_f32_16x16x32_bf16 v[20:23], v[164:167], v[208:211], v[20:23]
	v_mfma_f32_16x16x32_bf16 v[16:19], v[182:185], v[208:211], v[16:19]
	v_mfma_f32_16x16x32_bf16 v[4:7], v[164:167], v[216:219], v[4:7]
	v_mfma_f32_16x16x32_bf16 v[0:3], v[182:185], v[216:219], v[0:3]
	s_setprio 0
	s_barrier
	s_add_i32 s87, 0, 0x18000
	s_add_i32 s88, 0, 0x1c000
	v_add_u32_e32 v140, s87, v169
	v_add_u32_e32 v175, s88, v169
	ds_read_b128 v[128:131], v140
	ds_read_b128 v[132:135], v140 offset:1024
	ds_read_b128 v[136:139], v140 offset:2048
	ds_read_b128 v[140:143], v140 offset:3072
	ds_read_b128 v[160:163], v175
	ds_read_b128 v[164:167], v175 offset:1024
	ds_read_b128 v[176:179], v175 offset:2048
	ds_read_b128 v[182:185], v175 offset:3072
	s_add_u32 s24, s24, 0xb0000
	s_addc_u32 s25, s25, 0
	s_mov_b32 m0, s42
	v_lshl_add_u64 v[228:229], s[24:25], 0, v[144:145]
	ds_read_b128 v[186:189], v173 offset:32768
	ds_read_b128 v[192:195], v173 offset:33792
	ds_read_b128 v[196:199], v173 offset:34816
	ds_read_b128 v[200:203], v173 offset:35840
	ds_read_b128 v[204:207], v173 offset:36864
	ds_read_b128 v[208:211], v173 offset:37888
	ds_read_b128 v[212:215], v173 offset:38912
	ds_read_b128 v[216:219], v173 offset:39936
	global_load_lds_dwordx4 v[228:229], off
	v_lshl_add_u64 v[228:229], s[24:25], 0, v[148:149]
	s_mov_b32 m0, s43
	s_nop 0
	global_load_lds_dwordx4 v[228:229], off
	s_waitcnt vmcnt(8)
	s_waitcnt lgkmcnt(0)
	s_barrier
	s_setprio 1
	s_waitcnt lgkmcnt(0)
	v_mfma_f32_16x16x32_bf16 v[124:127], v[128:131], v[186:189], v[124:127]
	v_mfma_f32_16x16x32_bf16 v[120:123], v[136:139], v[186:189], v[120:123]
	v_mfma_f32_16x16x32_bf16 v[108:111], v[128:131], v[196:199], v[108:111]
	v_mfma_f32_16x16x32_bf16 v[104:107], v[136:139], v[196:199], v[104:107]
	v_mfma_f32_16x16x32_bf16 v[92:95], v[128:131], v[204:207], v[92:95]
	v_mfma_f32_16x16x32_bf16 v[88:91], v[136:139], v[204:207], v[88:91]
	v_mfma_f32_16x16x32_bf16 v[76:79], v[128:131], v[212:215], v[76:79]
	v_mfma_f32_16x16x32_bf16 v[72:75], v[136:139], v[212:215], v[72:75]
	v_mfma_f32_16x16x32_bf16 v[124:127], v[132:135], v[192:195], v[124:127]
	v_mfma_f32_16x16x32_bf16 v[120:123], v[140:143], v[192:195], v[120:123]
	v_mfma_f32_16x16x32_bf16 v[108:111], v[132:135], v[200:203], v[108:111]
	v_mfma_f32_16x16x32_bf16 v[104:107], v[140:143], v[200:203], v[104:107]
	v_mfma_f32_16x16x32_bf16 v[92:95], v[132:135], v[208:211], v[92:95]
	v_mfma_f32_16x16x32_bf16 v[88:91], v[140:143], v[208:211], v[88:91]
	v_mfma_f32_16x16x32_bf16 v[76:79], v[132:135], v[216:219], v[76:79]
	v_mfma_f32_16x16x32_bf16 v[72:75], v[140:143], v[216:219], v[72:75]
	s_setprio 0
	s_setprio 1
	v_mfma_f32_16x16x32_bf16 v[116:119], v[160:163], v[186:189], v[116:119]
	v_mfma_f32_16x16x32_bf16 v[112:115], v[176:179], v[186:189], v[112:115]
	v_mfma_f32_16x16x32_bf16 v[100:103], v[160:163], v[196:199], v[100:103]
	v_mfma_f32_16x16x32_bf16 v[96:99], v[176:179], v[196:199], v[96:99]
	v_mfma_f32_16x16x32_bf16 v[84:87], v[160:163], v[204:207], v[84:87]
	v_mfma_f32_16x16x32_bf16 v[80:83], v[176:179], v[204:207], v[80:83]
	v_mfma_f32_16x16x32_bf16 v[68:71], v[160:163], v[212:215], v[68:71]
	v_mfma_f32_16x16x32_bf16 v[64:67], v[176:179], v[212:215], v[64:67]
	v_mfma_f32_16x16x32_bf16 v[116:119], v[164:167], v[192:195], v[116:119]
	v_mfma_f32_16x16x32_bf16 v[112:115], v[182:185], v[192:195], v[112:115]
	v_mfma_f32_16x16x32_bf16 v[100:103], v[164:167], v[200:203], v[100:103]
	v_mfma_f32_16x16x32_bf16 v[96:99], v[182:185], v[200:203], v[96:99]
	v_mfma_f32_16x16x32_bf16 v[84:87], v[164:167], v[208:211], v[84:87]
	v_mfma_f32_16x16x32_bf16 v[80:83], v[182:185], v[208:211], v[80:83]
	v_mfma_f32_16x16x32_bf16 v[68:71], v[164:167], v[216:219], v[68:71]
	v_mfma_f32_16x16x32_bf16 v[64:67], v[182:185], v[216:219], v[64:67]
	s_setprio 0
	s_barrier
; #define PG8_STAGE(bufoff, gbase, voff) do { _Pragma("unroll") for (int _i = 0; _i < 2; ++_i) \
;         __builtin_amdgcn_global_load_lds((const unsigned*)((const char*)(gbase) + (voff)[_i]), (PG8_LAS unsigned*)(lds + (bufoff) + ldsw + _i * 8192), 16, 0, 0); } while (0)
; #define PG8_LDA(dst, b, h) do { _Pragma("unroll") for (int m = 0; m < 4; ++m) _Pragma("unroll") for (int k = 0; k < 2; ++k) dst[m][k] = *(const PG8_LAS bf16x8*)(lds + PG8_SA(b, h) + aoff + m * 2048 + k * 1024); } while (0)
; #define PG8_MMA(ai, bj, At, Bt) do { __builtin_amdgcn_s_setprio(1); _Pragma("unroll") for (int m = 0; m < 4; ++m) _Pragma("unroll") for (int n = 0; n < 2; ++n) _Pragma("unroll") for (int k = 0; k < 2; ++k) \
;         acc[ai][bj][m][n] = __builtin_amdgcn_mfma_f32_16x16x32_bf16(Bt[n][k], At[m][k], acc[ai][bj][m][n], 0, 0, 0); __builtin_amdgcn_s_setprio(0); } while (0)
; #define PG8_WAIT_V(n) asm volatile("s_waitcnt vmcnt(" #n ")" ::: "memory")
; #define PG8_WAIT_L(n) asm volatile("s_waitcnt lgkmcnt(" #n ")" ::: "memory")
; #define PG8_BAR __builtin_amdgcn_s_barrier()
; #define PG8_SCHED __builtin_amdgcn_sched_barrier(0)
; template <class Epi, class Sched, bool ALIGN_EPI = false, bool SP2 = false>
; __device__ __forceinline__ void gemm_phase(PG8_LAS unsigned char* lds, const Gemm g, const Sched& S, const Epi& E) {
;     ...
;         for (int t = 0; t < nt; t += 2) {
;             const bool last = (t == nt - 2);
;             const char* a1 = cA + (size_t)(t + 1) * kstep;
;             const char* a2 = last ? nA : cA + (size_t)(t + 2) * kstep; const char* b2 = last ? nB : cB + (size_t)(t + 2) * kstep;
;     ...
;             PG8_LDA(At, 1, 1); PG8_STAGE(PG8_SB(1, 0), b3, voffB); PG8_STAGE(PG8_SB(1, 1), b3 + hstep, voffB); PG8_STAGE(PG8_SA(1, 0), a3, voffA);
;             PG8_WAIT_V(8); PG8_WAIT_L(0); PG8_BAR; PG8_MMA(1, 0, At, B0); PG8_MMA(1, 1, At, B1); PG8_BAR; PG8_SCHED;
	s_add_i32 s24, s87, s27
	v_lshl_add_u64 v[220:221], v[220:221], 0, s[18:19]
	s_mov_b32 m0, s24
	ds_read_b128 v[186:189], v173 offset:49152
	ds_read_b128 v[192:195], v173 offset:50176
	ds_read_b128 v[196:199], v173 offset:51200
	ds_read_b128 v[200:203], v173 offset:52224
	ds_read_b128 v[204:207], v173 offset:53248
	ds_read_b128 v[208:211], v173 offset:54272
	ds_read_b128 v[212:215], v173 offset:55296
	ds_read_b128 v[216:219], v173 offset:56320
	global_load_lds_dwordx4 v[220:221], off
	s_add_i32 m0, s24, 0x2000
	s_add_u32 s22, s22, 0xb0080
	v_lshl_add_u64 v[220:221], v[222:223], 0, s[18:19]
	s_addc_u32 s23, s23, 0
	s_add_i32 s24, s88, s27
	global_load_lds_dwordx4 v[220:221], off
	v_lshl_add_u64 v[220:221], s[22:23], 0, v[146:147]
	s_mov_b32 m0, s24
	s_nop 0
	global_load_lds_dwordx4 v[220:221], off
	v_lshl_add_u64 v[220:221], s[22:23], 0, v[150:151]
	s_add_i32 m0, s24, 0x2000
	s_nop 0
	global_load_lds_dwordx4 v[220:221], off
	s_waitcnt vmcnt(6)
	s_waitcnt lgkmcnt(0)
	s_barrier
	s_setprio 1
	s_waitcnt lgkmcnt(0)
	v_mfma_f32_16x16x32_bf16 v[60:63], v[128:131], v[186:189], v[60:63]
	v_mfma_f32_16x16x32_bf16 v[56:59], v[136:139], v[186:189], v[56:59]
	v_mfma_f32_16x16x32_bf16 v[44:47], v[128:131], v[196:199], v[44:47]
	v_mfma_f32_16x16x32_bf16 v[40:43], v[136:139], v[196:199], v[40:43]
	v_mfma_f32_16x16x32_bf16 v[28:31], v[128:131], v[204:207], v[28:31]
	v_mfma_f32_16x16x32_bf16 v[24:27], v[136:139], v[204:207], v[24:27]
	v_lshl_add_u64 v[220:221], v[224:225], 0, s[18:19]
	s_mov_b32 m0, s45
	s_nop 0
	global_load_lds_dwordx4 v[220:221], off
	v_mfma_f32_16x16x32_bf16 v[12:15], v[128:131], v[212:215], v[12:15]
	v_mfma_f32_16x16x32_bf16 v[8:11], v[136:139], v[212:215], v[8:11]
	v_mfma_f32_16x16x32_bf16 v[60:63], v[132:135], v[192:195], v[60:63]
	v_mfma_f32_16x16x32_bf16 v[56:59], v[140:143], v[192:195], v[56:59]
	v_mfma_f32_16x16x32_bf16 v[44:47], v[132:135], v[200:203], v[44:47]
	v_mfma_f32_16x16x32_bf16 v[40:43], v[140:143], v[200:203], v[40:43]
	v_mfma_f32_16x16x32_bf16 v[28:31], v[132:135], v[208:211], v[28:31]
	v_mfma_f32_16x16x32_bf16 v[24:27], v[140:143], v[208:211], v[24:27]
	v_mfma_f32_16x16x32_bf16 v[12:15], v[132:135], v[216:219], v[12:15]
	v_mfma_f32_16x16x32_bf16 v[8:11], v[140:143], v[216:219], v[8:11]
	s_setprio 0
	s_setprio 1
	v_mfma_f32_16x16x32_bf16 v[52:55], v[160:163], v[186:189], v[52:55]
	v_mfma_f32_16x16x32_bf16 v[48:51], v[176:179], v[186:189], v[48:51]
	v_mfma_f32_16x16x32_bf16 v[36:39], v[160:163], v[196:199], v[36:39]
	v_mfma_f32_16x16x32_bf16 v[32:35], v[176:179], v[196:199], v[32:35]
	v_mfma_f32_16x16x32_bf16 v[20:23], v[160:163], v[204:207], v[20:23]
	v_mfma_f32_16x16x32_bf16 v[16:19], v[176:179], v[204:207], v[16:19]
	v_lshl_add_u64 v[220:221], v[226:227], 0, s[18:19]
	s_mov_b32 m0, s46
	s_nop 0
	global_load_lds_dwordx4 v[220:221], off
	v_mfma_f32_16x16x32_bf16 v[4:7], v[160:163], v[212:215], v[4:7]
	v_mfma_f32_16x16x32_bf16 v[0:3], v[176:179], v[212:215], v[0:3]
	v_mfma_f32_16x16x32_bf16 v[52:55], v[164:167], v[192:195], v[52:55]
	v_mfma_f32_16x16x32_bf16 v[48:51], v[182:185], v[192:195], v[48:51]
	v_mfma_f32_16x16x32_bf16 v[36:39], v[164:167], v[200:203], v[36:39]
	v_mfma_f32_16x16x32_bf16 v[32:35], v[182:185], v[200:203], v[32:35]
	v_mfma_f32_16x16x32_bf16 v[20:23], v[164:167], v[208:211], v[20:23]
	v_mfma_f32_16x16x32_bf16 v[16:19], v[182:185], v[208:211], v[16:19]
	v_mfma_f32_16x16x32_bf16 v[4:7], v[164:167], v[216:219], v[4:7]
	v_mfma_f32_16x16x32_bf16 v[0:3], v[182:185], v[216:219], v[0:3]
	s_setprio 0
	s_barrier
	s_add_i32 s86, s86, 2
	s_add_u32 s20, s20, 0x100
	s_addc_u32 s21, s21, 0
	s_add_u32 s84, s84, 0x100
	s_addc_u32 s85, s85, 0
	s_cmp_gt_u32 s86, 41
	s_cbranch_scc0 .LBB0_266
; __device__ __forceinline__ u32x2 pack4(f32x4 v) { u32x2 w; w.x = cvt_pk_bf16(v[0], v[1]); w.y = cvt_pk_bf16(v[2], v[3]); return w; }
;     __device__ __forceinline__ void operator()(const f32x4 (&acc)[2][2][4][2], const Unit& u, int wr, int wc, int fr, int fq) const {
;         const int row0 = u.pm * BM + wr * 64 + fr, col0 = u.pn * BM + wc * 32 + 8 * fq;
;         const float* base = (u.pm * BM < split) ? base0 : base1; bf16_t* const xn = (bf16_t*)(ws + WS_XN); float* const ssq = (float*)(ws + WS_SSQ);
; #pragma unroll
;         for (int ai = 0; ai < 2; ++ai)
; #pragma unroll
;         for (int mh = 0; mh < 4; mh += 2) {
;             f32x4 pre[4][2][2];
; #pragma unroll
;             for (int m = mh; m < mh + 2; ++m)
; #pragma unroll
;                 for (int bj = 0; bj < 2; ++bj)
; #pragma unroll
;                     for (int n = 0; n < 2; ++n) pre[m][bj][n] = *(const f32x4*)(base + (size_t)(row0 + ai * HALF + m * 16) * 1024 + col0 + bj * HALF + n * 4);
;             asm volatile("" ::: "memory");
; #pragma unroll
;             for (int m = mh; m < mh + 2; ++m) { const int row = row0 + ai * HALF + m * 16; const size_t off = (size_t)row * 1024 + col0; float ss = 0.f;
; #pragma unroll
;                 for (int bj = 0; bj < 2; ++bj) { u32x4e w;
; #pragma unroll
;                     for (int n = 0; n < 2; ++n) { const f32x4 o = pre[m][bj][n] + acc[ai][bj][m][n] * s;
;                         *(f32x4*)(out + off + bj * HALF + n * 4) = o;
;                         if (NORMOUT) { const u32x2 p = pack4(o); w[2 * n] = p.x; w[2 * n + 1] = p.y; ss += (o[0] * o[0] + o[1] * o[1]) + (o[2] * o[2] + o[3] * o[3]); } }
;                     if (NORMOUT) *(u32x4e*)(xn + off + bj * HALF) = w; }
;                 if (NORMOUT) { ss += __shfl_xor(ss, 16); ss += __shfl_xor(ss, 32); if (fq == 0) ssq[(size_t)row * 16 + u.pn * 4 + wc] = ss; } }
	s_cmpk_lt_i32 s83, 0x80
	v_lshl_add_u32 v162, s83, 8, v168
	v_lshl_or_b32 v160, s82, 8, v170
	s_cselect_b32 s20, s37, s39
	s_cselect_b32 s21, s36, s38
	v_mov_b32_e32 v128, s21
	v_mov_b32_e32 v129, s20
	v_ashrrev_i32_e32 v161, 31, v160
	v_ashrrev_i32_e32 v163, 31, v162
	v_lshl_add_u64 v[164:165], v[160:161], 2, v[128:129]
	v_lshlrev_b64 v[128:129], 12, v[162:163]
	v_lshl_add_u64 v[128:129], v[164:165], 0, v[128:129]
	global_load_dwordx4 v[182:185], v[128:129], off
	global_load_dwordx4 v[186:189], v[128:129], off offset:16
	global_load_dwordx4 v[192:195], v[128:129], off offset:512
	global_load_dwordx4 v[196:199], v[128:129], off offset:528
	v_or_b32_e32 v166, 16, v162
	v_ashrrev_i32_e32 v167, 31, v166
	v_lshlrev_b64 v[128:129], 12, v[166:167]
	v_lshl_add_u64 v[132:133], v[164:165], 0, v[128:129]
	global_load_dwordx4 v[136:139], v[132:133], off offset:16
	global_load_dwordx4 v[140:143], v[132:133], off
	global_load_dwordx4 v[128:131], v[132:133], off offset:528
	s_nop 0
	global_load_dwordx4 v[132:135], v[132:133], off offset:512
	v_and_b32_e32 v176, 64, v174
	v_xor_b32_e32 v175, 16, v174
	v_add_u32_e32 v176, 64, v176
	v_lshlrev_b64 v[178:179], 10, v[162:163]
	v_xor_b32_e32 v177, 32, v174
	v_cmp_lt_i32_e32 vcc, v175, v176
	v_lshl_add_u64 v[178:179], v[178:179], 0, v[160:161]
	v_lshl_add_u64 v[200:201], v[178:179], 1, s[64:65]
	v_cndmask_b32_e32 v175, v174, v175, vcc
	v_cmp_lt_i32_e32 vcc, v177, v176
	v_lshl_add_u64 v[178:179], v[178:179], 2, s[56:57]
	v_lshlrev_b32_e32 v176, 2, v175
	v_cndmask_b32_e32 v177, v174, v177, vcc
	v_lshlrev_b32_e32 v175, 2, v177
	s_lshl_b32 s20, s82, 2
	s_ashr_i32 s21, s20, 31
	s_lshl_b64 s[20:21], s[20:21], 2
	s_add_u32 s20, s49, s20
	s_addc_u32 s21, s60, s21
	s_waitcnt vmcnt(0)
	v_pk_fma_f32 v[126:127], v[126:127], 0.5, v[184:185] op_sel_hi:[1,0,1]
	v_pk_fma_f32 v[124:125], v[124:125], 0.5, v[182:183] op_sel_hi:[1,0,1]
	v_pk_fma_f32 v[122:123], v[122:123], 0.5, v[188:189] op_sel_hi:[1,0,1]
	v_pk_fma_f32 v[120:121], v[120:121], 0.5, v[186:187] op_sel_hi:[1,0,1]
	v_pk_fma_f32 v[118:119], v[118:119], 0.5, v[194:195] op_sel_hi:[1,0,1]
	v_pk_fma_f32 v[116:117], v[116:117], 0.5, v[192:193] op_sel_hi:[1,0,1]
	v_pk_fma_f32 v[184:185], v[114:115], 0.5, v[198:199] op_sel_hi:[1,0,1]
	v_pk_fma_f32 v[182:183], v[112:113], 0.5, v[196:197] op_sel_hi:[1,0,1]
	global_store_dwordx4 v[178:179], v[124:127], off
	v_cvt_pk_bf16_f32 v112, v124, v125
	v_cvt_pk_bf16_f32 v113, v126, v127
	v_mul_f32_e32 v125, v125, v125
	v_mul_f32_e32 v127, v127, v127
	global_store_dwordx4 v[178:179], v[120:123], off offset:16
	v_cvt_pk_bf16_f32 v114, v120, v121
	v_cvt_pk_bf16_f32 v115, v122, v123
	v_mul_f32_e32 v121, v121, v121
	v_mul_f32_e32 v123, v123, v123
	v_mul_f32_e32 v177, v117, v117
	v_mul_f32_e32 v181, v119, v119
	v_fmac_f32_e32 v125, v124, v124
	v_fmac_f32_e32 v127, v126, v126
	v_fmac_f32_e32 v121, v120, v120
	v_fmac_f32_e32 v123, v122, v122
	v_mul_f32_e32 v186, v183, v183
	v_mul_f32_e32 v187, v185, v185
	v_fmac_f32_e32 v177, v116, v116
	v_fmac_f32_e32 v181, v118, v118
	v_add_f32_e32 v120, v125, v127
	v_add_f32_e32 v121, v121, v123
	v_fmac_f32_e32 v186, v182, v182
	v_fmac_f32_e32 v187, v184, v184
	v_add_f32_e32 v122, v177, v181
	v_add_f32_e32 v120, v120, v121
	v_add_f32_e32 v120, v122, v120
	v_add_f32_e32 v121, v186, v187
	v_add_f32_e32 v120, v121, v120
	ds_bpermute_b32 v121, v176, v120
	global_store_dwordx4 v[200:201], v[112:115], off
	global_store_dwordx4 v[178:179], v[116:119], off offset:512
	global_store_dwordx4 v[178:179], v[182:185], off offset:528
	v_cvt_pk_bf16_f32 v114, v116, v117
	v_cvt_pk_bf16_f32 v115, v118, v119
	s_waitcnt lgkmcnt(0)
	v_add_f32_e32 v112, v120, v121
	ds_bpermute_b32 v113, v175, v112
	v_cvt_pk_bf16_f32 v116, v182, v183
	v_cvt_pk_bf16_f32 v117, v184, v185
	global_store_dwordx4 v[200:201], v[114:117], off offset:256
	s_and_saveexec_b64 s[22:23], s[2:3]
	s_cbranch_execz .LBB0_269
	v_lshlrev_b64 v[114:115], 6, v[162:163]
	v_lshl_add_u64 v[114:115], s[20:21], 0, v[114:115]
	s_waitcnt lgkmcnt(0)
	v_add_f32_e32 v112, v112, v113
	global_store_dword v[114:115], v112, off

; #define PG8_STAGE(bufoff, gbase, voff) do { _Pragma("unroll") for (int _i = 0; _i < 2; ++_i) \
;         __builtin_amdgcn_global_load_lds((const unsigned*)((const char*)(gbase) + (voff)[_i]), (PG8_LAS unsigned*)(lds + (bufoff) + ldsw + _i * 8192), 16, 0, 0); } while (0)
; #define PG8_LDA(dst, b, h) do { _Pragma("unroll") for (int m = 0; m < 4; ++m) _Pragma("unroll") for (int k = 0; k < 2; ++k) dst[m][k] = *(const PG8_LAS bf16x8*)(lds + PG8_SA(b, h) + aoff + m * 2048 + k * 1024); } while (0)
; #define PG8_LDB(dst, b, h) do { _Pragma("unroll") for (int n = 0; n < 2; ++n) _Pragma("unroll") for (int k = 0; k < 2; ++k) dst[n][k] = *(const PG8_LAS bf16x8*)(lds + PG8_SB(b, h) + boff + n * 2048 + k * 1024); } while (0)
; #define PG8_MMA(ai, bj, At, Bt) do { __builtin_amdgcn_s_setprio(1); _Pragma("unroll") for (int m = 0; m < 4; ++m) _Pragma("unroll") for (int n = 0; n < 2; ++n) _Pragma("unroll") for (int k = 0; k < 2; ++k) \
;         acc[ai][bj][m][n] = __builtin_amdgcn_mfma_f32_16x16x32_bf16(Bt[n][k], At[m][k], acc[ai][bj][m][n], 0, 0, 0); __builtin_amdgcn_s_setprio(0); } while (0)
; #define PG8_WAIT_V(n) asm volatile("s_waitcnt vmcnt(" #n ")" ::: "memory")
; #define PG8_WAIT_L(n) asm volatile("s_waitcnt lgkmcnt(" #n ")" ::: "memory")
; #define PG8_BAR __builtin_amdgcn_s_barrier()
; #define PG8_SCHED __builtin_amdgcn_sched_barrier(0)
; template <class Epi, class Sched, bool ALIGN_EPI = false, bool SP2 = false>
; __device__ __forceinline__ void gemm_phase(PG8_LAS unsigned char* lds, const Gemm g, const Sched& S, const Epi& E) {
;     ...
;             PG8_LDB(B0, 0, 0); PG8_LDB(B1, 0, 1); PG8_SCHED; PG8_LDA(At, 0, 0); PG8_STAGE(PG8_SA(1, 1), a1 + hstep, voffA);
;             PG8_WAIT_V(8); PG8_WAIT_L(0); PG8_BAR; PG8_MMA(0, 0, At, B0); PG8_MMA(0, 1, At, B1); PG8_BAR; PG8_SCHED;
;             PG8_LDA(At, 0, 1); PG8_STAGE(PG8_SB(0, 0), b2, voffB); PG8_STAGE(PG8_SB(0, 1), b2 + hstep, voffB); PG8_STAGE(PG8_SA(0, 0), a2, voffA);
;             PG8_WAIT_V(8); PG8_WAIT_L(0); PG8_BAR; PG8_MMA(1, 0, At, B0); PG8_MMA(1, 1, At, B1); PG8_BAR; PG8_SCHED;
.LBB0_348:
	ds_read_b128 v[128:131], v186
	ds_read_b128 v[132:135], v186 offset:1024
	ds_read_b128 v[136:139], v186 offset:2048
	ds_read_b128 v[164:167], v186 offset:3072
	ds_read_b128 v[168:171], v187
	ds_read_b128 v[172:175], v187 offset:1024
	ds_read_b128 v[176:179], v187 offset:2048
	ds_read_b128 v[196:199], v187 offset:3072
	s_add_u32 s48, s6, 0xfffc0080
	s_addc_u32 s49, s7, -1
	s_cmp_eq_u32 s79, 12
	s_cselect_b32 s75, s1, s49
	s_cselect_b32 s74, s43, s48
	s_cselect_b32 s49, s41, s78
	s_cselect_b32 s48, s76, s77
	v_lshl_add_u64 v[228:229], s[6:7], 0, v[156:157]
	s_add_i32 m0, s83, 0xc000
	ds_read_b128 v[200:203], v188
	ds_read_b128 v[204:207], v188 offset:1024
	ds_read_b128 v[208:211], v188 offset:2048
	ds_read_b128 v[212:215], v188 offset:3072
	ds_read_b128 v[216:219], v188 offset:4096
	ds_read_b128 v[220:223], v188 offset:5120
	ds_read_b128 v[224:227], v188 offset:6144
	ds_read_b128 v[232:235], v188 offset:7168
	global_load_lds_dwordx4 v[228:229], off
	v_lshl_add_u64 v[228:229], s[6:7], 0, v[158:159]
	s_add_i32 m0, s83, 0xe000
	s_nop 0
	global_load_lds_dwordx4 v[228:229], off
	s_waitcnt vmcnt(8)
	s_waitcnt lgkmcnt(0)
	s_barrier
	s_setprio 1
	s_waitcnt lgkmcnt(0)
	v_mfma_f32_16x16x32_bf16 v[124:127], v[128:131], v[200:203], v[124:127]
	v_mfma_f32_16x16x32_bf16 v[120:123], v[136:139], v[200:203], v[120:123]
	v_mfma_f32_16x16x32_bf16 v[108:111], v[128:131], v[208:211], v[108:111]
	v_mfma_f32_16x16x32_bf16 v[104:107], v[136:139], v[208:211], v[104:107]
	v_mfma_f32_16x16x32_bf16 v[92:95], v[128:131], v[216:219], v[92:95]
	v_mfma_f32_16x16x32_bf16 v[88:91], v[136:139], v[216:219], v[88:91]
	v_mfma_f32_16x16x32_bf16 v[76:79], v[128:131], v[224:227], v[76:79]
	v_mfma_f32_16x16x32_bf16 v[72:75], v[136:139], v[224:227], v[72:75]
	v_mfma_f32_16x16x32_bf16 v[124:127], v[132:135], v[204:207], v[124:127]
	v_mfma_f32_16x16x32_bf16 v[120:123], v[164:167], v[204:207], v[120:123]
	v_mfma_f32_16x16x32_bf16 v[108:111], v[132:135], v[212:215], v[108:111]
	v_mfma_f32_16x16x32_bf16 v[104:107], v[164:167], v[212:215], v[104:107]
	v_mfma_f32_16x16x32_bf16 v[92:95], v[132:135], v[220:223], v[92:95]
	v_mfma_f32_16x16x32_bf16 v[88:91], v[164:167], v[220:223], v[88:91]
	v_mfma_f32_16x16x32_bf16 v[76:79], v[132:135], v[232:235], v[76:79]
	v_mfma_f32_16x16x32_bf16 v[72:75], v[164:167], v[232:235], v[72:75]
	s_setprio 0
	s_setprio 1
	v_mfma_f32_16x16x32_bf16 v[116:119], v[168:171], v[200:203], v[116:119]
	v_mfma_f32_16x16x32_bf16 v[112:115], v[176:179], v[200:203], v[112:115]
	v_mfma_f32_16x16x32_bf16 v[100:103], v[168:171], v[208:211], v[100:103]
	v_mfma_f32_16x16x32_bf16 v[96:99], v[176:179], v[208:211], v[96:99]
	v_mfma_f32_16x16x32_bf16 v[84:87], v[168:171], v[216:219], v[84:87]
	v_mfma_f32_16x16x32_bf16 v[80:83], v[176:179], v[216:219], v[80:83]
	v_mfma_f32_16x16x32_bf16 v[68:71], v[168:171], v[224:227], v[68:71]
	v_mfma_f32_16x16x32_bf16 v[64:67], v[176:179], v[224:227], v[64:67]
	v_mfma_f32_16x16x32_bf16 v[116:119], v[172:175], v[204:207], v[116:119]
	v_mfma_f32_16x16x32_bf16 v[112:115], v[196:199], v[204:207], v[112:115]
	v_mfma_f32_16x16x32_bf16 v[100:103], v[172:175], v[212:215], v[100:103]
	v_mfma_f32_16x16x32_bf16 v[96:99], v[196:199], v[212:215], v[96:99]
	v_mfma_f32_16x16x32_bf16 v[84:87], v[172:175], v[220:223], v[84:87]
	v_mfma_f32_16x16x32_bf16 v[80:83], v[196:199], v[220:223], v[80:83]
	v_mfma_f32_16x16x32_bf16 v[68:71], v[172:175], v[232:235], v[68:71]
	v_mfma_f32_16x16x32_bf16 v[64:67], v[196:199], v[232:235], v[64:67]
	s_setprio 0
	s_barrier
	s_add_i32 vcc_lo, s97, s80
	v_lshl_add_u64 v[228:229], s[48:49], 0, v[144:145]
	s_mov_b32 m0, vcc_lo
	ds_read_b128 v[200:203], v188 offset:16384
	ds_read_b128 v[204:207], v188 offset:17408
	ds_read_b128 v[208:211], v188 offset:18432
	ds_read_b128 v[212:215], v188 offset:19456
	ds_read_b128 v[216:219], v188 offset:20480
	ds_read_b128 v[220:223], v188 offset:21504
	ds_read_b128 v[224:227], v188 offset:22528
	ds_read_b128 v[232:235], v188 offset:23552
	global_load_lds_dwordx4 v[228:229], off
	s_add_i32 m0, vcc_lo, 0x2000
	s_add_u32 vcc_lo, s48, 0x40000
	v_lshl_add_u64 v[236:237], s[48:49], 0, v[140:141]
	s_addc_u32 vcc_hi, s49, 0
	s_add_i32 s94, s60, s80
	global_load_lds_dwordx4 v[236:237], off
	v_lshl_add_u64 v[238:239], vcc, 0, v[144:145]
	s_mov_b32 m0, s94
	v_lshl_add_u64 v[240:241], s[74:75], 0, v[142:143]
	global_load_lds_dwordx4 v[238:239], off
	v_lshl_add_u64 v[238:239], vcc, 0, v[140:141]
	s_add_i32 m0, s94, 0x2000
	s_nop 0
	global_load_lds_dwordx4 v[238:239], off
	s_waitcnt vmcnt(6)
	s_waitcnt lgkmcnt(0)
	s_barrier
; #define PG8_STAGE(bufoff, gbase, voff) do { _Pragma("unroll") for (int _i = 0; _i < 2; ++_i) \
;         __builtin_amdgcn_global_load_lds((const unsigned*)((const char*)(gbase) + (voff)[_i]), (PG8_LAS unsigned*)(lds + (bufoff) + ldsw + _i * 8192), 16, 0, 0); } while (0)
; #define PG8_LDA(dst, b, h) do { _Pragma("unroll") for (int m = 0; m < 4; ++m) _Pragma("unroll") for (int k = 0; k < 2; ++k) dst[m][k] = *(const PG8_LAS bf16x8*)(lds + PG8_SA(b, h) + aoff + m * 2048 + k * 1024); } while (0)
; #define PG8_LDB(dst, b, h) do { _Pragma("unroll") for (int n = 0; n < 2; ++n) _Pragma("unroll") for (int k = 0; k < 2; ++k) dst[n][k] = *(const PG8_LAS bf16x8*)(lds + PG8_SB(b, h) + boff + n * 2048 + k * 1024); } while (0)
; #define PG8_MMA(ai, bj, At, Bt) do { __builtin_amdgcn_s_setprio(1); _Pragma("unroll") for (int m = 0; m < 4; ++m) _Pragma("unroll") for (int n = 0; n < 2; ++n) _Pragma("unroll") for (int k = 0; k < 2; ++k) \
;         acc[ai][bj][m][n] = __builtin_amdgcn_mfma_f32_16x16x32_bf16(Bt[n][k], At[m][k], acc[ai][bj][m][n], 0, 0, 0); __builtin_amdgcn_s_setprio(0); } while (0)
; #define PG8_WAIT_V(n) asm volatile("s_waitcnt vmcnt(" #n ")" ::: "memory")
; #define PG8_WAIT_L(n) asm volatile("s_waitcnt lgkmcnt(" #n ")" ::: "memory")
; #define PG8_BAR __builtin_amdgcn_s_barrier()
; #define PG8_SCHED __builtin_amdgcn_sched_barrier(0)
; template <class Epi, class Sched, bool ALIGN_EPI = false, bool SP2 = false>
; __device__ __forceinline__ void gemm_phase(PG8_LAS unsigned char* lds, const Gemm g, const Sched& S, const Epi& E) {
;     ...
;             PG8_WAIT_V(8); PG8_WAIT_L(0); PG8_BAR; PG8_MMA(1, 0, At, B0); PG8_MMA(1, 1, At, B1); PG8_BAR; PG8_SCHED;
;             PG8_LDB(B0, 1, 0); PG8_LDB(B1, 1, 1); PG8_SCHED; PG8_LDA(At, 1, 0); PG8_STAGE(PG8_SA(0, 1), a2 + hstep, voffA);
;             PG8_WAIT_V(8); PG8_WAIT_L(0); PG8_BAR; PG8_MMA(0, 0, At, B0); PG8_MMA(0, 1, At, B1); PG8_BAR; PG8_SCHED;
	s_setprio 1
	s_waitcnt lgkmcnt(0)
	v_mfma_f32_16x16x32_bf16 v[60:63], v[128:131], v[200:203], v[60:63]
	v_mfma_f32_16x16x32_bf16 v[56:59], v[136:139], v[200:203], v[56:59]
	v_mfma_f32_16x16x32_bf16 v[44:47], v[128:131], v[208:211], v[44:47]
	v_mfma_f32_16x16x32_bf16 v[40:43], v[136:139], v[208:211], v[40:43]
	v_mfma_f32_16x16x32_bf16 v[28:31], v[128:131], v[216:219], v[28:31]
	v_mfma_f32_16x16x32_bf16 v[24:27], v[136:139], v[216:219], v[24:27]
	v_lshl_add_u64 v[238:239], s[74:75], 0, v[146:147]
	s_mov_b32 m0, s83
	s_nop 0
	global_load_lds_dwordx4 v[238:239], off
	v_mfma_f32_16x16x32_bf16 v[12:15], v[128:131], v[224:227], v[12:15]
	v_mfma_f32_16x16x32_bf16 v[8:11], v[136:139], v[224:227], v[8:11]
	v_mfma_f32_16x16x32_bf16 v[60:63], v[132:135], v[204:207], v[60:63]
	v_mfma_f32_16x16x32_bf16 v[56:59], v[164:167], v[204:207], v[56:59]
	v_mfma_f32_16x16x32_bf16 v[44:47], v[132:135], v[212:215], v[44:47]
	v_mfma_f32_16x16x32_bf16 v[40:43], v[164:167], v[212:215], v[40:43]
	v_mfma_f32_16x16x32_bf16 v[28:31], v[132:135], v[220:223], v[28:31]
	v_mfma_f32_16x16x32_bf16 v[24:27], v[164:167], v[220:223], v[24:27]
	v_mfma_f32_16x16x32_bf16 v[12:15], v[132:135], v[232:235], v[12:15]
	v_mfma_f32_16x16x32_bf16 v[8:11], v[164:167], v[232:235], v[8:11]
	s_setprio 0
	s_setprio 1
	v_mfma_f32_16x16x32_bf16 v[52:55], v[168:171], v[200:203], v[52:55]
	v_mfma_f32_16x16x32_bf16 v[48:51], v[176:179], v[200:203], v[48:51]
	v_mfma_f32_16x16x32_bf16 v[36:39], v[168:171], v[208:211], v[36:39]
	v_mfma_f32_16x16x32_bf16 v[32:35], v[176:179], v[208:211], v[32:35]
	v_mfma_f32_16x16x32_bf16 v[20:23], v[168:171], v[216:219], v[20:23]
	v_mfma_f32_16x16x32_bf16 v[16:19], v[176:179], v[216:219], v[16:19]
	s_mov_b32 m0, s84
	s_nop 0
	global_load_lds_dwordx4 v[240:241], off
	v_mfma_f32_16x16x32_bf16 v[4:7], v[168:171], v[224:227], v[4:7]
	v_mfma_f32_16x16x32_bf16 v[0:3], v[176:179], v[224:227], v[0:3]
	v_mfma_f32_16x16x32_bf16 v[52:55], v[172:175], v[204:207], v[52:55]
	v_mfma_f32_16x16x32_bf16 v[48:51], v[196:199], v[204:207], v[48:51]
	v_mfma_f32_16x16x32_bf16 v[36:39], v[172:175], v[212:215], v[36:39]
	v_mfma_f32_16x16x32_bf16 v[32:35], v[196:199], v[212:215], v[32:35]
	v_mfma_f32_16x16x32_bf16 v[20:23], v[172:175], v[220:223], v[20:23]
	v_mfma_f32_16x16x32_bf16 v[16:19], v[196:199], v[220:223], v[16:19]
	v_mfma_f32_16x16x32_bf16 v[4:7], v[172:175], v[232:235], v[4:7]
	v_mfma_f32_16x16x32_bf16 v[0:3], v[196:199], v[232:235], v[0:3]
	s_setprio 0
	s_barrier
	s_add_i32 s94, 0, 0x18000
	v_add_u32_e32 v148, s94, v181
	s_add_i32 vcc_lo, 0, 0x1c000
	ds_read_b128 v[128:131], v148
	ds_read_b128 v[132:135], v148 offset:1024
	ds_read_b128 v[136:139], v148 offset:2048
	ds_read_b128 v[164:167], v148 offset:3072
	v_add_u32_e32 v148, vcc_lo, v181
	ds_read_b128 v[168:171], v148
	ds_read_b128 v[172:175], v148 offset:1024
	ds_read_b128 v[176:179], v148 offset:2048
	ds_read_b128 v[196:199], v148 offset:3072
	s_add_u32 s74, s74, 0x40000
	s_addc_u32 s75, s75, 0
	s_mov_b32 m0, s85
	v_lshl_add_u64 v[242:243], s[74:75], 0, v[146:147]
	ds_read_b128 v[200:203], v188 offset:32768
	ds_read_b128 v[204:207], v188 offset:33792
	ds_read_b128 v[208:211], v188 offset:34816
	ds_read_b128 v[212:215], v188 offset:35840
	ds_read_b128 v[216:219], v188 offset:36864
	ds_read_b128 v[220:223], v188 offset:37888
	ds_read_b128 v[224:227], v188 offset:38912
	ds_read_b128 v[232:235], v188 offset:39936
	global_load_lds_dwordx4 v[242:243], off
	v_lshl_add_u64 v[242:243], s[74:75], 0, v[142:143]
	s_mov_b32 m0, s86
	s_nop 0
	global_load_lds_dwordx4 v[242:243], off
	s_waitcnt vmcnt(8)
	s_waitcnt lgkmcnt(0)
	s_barrier
	s_setprio 1
	s_waitcnt lgkmcnt(0)
	v_mfma_f32_16x16x32_bf16 v[124:127], v[128:131], v[200:203], v[124:127]
	v_mfma_f32_16x16x32_bf16 v[120:123], v[136:139], v[200:203], v[120:123]
	v_mfma_f32_16x16x32_bf16 v[108:111], v[128:131], v[208:211], v[108:111]
	v_mfma_f32_16x16x32_bf16 v[104:107], v[136:139], v[208:211], v[104:107]
	v_mfma_f32_16x16x32_bf16 v[92:95], v[128:131], v[216:219], v[92:95]
	v_mfma_f32_16x16x32_bf16 v[88:91], v[136:139], v[216:219], v[88:91]
	v_mfma_f32_16x16x32_bf16 v[76:79], v[128:131], v[224:227], v[76:79]
	v_mfma_f32_16x16x32_bf16 v[72:75], v[136:139], v[224:227], v[72:75]
	v_mfma_f32_16x16x32_bf16 v[124:127], v[132:135], v[204:207], v[124:127]
	v_mfma_f32_16x16x32_bf16 v[120:123], v[164:167], v[204:207], v[120:123]
	v_mfma_f32_16x16x32_bf16 v[108:111], v[132:135], v[212:215], v[108:111]
	v_mfma_f32_16x16x32_bf16 v[104:107], v[164:167], v[212:215], v[104:107]
	v_mfma_f32_16x16x32_bf16 v[92:95], v[132:135], v[220:223], v[92:95]
	v_mfma_f32_16x16x32_bf16 v[88:91], v[164:167], v[220:223], v[88:91]
	v_mfma_f32_16x16x32_bf16 v[76:79], v[132:135], v[232:235], v[76:79]
	v_mfma_f32_16x16x32_bf16 v[72:75], v[164:167], v[232:235], v[72:75]
	s_setprio 0
	s_setprio 1
	v_mfma_f32_16x16x32_bf16 v[116:119], v[168:171], v[200:203], v[116:119]
	v_mfma_f32_16x16x32_bf16 v[112:115], v[176:179], v[200:203], v[112:115]
	v_mfma_f32_16x16x32_bf16 v[100:103], v[168:171], v[208:211], v[100:103]
	v_mfma_f32_16x16x32_bf16 v[96:99], v[176:179], v[208:211], v[96:99]
	v_mfma_f32_16x16x32_bf16 v[84:87], v[168:171], v[216:219], v[84:87]
	v_mfma_f32_16x16x32_bf16 v[80:83], v[176:179], v[216:219], v[80:83]
	v_mfma_f32_16x16x32_bf16 v[68:71], v[168:171], v[224:227], v[68:71]
	v_mfma_f32_16x16x32_bf16 v[64:67], v[176:179], v[224:227], v[64:67]
	v_mfma_f32_16x16x32_bf16 v[116:119], v[172:175], v[204:207], v[116:119]
	v_mfma_f32_16x16x32_bf16 v[112:115], v[196:199], v[204:207], v[112:115]
	v_mfma_f32_16x16x32_bf16 v[100:103], v[172:175], v[212:215], v[100:103]
	v_mfma_f32_16x16x32_bf16 v[96:99], v[196:199], v[212:215], v[96:99]
	v_mfma_f32_16x16x32_bf16 v[84:87], v[172:175], v[220:223], v[84:87]
	v_mfma_f32_16x16x32_bf16 v[80:83], v[196:199], v[220:223], v[80:83]
	v_mfma_f32_16x16x32_bf16 v[68:71], v[172:175], v[232:235], v[68:71]
	v_mfma_f32_16x16x32_bf16 v[64:67], v[196:199], v[232:235], v[64:67]
	s_setprio 0
	s_barrier
; #define PG8_STAGE(bufoff, gbase, voff) do { _Pragma("unroll") for (int _i = 0; _i < 2; ++_i) \
;         __builtin_amdgcn_global_load_lds((const unsigned*)((const char*)(gbase) + (voff)[_i]), (PG8_LAS unsigned*)(lds + (bufoff) + ldsw + _i * 8192), 16, 0, 0); } while (0)
; #define PG8_LDA(dst, b, h) do { _Pragma("unroll") for (int m = 0; m < 4; ++m) _Pragma("unroll") for (int k = 0; k < 2; ++k) dst[m][k] = *(const PG8_LAS bf16x8*)(lds + PG8_SA(b, h) + aoff + m * 2048 + k * 1024); } while (0)
; #define PG8_MMA(ai, bj, At, Bt) do { __builtin_amdgcn_s_setprio(1); _Pragma("unroll") for (int m = 0; m < 4; ++m) _Pragma("unroll") for (int n = 0; n < 2; ++n) _Pragma("unroll") for (int k = 0; k < 2; ++k) \
;         acc[ai][bj][m][n] = __builtin_amdgcn_mfma_f32_16x16x32_bf16(Bt[n][k], At[m][k], acc[ai][bj][m][n], 0, 0, 0); __builtin_amdgcn_s_setprio(0); } while (0)
; #define PG8_WAIT_V(n) asm volatile("s_waitcnt vmcnt(" #n ")" ::: "memory")
; #define PG8_WAIT_L(n) asm volatile("s_waitcnt lgkmcnt(" #n ")" ::: "memory")
; #define PG8_BAR __builtin_amdgcn_s_barrier()
; #define PG8_SCHED __builtin_amdgcn_sched_barrier(0)
; template <class Epi, class Sched, bool ALIGN_EPI = false, bool SP2 = false>
; __device__ __forceinline__ void gemm_phase(PG8_LAS unsigned char* lds, const Gemm g, const Sched& S, const Epi& E) {
;     ...
;             PG8_LDA(At, 1, 1); PG8_STAGE(PG8_SB(1, 0), b3, voffB); PG8_STAGE(PG8_SB(1, 1), b3 + hstep, voffB); PG8_STAGE(PG8_SA(1, 0), a3, voffA);
;             PG8_WAIT_V(8); PG8_WAIT_L(0); PG8_BAR; PG8_MMA(1, 0, At, B0); PG8_MMA(1, 1, At, B1); PG8_BAR; PG8_SCHED;
;     ...
;         if constexpr (ALIGN_EPI) { if (wr == 0) PG8_BAR; }
	s_add_i32 s74, s94, s80
	v_lshl_add_u64 v[228:229], v[228:229], 0, s[22:23]
	s_mov_b32 m0, s74
	ds_read_b128 v[200:203], v188 offset:49152
	ds_read_b128 v[204:207], v188 offset:50176
	ds_read_b128 v[208:211], v188 offset:51200
	ds_read_b128 v[212:215], v188 offset:52224
	ds_read_b128 v[216:219], v188 offset:53248
	ds_read_b128 v[220:223], v188 offset:54272
	ds_read_b128 v[224:227], v188 offset:55296
	ds_read_b128 v[232:235], v188 offset:56320
	global_load_lds_dwordx4 v[228:229], off
	s_add_i32 m0, s74, 0x2000
	s_add_u32 s48, s48, 0x40080
	v_lshl_add_u64 v[228:229], v[236:237], 0, s[22:23]
	s_addc_u32 s49, s49, 0
	s_add_i32 s74, vcc_lo, s80
	global_load_lds_dwordx4 v[228:229], off
	v_lshl_add_u64 v[228:229], s[48:49], 0, v[144:145]
	s_mov_b32 m0, s74
	s_nop 0
	global_load_lds_dwordx4 v[228:229], off
	v_lshl_add_u64 v[228:229], s[48:49], 0, v[140:141]
	s_add_i32 m0, s74, 0x2000
	s_nop 0
	global_load_lds_dwordx4 v[228:229], off
	s_waitcnt vmcnt(6)
	s_waitcnt lgkmcnt(0)
	s_barrier
	s_setprio 1
	s_waitcnt lgkmcnt(0)
	v_mfma_f32_16x16x32_bf16 v[60:63], v[128:131], v[200:203], v[60:63]
	v_mfma_f32_16x16x32_bf16 v[56:59], v[136:139], v[200:203], v[56:59]
	v_mfma_f32_16x16x32_bf16 v[44:47], v[128:131], v[208:211], v[44:47]
	v_mfma_f32_16x16x32_bf16 v[40:43], v[136:139], v[208:211], v[40:43]
	v_mfma_f32_16x16x32_bf16 v[28:31], v[128:131], v[216:219], v[28:31]
	v_mfma_f32_16x16x32_bf16 v[24:27], v[136:139], v[216:219], v[24:27]
	v_lshl_add_u64 v[228:229], v[238:239], 0, s[22:23]
	s_mov_b32 m0, s89
	s_nop 0
	global_load_lds_dwordx4 v[228:229], off
	v_mfma_f32_16x16x32_bf16 v[12:15], v[128:131], v[224:227], v[12:15]
	v_mfma_f32_16x16x32_bf16 v[8:11], v[136:139], v[224:227], v[8:11]
	v_mfma_f32_16x16x32_bf16 v[60:63], v[132:135], v[204:207], v[60:63]
	v_mfma_f32_16x16x32_bf16 v[56:59], v[164:167], v[204:207], v[56:59]
	v_mfma_f32_16x16x32_bf16 v[44:47], v[132:135], v[212:215], v[44:47]
	v_mfma_f32_16x16x32_bf16 v[40:43], v[164:167], v[212:215], v[40:43]
	v_mfma_f32_16x16x32_bf16 v[28:31], v[132:135], v[220:223], v[28:31]
	v_mfma_f32_16x16x32_bf16 v[24:27], v[164:167], v[220:223], v[24:27]
	v_mfma_f32_16x16x32_bf16 v[12:15], v[132:135], v[232:235], v[12:15]
	v_mfma_f32_16x16x32_bf16 v[8:11], v[164:167], v[232:235], v[8:11]
	s_setprio 0
	s_setprio 1
	v_mfma_f32_16x16x32_bf16 v[52:55], v[168:171], v[200:203], v[52:55]
	v_mfma_f32_16x16x32_bf16 v[48:51], v[176:179], v[200:203], v[48:51]
	v_mfma_f32_16x16x32_bf16 v[36:39], v[168:171], v[208:211], v[36:39]
	v_mfma_f32_16x16x32_bf16 v[32:35], v[176:179], v[208:211], v[32:35]
	v_mfma_f32_16x16x32_bf16 v[20:23], v[168:171], v[216:219], v[20:23]
	v_mfma_f32_16x16x32_bf16 v[16:19], v[176:179], v[216:219], v[16:19]
	v_lshl_add_u64 v[228:229], v[240:241], 0, s[22:23]
	s_mov_b32 m0, s90
	s_nop 0
	global_load_lds_dwordx4 v[228:229], off
	v_mfma_f32_16x16x32_bf16 v[4:7], v[168:171], v[224:227], v[4:7]
	v_mfma_f32_16x16x32_bf16 v[0:3], v[176:179], v[224:227], v[0:3]
	v_mfma_f32_16x16x32_bf16 v[52:55], v[172:175], v[204:207], v[52:55]
	v_mfma_f32_16x16x32_bf16 v[48:51], v[196:199], v[204:207], v[48:51]
	v_mfma_f32_16x16x32_bf16 v[36:39], v[172:175], v[212:215], v[36:39]
	v_mfma_f32_16x16x32_bf16 v[32:35], v[196:199], v[212:215], v[32:35]
	v_mfma_f32_16x16x32_bf16 v[20:23], v[172:175], v[220:223], v[20:23]
	v_mfma_f32_16x16x32_bf16 v[16:19], v[196:199], v[220:223], v[16:19]
	v_mfma_f32_16x16x32_bf16 v[4:7], v[172:175], v[232:235], v[4:7]
	v_mfma_f32_16x16x32_bf16 v[0:3], v[196:199], v[232:235], v[0:3]
	s_setprio 0
	s_barrier
	s_add_i32 s79, s79, 2
	s_add_u32 s6, s6, 0x100
	s_addc_u32 s7, s7, 0
	s_add_u32 s77, s77, 0x100
	s_addc_u32 s78, s78, 0
	s_cmp_gt_u32 s79, 13
	s_cbranch_scc0 .LBB0_348
	s_and_b64 vcc, exec, s[24:25]
	s_cbranch_vccz .LBB0_351
	s_barrier

; #define PG8_STAGE(bufoff, gbase, voff) do { _Pragma("unroll") for (int _i = 0; _i < 2; ++_i) \
;         __builtin_amdgcn_global_load_lds((const unsigned*)((const char*)(gbase) + (voff)[_i]), (PG8_LAS unsigned*)(lds + (bufoff) + ldsw + _i * 8192), 16, 0, 0); } while (0)
; #define PG8_LDA(dst, b, h) do { _Pragma("unroll") for (int m = 0; m < 4; ++m) _Pragma("unroll") for (int k = 0; k < 2; ++k) dst[m][k] = *(const PG8_LAS bf16x8*)(lds + PG8_SA(b, h) + aoff + m * 2048 + k * 1024); } while (0)
; #define PG8_LDB(dst, b, h) do { _Pragma("unroll") for (int n = 0; n < 2; ++n) _Pragma("unroll") for (int k = 0; k < 2; ++k) dst[n][k] = *(const PG8_LAS bf16x8*)(lds + PG8_SB(b, h) + boff + n * 2048 + k * 1024); } while (0)
; #define PG8_MMA(ai, bj, At, Bt) do { __builtin_amdgcn_s_setprio(1); _Pragma("unroll") for (int m = 0; m < 4; ++m) _Pragma("unroll") for (int n = 0; n < 2; ++n) _Pragma("unroll") for (int k = 0; k < 2; ++k) \
;         acc[ai][bj][m][n] = __builtin_amdgcn_mfma_f32_16x16x32_bf16(Bt[n][k], At[m][k], acc[ai][bj][m][n], 0, 0, 0); __builtin_amdgcn_s_setprio(0); } while (0)
; #define PG8_WAIT_V(n) asm volatile("s_waitcnt vmcnt(" #n ")" ::: "memory")
; #define PG8_WAIT_L(n) asm volatile("s_waitcnt lgkmcnt(" #n ")" ::: "memory")
; #define PG8_BAR __builtin_amdgcn_s_barrier()
; #define PG8_SCHED __builtin_amdgcn_sched_barrier(0)
; template <class Epi, class Sched, bool ALIGN_EPI = false, bool SP2 = false>
; __device__ __forceinline__ void gemm_phase(PG8_LAS unsigned char* lds, const Gemm g, const Sched& S, const Epi& E) {
;     ...
;             PG8_LDB(B0, 0, 0); PG8_LDB(B1, 0, 1); PG8_SCHED; PG8_LDA(At, 0, 0); PG8_STAGE(PG8_SA(1, 1), a1 + hstep, voffA);
;             PG8_WAIT_V(8); PG8_WAIT_L(0); PG8_BAR; PG8_MMA(0, 0, At, B0); PG8_MMA(0, 1, At, B1); PG8_BAR; PG8_SCHED;
;             PG8_LDA(At, 0, 1); PG8_STAGE(PG8_SB(0, 0), b2, voffB); PG8_STAGE(PG8_SB(0, 1), b2 + hstep, voffB); PG8_STAGE(PG8_SA(0, 0), a2, voffA);
;             PG8_WAIT_V(8); PG8_WAIT_L(0); PG8_BAR; PG8_MMA(1, 0, At, B0); PG8_MMA(1, 1, At, B1); PG8_BAR; PG8_SCHED;
.LBB0_735:
	ds_read_b128 v[144:147], v159
	ds_read_b128 v[162:165], v159 offset:1024
	ds_read_b128 v[166:169], v159 offset:2048
	ds_read_b128 v[170:173], v159 offset:3072
	ds_read_b128 v[174:177], v160
	ds_read_b128 v[178:181], v160 offset:1024
	ds_read_b128 v[182:185], v160 offset:2048
	ds_read_b128 v[186:189], v160 offset:3072
	s_add_u32 s44, s42, 0xfffe0080
	s_addc_u32 s45, s43, -1
	s_cmp_eq_u32 s86, 4
	s_cselect_b32 s47, s27, s45
	s_cselect_b32 s46, s82, s44
	s_cselect_b32 s45, s25, s85
	s_cselect_b32 s44, s83, s84
	v_lshl_add_u64 v[222:223], s[42:43], 0, v[136:137]
	s_add_i32 m0, s41, 0xc000
	ds_read_b128 v[190:193], v161
	ds_read_b128 v[194:197], v161 offset:1024
	ds_read_b128 v[198:201], v161 offset:2048
	ds_read_b128 v[202:205], v161 offset:3072
	ds_read_b128 v[206:209], v161 offset:4096
	ds_read_b128 v[210:213], v161 offset:5120
	ds_read_b128 v[214:217], v161 offset:6144
	ds_read_b128 v[218:221], v161 offset:7168
	global_load_lds_dwordx4 v[222:223], off
	v_lshl_add_u64 v[222:223], s[42:43], 0, v[138:139]
	s_add_i32 m0, s41, 0xe000
	s_nop 0
	global_load_lds_dwordx4 v[222:223], off
	s_waitcnt vmcnt(8)
	s_waitcnt lgkmcnt(0)
	s_barrier
	s_setprio 1
	s_waitcnt lgkmcnt(0)
	v_mfma_f32_16x16x32_bf16 v[124:127], v[144:147], v[190:193], v[124:127]
	v_mfma_f32_16x16x32_bf16 v[120:123], v[166:169], v[190:193], v[120:123]
	v_mfma_f32_16x16x32_bf16 v[112:115], v[144:147], v[198:201], v[112:115]
	v_mfma_f32_16x16x32_bf16 v[104:107], v[166:169], v[198:201], v[104:107]
	v_mfma_f32_16x16x32_bf16 v[92:95], v[144:147], v[206:209], v[92:95]
	v_mfma_f32_16x16x32_bf16 v[88:91], v[166:169], v[206:209], v[88:91]
	v_mfma_f32_16x16x32_bf16 v[84:87], v[144:147], v[214:217], v[84:87]
	v_mfma_f32_16x16x32_bf16 v[80:83], v[166:169], v[214:217], v[80:83]
	v_mfma_f32_16x16x32_bf16 v[124:127], v[162:165], v[194:197], v[124:127]
	v_mfma_f32_16x16x32_bf16 v[120:123], v[170:173], v[194:197], v[120:123]
	v_mfma_f32_16x16x32_bf16 v[112:115], v[162:165], v[202:205], v[112:115]
	v_mfma_f32_16x16x32_bf16 v[104:107], v[170:173], v[202:205], v[104:107]
	v_mfma_f32_16x16x32_bf16 v[92:95], v[162:165], v[210:213], v[92:95]
	v_mfma_f32_16x16x32_bf16 v[88:91], v[170:173], v[210:213], v[88:91]
	v_mfma_f32_16x16x32_bf16 v[84:87], v[162:165], v[218:221], v[84:87]
	v_mfma_f32_16x16x32_bf16 v[80:83], v[170:173], v[218:221], v[80:83]
	s_setprio 0
	s_setprio 1
	v_mfma_f32_16x16x32_bf16 v[116:119], v[174:177], v[190:193], v[116:119]
	v_mfma_f32_16x16x32_bf16 v[108:111], v[182:185], v[190:193], v[108:111]
	v_mfma_f32_16x16x32_bf16 v[100:103], v[174:177], v[198:201], v[100:103]
	v_mfma_f32_16x16x32_bf16 v[96:99], v[182:185], v[198:201], v[96:99]
	v_mfma_f32_16x16x32_bf16 v[76:79], v[174:177], v[206:209], v[76:79]
	v_mfma_f32_16x16x32_bf16 v[72:75], v[182:185], v[206:209], v[72:75]
	v_mfma_f32_16x16x32_bf16 v[68:71], v[174:177], v[214:217], v[68:71]
	v_mfma_f32_16x16x32_bf16 v[64:67], v[182:185], v[214:217], v[64:67]
	v_mfma_f32_16x16x32_bf16 v[116:119], v[178:181], v[194:197], v[116:119]
	v_mfma_f32_16x16x32_bf16 v[108:111], v[186:189], v[194:197], v[108:111]
	v_mfma_f32_16x16x32_bf16 v[100:103], v[178:181], v[202:205], v[100:103]
	v_mfma_f32_16x16x32_bf16 v[96:99], v[186:189], v[202:205], v[96:99]
	v_mfma_f32_16x16x32_bf16 v[76:79], v[178:181], v[210:213], v[76:79]
	v_mfma_f32_16x16x32_bf16 v[72:75], v[186:189], v[210:213], v[72:75]
	v_mfma_f32_16x16x32_bf16 v[68:71], v[178:181], v[218:221], v[68:71]
	v_mfma_f32_16x16x32_bf16 v[64:67], v[186:189], v[218:221], v[64:67]
	s_setprio 0
	s_barrier
	s_add_i32 s87, s75, s49
	v_lshl_add_u64 v[222:223], s[44:45], 0, v[130:131]
	s_mov_b32 m0, s87
	ds_read_b128 v[190:193], v161 offset:16384
	ds_read_b128 v[194:197], v161 offset:17408
	ds_read_b128 v[198:201], v161 offset:18432
	ds_read_b128 v[202:205], v161 offset:19456
	ds_read_b128 v[206:209], v161 offset:20480
	ds_read_b128 v[210:213], v161 offset:21504
	ds_read_b128 v[214:217], v161 offset:22528
	ds_read_b128 v[218:221], v161 offset:23552
	global_load_lds_dwordx4 v[222:223], off
	s_add_i32 m0, s87, 0x2000
	s_add_u32 s88, s44, 0x20000
	v_lshl_add_u64 v[224:225], s[44:45], 0, v[134:135]
	s_addc_u32 s89, s45, 0
	s_add_i32 s87, s76, s49
	global_load_lds_dwordx4 v[224:225], off
	v_lshl_add_u64 v[226:227], s[88:89], 0, v[130:131]
	s_mov_b32 m0, s87
	v_lshl_add_u64 v[228:229], s[46:47], 0, v[132:133]
	global_load_lds_dwordx4 v[226:227], off
	v_lshl_add_u64 v[226:227], s[88:89], 0, v[134:135]
	s_add_i32 m0, s87, 0x2000
	s_nop 0
	global_load_lds_dwordx4 v[226:227], off
	s_waitcnt vmcnt(6)
	s_waitcnt lgkmcnt(0)
	s_barrier
; #define PG8_STAGE(bufoff, gbase, voff) do { _Pragma("unroll") for (int _i = 0; _i < 2; ++_i) \
;         __builtin_amdgcn_global_load_lds((const unsigned*)((const char*)(gbase) + (voff)[_i]), (PG8_LAS unsigned*)(lds + (bufoff) + ldsw + _i * 8192), 16, 0, 0); } while (0)
; #define PG8_LDA(dst, b, h) do { _Pragma("unroll") for (int m = 0; m < 4; ++m) _Pragma("unroll") for (int k = 0; k < 2; ++k) dst[m][k] = *(const PG8_LAS bf16x8*)(lds + PG8_SA(b, h) + aoff + m * 2048 + k * 1024); } while (0)
; #define PG8_LDB(dst, b, h) do { _Pragma("unroll") for (int n = 0; n < 2; ++n) _Pragma("unroll") for (int k = 0; k < 2; ++k) dst[n][k] = *(const PG8_LAS bf16x8*)(lds + PG8_SB(b, h) + boff + n * 2048 + k * 1024); } while (0)
; #define PG8_MMA(ai, bj, At, Bt) do { __builtin_amdgcn_s_setprio(1); _Pragma("unroll") for (int m = 0; m < 4; ++m) _Pragma("unroll") for (int n = 0; n < 2; ++n) _Pragma("unroll") for (int k = 0; k < 2; ++k) \
;         acc[ai][bj][m][n] = __builtin_amdgcn_mfma_f32_16x16x32_bf16(Bt[n][k], At[m][k], acc[ai][bj][m][n], 0, 0, 0); __builtin_amdgcn_s_setprio(0); } while (0)
; #define PG8_WAIT_V(n) asm volatile("s_waitcnt vmcnt(" #n ")" ::: "memory")
; #define PG8_WAIT_L(n) asm volatile("s_waitcnt lgkmcnt(" #n ")" ::: "memory")
; #define PG8_BAR __builtin_amdgcn_s_barrier()
; #define PG8_SCHED __builtin_amdgcn_sched_barrier(0)
; template <class Epi, class Sched, bool ALIGN_EPI = false, bool SP2 = false>
; __device__ __forceinline__ void gemm_phase(PG8_LAS unsigned char* lds, const Gemm g, const Sched& S, const Epi& E) {
;     ...
;             PG8_WAIT_V(8); PG8_WAIT_L(0); PG8_BAR; PG8_MMA(1, 0, At, B0); PG8_MMA(1, 1, At, B1); PG8_BAR; PG8_SCHED;
;             PG8_LDB(B0, 1, 0); PG8_LDB(B1, 1, 1); PG8_SCHED; PG8_LDA(At, 1, 0); PG8_STAGE(PG8_SA(0, 1), a2 + hstep, voffA);
;             PG8_WAIT_V(8); PG8_WAIT_L(0); PG8_BAR; PG8_MMA(0, 0, At, B0); PG8_MMA(0, 1, At, B1); PG8_BAR; PG8_SCHED;
	s_setprio 1
	s_waitcnt lgkmcnt(0)
	v_mfma_f32_16x16x32_bf16 v[60:63], v[144:147], v[190:193], v[60:63]
	v_mfma_f32_16x16x32_bf16 v[56:59], v[166:169], v[190:193], v[56:59]
	v_mfma_f32_16x16x32_bf16 v[52:55], v[144:147], v[198:201], v[52:55]
	v_mfma_f32_16x16x32_bf16 v[48:51], v[166:169], v[198:201], v[48:51]
	v_mfma_f32_16x16x32_bf16 v[28:31], v[144:147], v[206:209], v[28:31]
	v_mfma_f32_16x16x32_bf16 v[24:27], v[166:169], v[206:209], v[24:27]
	v_lshl_add_u64 v[226:227], s[46:47], 0, v[128:129]
	s_mov_b32 m0, s41
	s_nop 0
	global_load_lds_dwordx4 v[226:227], off
	v_mfma_f32_16x16x32_bf16 v[20:23], v[144:147], v[214:217], v[20:23]
	v_mfma_f32_16x16x32_bf16 v[16:19], v[166:169], v[214:217], v[16:19]
	v_mfma_f32_16x16x32_bf16 v[60:63], v[162:165], v[194:197], v[60:63]
	v_mfma_f32_16x16x32_bf16 v[56:59], v[170:173], v[194:197], v[56:59]
	v_mfma_f32_16x16x32_bf16 v[52:55], v[162:165], v[202:205], v[52:55]
	v_mfma_f32_16x16x32_bf16 v[48:51], v[170:173], v[202:205], v[48:51]
	v_mfma_f32_16x16x32_bf16 v[28:31], v[162:165], v[210:213], v[28:31]
	v_mfma_f32_16x16x32_bf16 v[24:27], v[170:173], v[210:213], v[24:27]
	v_mfma_f32_16x16x32_bf16 v[20:23], v[162:165], v[218:221], v[20:23]
	v_mfma_f32_16x16x32_bf16 v[16:19], v[170:173], v[218:221], v[16:19]
	s_setprio 0
	s_setprio 1
	v_mfma_f32_16x16x32_bf16 v[44:47], v[174:177], v[190:193], v[44:47]
	v_mfma_f32_16x16x32_bf16 v[40:43], v[182:185], v[190:193], v[40:43]
	v_mfma_f32_16x16x32_bf16 v[36:39], v[174:177], v[198:201], v[36:39]
	v_mfma_f32_16x16x32_bf16 v[32:35], v[182:185], v[198:201], v[32:35]
	v_mfma_f32_16x16x32_bf16 v[12:15], v[174:177], v[206:209], v[12:15]
	v_mfma_f32_16x16x32_bf16 v[8:11], v[182:185], v[206:209], v[8:11]
	s_mov_b32 m0, s51
	s_nop 0
	global_load_lds_dwordx4 v[228:229], off
	v_mfma_f32_16x16x32_bf16 v[4:7], v[174:177], v[214:217], v[4:7]
	v_mfma_f32_16x16x32_bf16 v[0:3], v[182:185], v[214:217], v[0:3]
	v_mfma_f32_16x16x32_bf16 v[44:47], v[178:181], v[194:197], v[44:47]
	v_mfma_f32_16x16x32_bf16 v[40:43], v[186:189], v[194:197], v[40:43]
	v_mfma_f32_16x16x32_bf16 v[36:39], v[178:181], v[202:205], v[36:39]
	v_mfma_f32_16x16x32_bf16 v[32:35], v[186:189], v[202:205], v[32:35]
	v_mfma_f32_16x16x32_bf16 v[12:15], v[178:181], v[210:213], v[12:15]
	v_mfma_f32_16x16x32_bf16 v[8:11], v[186:189], v[210:213], v[8:11]
	v_mfma_f32_16x16x32_bf16 v[4:7], v[178:181], v[218:221], v[4:7]
	v_mfma_f32_16x16x32_bf16 v[0:3], v[186:189], v[218:221], v[0:3]
	s_setprio 0
	s_barrier
	s_add_i32 s87, 0, 0x18000
	s_add_i32 s88, 0, 0x1c000
	v_add_u32_e32 v170, s87, v157
	v_add_u32_e32 v186, s88, v157
	ds_read_b128 v[144:147], v170
	ds_read_b128 v[162:165], v170 offset:1024
	ds_read_b128 v[166:169], v170 offset:2048
	ds_read_b128 v[170:173], v170 offset:3072
	ds_read_b128 v[174:177], v186
	ds_read_b128 v[178:181], v186 offset:1024
	ds_read_b128 v[182:185], v186 offset:2048
	ds_read_b128 v[186:189], v186 offset:3072
	s_add_u32 s46, s46, 0x20000
	s_addc_u32 s47, s47, 0
	s_mov_b32 m0, s52
	v_lshl_add_u64 v[232:233], s[46:47], 0, v[128:129]
	ds_read_b128 v[190:193], v161 offset:32768
	ds_read_b128 v[194:197], v161 offset:33792
	ds_read_b128 v[198:201], v161 offset:34816
	ds_read_b128 v[202:205], v161 offset:35840
	ds_read_b128 v[206:209], v161 offset:36864
	ds_read_b128 v[210:213], v161 offset:37888
	ds_read_b128 v[214:217], v161 offset:38912
	ds_read_b128 v[218:221], v161 offset:39936
	global_load_lds_dwordx4 v[232:233], off
	v_lshl_add_u64 v[232:233], s[46:47], 0, v[132:133]
	s_mov_b32 m0, s53
	s_nop 0
	global_load_lds_dwordx4 v[232:233], off
	s_waitcnt vmcnt(8)
	s_waitcnt lgkmcnt(0)
	s_barrier
	s_setprio 1
	s_waitcnt lgkmcnt(0)
	v_mfma_f32_16x16x32_bf16 v[124:127], v[144:147], v[190:193], v[124:127]
	v_mfma_f32_16x16x32_bf16 v[120:123], v[166:169], v[190:193], v[120:123]
	v_mfma_f32_16x16x32_bf16 v[112:115], v[144:147], v[198:201], v[112:115]
	v_mfma_f32_16x16x32_bf16 v[104:107], v[166:169], v[198:201], v[104:107]
	v_mfma_f32_16x16x32_bf16 v[92:95], v[144:147], v[206:209], v[92:95]
	v_mfma_f32_16x16x32_bf16 v[88:91], v[166:169], v[206:209], v[88:91]
	v_mfma_f32_16x16x32_bf16 v[84:87], v[144:147], v[214:217], v[84:87]
	v_mfma_f32_16x16x32_bf16 v[80:83], v[166:169], v[214:217], v[80:83]
	v_mfma_f32_16x16x32_bf16 v[124:127], v[162:165], v[194:197], v[124:127]
	v_mfma_f32_16x16x32_bf16 v[120:123], v[170:173], v[194:197], v[120:123]
	v_mfma_f32_16x16x32_bf16 v[112:115], v[162:165], v[202:205], v[112:115]
	v_mfma_f32_16x16x32_bf16 v[104:107], v[170:173], v[202:205], v[104:107]
	v_mfma_f32_16x16x32_bf16 v[92:95], v[162:165], v[210:213], v[92:95]
	v_mfma_f32_16x16x32_bf16 v[88:91], v[170:173], v[210:213], v[88:91]
	v_mfma_f32_16x16x32_bf16 v[84:87], v[162:165], v[218:221], v[84:87]
	v_mfma_f32_16x16x32_bf16 v[80:83], v[170:173], v[218:221], v[80:83]
	s_setprio 0
	s_setprio 1
	v_mfma_f32_16x16x32_bf16 v[116:119], v[174:177], v[190:193], v[116:119]
	v_mfma_f32_16x16x32_bf16 v[108:111], v[182:185], v[190:193], v[108:111]
	v_mfma_f32_16x16x32_bf16 v[100:103], v[174:177], v[198:201], v[100:103]
	v_mfma_f32_16x16x32_bf16 v[96:99], v[182:185], v[198:201], v[96:99]
	v_mfma_f32_16x16x32_bf16 v[76:79], v[174:177], v[206:209], v[76:79]
	v_mfma_f32_16x16x32_bf16 v[72:75], v[182:185], v[206:209], v[72:75]
	v_mfma_f32_16x16x32_bf16 v[68:71], v[174:177], v[214:217], v[68:71]
	v_mfma_f32_16x16x32_bf16 v[64:67], v[182:185], v[214:217], v[64:67]
	v_mfma_f32_16x16x32_bf16 v[116:119], v[178:181], v[194:197], v[116:119]
	v_mfma_f32_16x16x32_bf16 v[108:111], v[186:189], v[194:197], v[108:111]
	v_mfma_f32_16x16x32_bf16 v[100:103], v[178:181], v[202:205], v[100:103]
	v_mfma_f32_16x16x32_bf16 v[96:99], v[186:189], v[202:205], v[96:99]
	v_mfma_f32_16x16x32_bf16 v[76:79], v[178:181], v[210:213], v[76:79]
	v_mfma_f32_16x16x32_bf16 v[72:75], v[186:189], v[210:213], v[72:75]
	v_mfma_f32_16x16x32_bf16 v[68:71], v[178:181], v[218:221], v[68:71]
	v_mfma_f32_16x16x32_bf16 v[64:67], v[186:189], v[218:221], v[64:67]
	s_setprio 0
	s_barrier
; #define PG8_STAGE(bufoff, gbase, voff) do { _Pragma("unroll") for (int _i = 0; _i < 2; ++_i) \
;         __builtin_amdgcn_global_load_lds((const unsigned*)((const char*)(gbase) + (voff)[_i]), (PG8_LAS unsigned*)(lds + (bufoff) + ldsw + _i * 8192), 16, 0, 0); } while (0)
; #define PG8_LDA(dst, b, h) do { _Pragma("unroll") for (int m = 0; m < 4; ++m) _Pragma("unroll") for (int k = 0; k < 2; ++k) dst[m][k] = *(const PG8_LAS bf16x8*)(lds + PG8_SA(b, h) + aoff + m * 2048 + k * 1024); } while (0)
; #define PG8_MMA(ai, bj, At, Bt) do { __builtin_amdgcn_s_setprio(1); _Pragma("unroll") for (int m = 0; m < 4; ++m) _Pragma("unroll") for (int n = 0; n < 2; ++n) _Pragma("unroll") for (int k = 0; k < 2; ++k) \
;         acc[ai][bj][m][n] = __builtin_amdgcn_mfma_f32_16x16x32_bf16(Bt[n][k], At[m][k], acc[ai][bj][m][n], 0, 0, 0); __builtin_amdgcn_s_setprio(0); } while (0)
; #define PG8_WAIT_V(n) asm volatile("s_waitcnt vmcnt(" #n ")" ::: "memory")
; #define PG8_BAR __builtin_amdgcn_s_barrier()
;     __device__ __forceinline__ void operator()(const f32x4 (&acc)[2][2][4][2], const Unit& u, int wr, int wc, int fr, int fq) const {
;         const int row0 = u.pm * BM + wr * 64 + fr, col0 = u.pn * BM + wc * 32 + 8 * fq;
;         const bf16_t* const G = (const bf16_t*)(ws + (ADD ? WS_GB : WS_GA)); bf16_t* const Mg = (bf16_t*)(ws + WS_GA);
; #pragma unroll
;         for (int ai = 0; ai < 2; ++ai)
; #pragma unroll
;         for (int mh = 0; mh < 4; mh += 2) {
;             u32x2 pg[4][2][2], pm_[4][2][2];
; #pragma unroll
;             for (int m = mh; m < mh + 2; ++m)
; #pragma unroll
;                 for (int bj = 0; bj < 2; ++bj)
; #pragma unroll
;                     for (int n = 0; n < 2; ++n) { const size_t off = (size_t)(row0 + ai * HALF + m * 16) * 1024 + col0 + bj * HALF + n * 4;
;                         pg[m][bj][n] = *(const u32x2*)(G + off); if (ADD) pm_[m][bj][n] = *(const u32x2*)(Mg + off); }
; template <class Epi, class Sched, bool ALIGN_EPI = false, bool SP2 = false>
; __device__ __forceinline__ void gemm_phase(PG8_LAS unsigned char* lds, const Gemm g, const Sched& S, const Epi& E) {
;     ...
;             PG8_LDA(At, 1, 1); PG8_STAGE(PG8_SB(1, 0), b3, voffB); PG8_STAGE(PG8_SB(1, 1), b3 + hstep, voffB); PG8_STAGE(PG8_SA(1, 0), a3, voffA);
;             PG8_WAIT_V(8); PG8_WAIT_L(0); PG8_BAR; PG8_MMA(1, 0, At, B0); PG8_MMA(1, 1, At, B1); PG8_BAR; PG8_SCHED;
	s_add_i32 s46, s87, s49
	v_lshl_add_u64 v[222:223], v[222:223], 0, s[6:7]
	s_mov_b32 m0, s46
	ds_read_b128 v[190:193], v161 offset:49152
	ds_read_b128 v[194:197], v161 offset:50176
	ds_read_b128 v[198:201], v161 offset:51200
	ds_read_b128 v[202:205], v161 offset:52224
	ds_read_b128 v[206:209], v161 offset:53248
	ds_read_b128 v[210:213], v161 offset:54272
	ds_read_b128 v[214:217], v161 offset:55296
	ds_read_b128 v[218:221], v161 offset:56320
	global_load_lds_dwordx4 v[222:223], off
	s_add_i32 m0, s46, 0x2000
	s_add_u32 s44, s44, 0x20080
	v_lshl_add_u64 v[222:223], v[224:225], 0, s[6:7]
	s_addc_u32 s45, s45, 0
	s_add_i32 s46, s88, s49
	global_load_lds_dwordx4 v[222:223], off
	v_lshl_add_u64 v[222:223], s[44:45], 0, v[130:131]
	s_mov_b32 m0, s46
	s_nop 0
	global_load_lds_dwordx4 v[222:223], off
	v_lshl_add_u64 v[222:223], s[44:45], 0, v[134:135]
	s_add_i32 m0, s46, 0x2000
	s_nop 0
	global_load_lds_dwordx4 v[222:223], off
	s_waitcnt vmcnt(6)
	s_waitcnt lgkmcnt(0)
	s_barrier
	s_setprio 1
	s_waitcnt lgkmcnt(0)
	v_mfma_f32_16x16x32_bf16 v[60:63], v[144:147], v[190:193], v[60:63]
	v_mfma_f32_16x16x32_bf16 v[56:59], v[166:169], v[190:193], v[56:59]
	v_mfma_f32_16x16x32_bf16 v[52:55], v[144:147], v[198:201], v[52:55]
	v_mfma_f32_16x16x32_bf16 v[48:51], v[166:169], v[198:201], v[48:51]
	v_mfma_f32_16x16x32_bf16 v[28:31], v[144:147], v[206:209], v[28:31]
	v_mfma_f32_16x16x32_bf16 v[24:27], v[166:169], v[206:209], v[24:27]
	v_lshl_add_u64 v[222:223], v[226:227], 0, s[6:7]
	s_mov_b32 m0, s61
	s_nop 0
	global_load_lds_dwordx4 v[222:223], off
	v_mfma_f32_16x16x32_bf16 v[20:23], v[144:147], v[214:217], v[20:23]
	v_mfma_f32_16x16x32_bf16 v[16:19], v[166:169], v[214:217], v[16:19]
	v_mfma_f32_16x16x32_bf16 v[60:63], v[162:165], v[194:197], v[60:63]
	v_mfma_f32_16x16x32_bf16 v[56:59], v[170:173], v[194:197], v[56:59]
	v_mfma_f32_16x16x32_bf16 v[52:55], v[162:165], v[202:205], v[52:55]
	v_mfma_f32_16x16x32_bf16 v[48:51], v[170:173], v[202:205], v[48:51]
	v_mfma_f32_16x16x32_bf16 v[28:31], v[162:165], v[210:213], v[28:31]
	v_mfma_f32_16x16x32_bf16 v[24:27], v[170:173], v[210:213], v[24:27]
	v_mfma_f32_16x16x32_bf16 v[20:23], v[162:165], v[218:221], v[20:23]
	v_mfma_f32_16x16x32_bf16 v[16:19], v[170:173], v[218:221], v[16:19]
	s_setprio 0
	s_setprio 1
	v_mfma_f32_16x16x32_bf16 v[44:47], v[174:177], v[190:193], v[44:47]
	v_mfma_f32_16x16x32_bf16 v[40:43], v[182:185], v[190:193], v[40:43]
	v_mfma_f32_16x16x32_bf16 v[36:39], v[174:177], v[198:201], v[36:39]
	v_mfma_f32_16x16x32_bf16 v[32:35], v[182:185], v[198:201], v[32:35]
	v_mfma_f32_16x16x32_bf16 v[12:15], v[174:177], v[206:209], v[12:15]
	v_mfma_f32_16x16x32_bf16 v[8:11], v[182:185], v[206:209], v[8:11]
	v_lshl_add_u64 v[222:223], v[228:229], 0, s[6:7]
	s_mov_b32 m0, s72
	s_nop 0
	global_load_lds_dwordx4 v[222:223], off
	v_mfma_f32_16x16x32_bf16 v[4:7], v[174:177], v[214:217], v[4:7]
	v_mfma_f32_16x16x32_bf16 v[0:3], v[182:185], v[214:217], v[0:3]
	v_mfma_f32_16x16x32_bf16 v[44:47], v[178:181], v[194:197], v[44:47]
	v_mfma_f32_16x16x32_bf16 v[40:43], v[186:189], v[194:197], v[40:43]
	v_mfma_f32_16x16x32_bf16 v[36:39], v[178:181], v[202:205], v[36:39]
	v_mfma_f32_16x16x32_bf16 v[32:35], v[186:189], v[202:205], v[32:35]
	v_mfma_f32_16x16x32_bf16 v[12:15], v[178:181], v[210:213], v[12:15]
	v_mfma_f32_16x16x32_bf16 v[8:11], v[186:189], v[210:213], v[8:11]
	v_mfma_f32_16x16x32_bf16 v[4:7], v[178:181], v[218:221], v[4:7]
	v_mfma_f32_16x16x32_bf16 v[0:3], v[186:189], v[218:221], v[0:3]
	s_setprio 0
	s_barrier
	s_add_i32 s86, s86, 2
	s_add_u32 s42, s42, 0x100
	s_addc_u32 s43, s43, 0
	s_add_u32 s84, s84, 0x100
	s_addc_u32 s85, s85, 0
	s_cmp_gt_u32 s86, 5
	s_cbranch_scc0 .LBB0_735
	v_lshl_add_u32 v178, s40, 8, v156
	v_lshl_or_b32 v144, s81, 8, v158
	v_ashrrev_i32_e32 v145, 31, v144
	v_ashrrev_i32_e32 v179, 31, v178
	v_lshl_add_u64 v[180:181], v[144:145], 1, s[0:1]
	v_lshlrev_b64 v[144:145], 11, v[178:179]
	v_or_b32_e32 v146, 16, v178
	v_lshl_add_u64 v[144:145], v[180:181], 0, v[144:145]
	v_ashrrev_i32_e32 v147, 31, v146
	global_load_dwordx4 v[162:165], v[144:145], off
	global_load_dwordx4 v[166:169], v[144:145], off offset:256
	v_lshlrev_b64 v[146:147], 11, v[146:147]
	v_lshl_add_u64 v[182:183], v[180:181], 0, v[146:147]
	global_load_dwordx4 v[170:173], v[182:183], off
	global_load_dwordx4 v[174:177], v[182:183], off offset:256
	v_or_b32_e32 v146, 32, v178
	v_ashrrev_i32_e32 v147, 31, v146
	v_lshlrev_b64 v[146:147], 11, v[146:147]
	v_lshl_add_u64 v[146:147], v[180:181], 0, v[146:147]
	s_mov_b32 s81, s24
	s_mov_b32 s40, s26
	s_mov_b64 s[44:45], s[38:39]
	s_mov_b64 s[42:43], s[36:37]
	s_waitcnt vmcnt(0)
; __device__ __forceinline__ u32x2 pack4(f32x4 v) { u32x2 w; w.x = cvt_pk_bf16(v[0], v[1]); w.y = cvt_pk_bf16(v[2], v[3]); return w; }
; __device__ __forceinline__ f32x4 unpack4(u32x2 w) { f32x4 v; v[0] = __uint_as_float(w.x << 16); v[1] = __uint_as_float(w.x & 0xffff0000u); v[2] = __uint_as_float(w.y << 16); v[3] = __uint_as_float(w.y & 0xffff0000u); return v; }
;     __device__ __forceinline__ void operator()(const f32x4 (&acc)[2][2][4][2], const Unit& u, int wr, int wc, int fr, int fq) const {
;     ...
;                     for (int n = 0; n < 2; ++n) { const size_t off = (size_t)(row0 + ai * HALF + m * 16) * 1024 + col0 + bj * HALF + n * 4;
;                         pg[m][bj][n] = *(const u32x2*)(G + off); if (ADD) pm_[m][bj][n] = *(const u32x2*)(Mg + off); }
;             asm volatile("" ::: "memory");
; #pragma unroll
;             for (int m = mh; m < mh + 2; ++m)
; #pragma unroll
;                 for (int bj = 0; bj < 2; ++bj)
; #pragma unroll
;                     for (int n = 0; n < 2; ++n) { const size_t off = (size_t)(row0 + ai * HALF + m * 16) * 1024 + col0 + bj * HALF + n * 4;
;                         f32x4 o = unpack4(pg[m][bj][n]) * acc[ai][bj][m][n]; if (ADD) o = o + unpack4(pm_[m][bj][n]);
;                         *(u32x2*)(Mg + off) = pack4(o); }
;             asm volatile("" ::: "memory");
	v_lshlrev_b32_e32 v184, 16, v162
	v_and_b32_e32 v185, 0xffff0000, v162
	v_lshlrev_b32_e32 v162, 16, v163
	v_and_b32_e32 v163, 0xffff0000, v163
	v_lshlrev_b32_e32 v188, 16, v166
	v_and_b32_e32 v189, 0xffff0000, v166
	v_lshlrev_b32_e32 v166, 16, v167
	v_and_b32_e32 v167, 0xffff0000, v167
	v_lshlrev_b32_e32 v190, 16, v168
	v_and_b32_e32 v191, 0xffff0000, v168
	v_lshlrev_b32_e32 v168, 16, v169
	v_and_b32_e32 v169, 0xffff0000, v169
	v_lshlrev_b32_e32 v186, 16, v164
	v_and_b32_e32 v187, 0xffff0000, v164
	v_lshlrev_b32_e32 v164, 16, v165
	v_and_b32_e32 v165, 0xffff0000, v165
	v_pk_mul_f32 v[126:127], v[126:127], v[162:163]
	v_pk_mul_f32 v[118:119], v[118:119], v[166:167]
	v_pk_mul_f32 v[162:163], v[110:111], v[168:169]
	v_lshlrev_b32_e32 v166, 16, v170
	v_and_b32_e32 v167, 0xffff0000, v170
	v_lshlrev_b32_e32 v168, 16, v171
	v_and_b32_e32 v169, 0xffff0000, v171
	v_lshlrev_b32_e32 v170, 16, v172
	v_and_b32_e32 v171, 0xffff0000, v172
	v_lshlrev_b32_e32 v172, 16, v173
	v_and_b32_e32 v173, 0xffff0000, v173
	v_pk_mul_f32 v[124:125], v[124:125], v[184:185]
	v_pk_mul_f32 v[122:123], v[122:123], v[164:165]
	v_pk_mul_f32 v[120:121], v[120:121], v[186:187]
	v_lshlrev_b32_e32 v184, 16, v174
	v_and_b32_e32 v185, 0xffff0000, v174
	v_lshlrev_b32_e32 v174, 16, v175
	v_and_b32_e32 v175, 0xffff0000, v175
	v_lshlrev_b32_e32 v186, 16, v176
	v_and_b32_e32 v187, 0xffff0000, v176
	v_lshlrev_b32_e32 v176, 16, v177
	v_and_b32_e32 v177, 0xffff0000, v177
	v_pk_mul_f32 v[114:115], v[114:115], v[168:169]
	v_pk_mul_f32 v[112:113], v[112:113], v[166:167]
	v_pk_mul_f32 v[106:107], v[106:107], v[172:173]
	v_pk_mul_f32 v[104:105], v[104:105], v[170:171]
	v_pk_mul_f32 v[116:117], v[116:117], v[188:189]
	v_pk_mul_f32 v[164:165], v[108:109], v[190:191]
	v_cvt_pk_bf16_f32 v108, v124, v125
	v_cvt_pk_bf16_f32 v109, v126, v127
	v_cvt_pk_bf16_f32 v110, v120, v121
	v_cvt_pk_bf16_f32 v111, v122, v123
	v_pk_mul_f32 v[102:103], v[102:103], v[174:175]
	v_pk_mul_f32 v[100:101], v[100:101], v[184:185]
	v_pk_mul_f32 v[120:121], v[98:99], v[176:177]
	v_pk_mul_f32 v[122:123], v[96:97], v[186:187]
	v_cvt_pk_bf16_f32 v96, v112, v113
	v_cvt_pk_bf16_f32 v97, v114, v115
	v_cvt_pk_bf16_f32 v98, v104, v105
	v_cvt_pk_bf16_f32 v99, v106, v107
	v_cvt_pk_bf16_f32 v116, v116, v117
	v_cvt_pk_bf16_f32 v117, v118, v119
	v_cvt_pk_bf16_f32 v118, v164, v165
	v_cvt_pk_bf16_f32 v119, v162, v163
	global_store_dwordx4 v[144:145], v[108:111], off
	global_store_dwordx4 v[144:145], v[116:119], off offset:256
	v_cvt_pk_bf16_f32 v100, v100, v101
	v_cvt_pk_bf16_f32 v101, v102, v103
	v_cvt_pk_bf16_f32 v102, v122, v123
	v_cvt_pk_bf16_f32 v103, v120, v121
	global_store_dwordx4 v[182:183], v[96:99], off
	global_store_dwordx4 v[182:183], v[100:103], off offset:256
	global_load_dwordx4 v[98:101], v[146:147], off
	global_load_dwordx4 v[102:105], v[146:147], off offset:256
	v_or_b32_e32 v96, 48, v178
	v_ashrrev_i32_e32 v97, 31, v96
	v_lshlrev_b64 v[96:97], 11, v[96:97]
	v_lshl_add_u64 v[114:115], v[180:181], 0, v[96:97]
	global_load_dwordx4 v[106:109], v[114:115], off
	global_load_dwordx4 v[110:113], v[114:115], off offset:256
	v_add_co_u32_e32 v96, vcc, s77, v144
	s_waitcnt vmcnt(3)
	v_lshlrev_b32_e32 v116, 16, v98
	v_and_b32_e32 v117, 0xffff0000, v98
	v_lshlrev_b32_e32 v98, 16, v99
	v_and_b32_e32 v99, 0xffff0000, v99
	v_lshlrev_b32_e32 v118, 16, v100
	v_and_b32_e32 v119, 0xffff0000, v100
	v_lshlrev_b32_e32 v100, 16, v101
	v_and_b32_e32 v101, 0xffff0000, v101
	s_waitcnt vmcnt(2)
	v_lshlrev_b32_e32 v120, 16, v102
	v_and_b32_e32 v121, 0xffff0000, v102
	v_lshlrev_b32_e32 v102, 16, v103
	v_and_b32_e32 v103, 0xffff0000, v103
	v_lshlrev_b32_e32 v122, 16, v104
	v_and_b32_e32 v123, 0xffff0000, v104
	v_lshlrev_b32_e32 v104, 16, v105
	v_and_b32_e32 v105, 0xffff0000, v105
	s_waitcnt vmcnt(1)
	v_lshlrev_b32_e32 v124, 16, v106
	v_and_b32_e32 v125, 0xffff0000, v106
	v_lshlrev_b32_e32 v106, 16, v107
	v_and_b32_e32 v107, 0xffff0000, v107
	v_lshlrev_b32_e32 v126, 16, v108
	v_and_b32_e32 v127, 0xffff0000, v108
	v_lshlrev_b32_e32 v108, 16, v109
	v_and_b32_e32 v109, 0xffff0000, v109
	s_waitcnt vmcnt(0)
	v_lshlrev_b32_e32 v162, 16, v110
	v_and_b32_e32 v163, 0xffff0000, v110
	v_lshlrev_b32_e32 v110, 16, v111
	v_and_b32_e32 v111, 0xffff0000, v111
	v_lshlrev_b32_e32 v164, 16, v112
	v_and_b32_e32 v165, 0xffff0000, v112
	v_lshlrev_b32_e32 v112, 16, v113
	v_and_b32_e32 v113, 0xffff0000, v113
	v_pk_mul_f32 v[94:95], v[94:95], v[98:99]
	v_pk_mul_f32 v[92:93], v[92:93], v[116:117]
	v_pk_mul_f32 v[90:91], v[90:91], v[100:101]
	v_pk_mul_f32 v[88:89], v[88:89], v[118:119]
	v_pk_mul_f32 v[78:79], v[78:79], v[102:103]
	v_pk_mul_f32 v[76:77], v[76:77], v[120:121]
	v_pk_mul_f32 v[74:75], v[74:75], v[104:105]
	v_pk_mul_f32 v[72:73], v[72:73], v[122:123]
	v_pk_mul_f32 v[86:87], v[86:87], v[106:107]
	v_pk_mul_f32 v[84:85], v[84:85], v[124:125]
	v_pk_mul_f32 v[82:83], v[82:83], v[108:109]
	v_pk_mul_f32 v[80:81], v[80:81], v[126:127]
	v_pk_mul_f32 v[98:99], v[70:71], v[110:111]
	v_pk_mul_f32 v[100:101], v[68:69], v[162:163]
	v_pk_mul_f32 v[102:103], v[66:67], v[112:113]
	v_pk_mul_f32 v[104:105], v[64:65], v[164:165]
	v_cvt_pk_bf16_f32 v64, v92, v93
	v_cvt_pk_bf16_f32 v65, v94, v95
	v_cvt_pk_bf16_f32 v66, v88, v89
	v_cvt_pk_bf16_f32 v67, v90, v91
	v_addc_co_u32_e32 v97, vcc, 0, v145, vcc
	v_cvt_pk_bf16_f32 v68, v76, v77
	v_cvt_pk_bf16_f32 v69, v78, v79
	v_cvt_pk_bf16_f32 v70, v72, v73
	v_cvt_pk_bf16_f32 v71, v74, v75
	v_cvt_pk_bf16_f32 v72, v84, v85
	v_cvt_pk_bf16_f32 v73, v86, v87
	v_cvt_pk_bf16_f32 v74, v80, v81
	v_cvt_pk_bf16_f32 v75, v82, v83
	v_cvt_pk_bf16_f32 v76, v100, v101
	v_cvt_pk_bf16_f32 v77, v98, v99
	v_cvt_pk_bf16_f32 v78, v104, v105
	v_cvt_pk_bf16_f32 v79, v102, v103
	global_store_dwordx4 v[146:147], v[64:67], off
	global_store_dwordx4 v[146:147], v[68:71], off offset:256
	global_store_dwordx4 v[114:115], v[72:75], off
	global_store_dwordx4 v[114:115], v[76:79], off offset:256
	v_add_co_u32_e32 v84, vcc, s78, v144
	global_load_dwordx4 v[66:69], v[96:97], off
	v_lshl_add_u64 v[82:83], v[144:145], 0, s[12:13]
	v_addc_co_u32_e32 v85, vcc, 0, v145, vcc
	v_lshl_add_u64 v[86:87], v[144:145], 0, s[14:15]
	global_load_dwordx4 v[70:73], v[82:83], off offset:256
	global_load_dwordx4 v[74:77], v[84:85], off
	global_load_dwordx4 v[78:81], v[86:87], off offset:256
	v_add_co_u32_e32 v64, vcc, s79, v144
	s_waitcnt vmcnt(3)
; __device__ __forceinline__ u32x2 pack4(f32x4 v) { u32x2 w; w.x = cvt_pk_bf16(v[0], v[1]); w.y = cvt_pk_bf16(v[2], v[3]); return w; }
; __device__ __forceinline__ f32x4 unpack4(u32x2 w) { f32x4 v; v[0] = __uint_as_float(w.x << 16); v[1] = __uint_as_float(w.x & 0xffff0000u); v[2] = __uint_as_float(w.y << 16); v[3] = __uint_as_float(w.y & 0xffff0000u); return v; }
; #define PG8_WAIT_V(n) asm volatile("s_waitcnt vmcnt(" #n ")" ::: "memory")
; #define PG8_BAR __builtin_amdgcn_s_barrier()
;     __device__ __forceinline__ void operator()(const f32x4 (&acc)[2][2][4][2], const Unit& u, int wr, int wc, int fr, int fq) const {
;     ...
;             for (int m = mh; m < mh + 2; ++m)
; #pragma unroll
;                 for (int bj = 0; bj < 2; ++bj)
; #pragma unroll
;                     for (int n = 0; n < 2; ++n) { const size_t off = (size_t)(row0 + ai * HALF + m * 16) * 1024 + col0 + bj * HALF + n * 4;
;                         f32x4 o = unpack4(pg[m][bj][n]) * acc[ai][bj][m][n]; if (ADD) o = o + unpack4(pm_[m][bj][n]);
;                         *(u32x2*)(Mg + off) = pack4(o); }
;             asm volatile("" ::: "memory");
; template <class Epi, class Sched, bool ALIGN_EPI = false, bool SP2 = false>
; __device__ __forceinline__ void gemm_phase(PG8_LAS unsigned char* lds, const Gemm g, const Sched& S, const Epi& E) {
;     ...
;         if (!has_next) break;
; #pragma unroll
;         for (int a = 0; a < 2; ++a)
; #pragma unroll
;             for (int b = 0; b < 2; ++b)
; #pragma unroll
;                 for (int m = 0; m < 4; ++m)
; #pragma unroll
;                     for (int n = 0; n < 2; ++n) acc[a][b][m][n] = (f32x4){0.f, 0.f, 0.f, 0.f};
;         cur = nxt; cA = nA; cB = nB; ++ui;
;         if constexpr (ALIGN_EPI) { if (wr == 1) PG8_BAR; }
;     }
;     PG8_WAIT_V(0);
;     if constexpr (!ALIGN_EPI) { if (wr == 0) PG8_BAR; }
;     PG8_BAR;
	v_lshlrev_b32_e32 v88, 16, v66
	v_and_b32_e32 v89, 0xffff0000, v66
	v_lshlrev_b32_e32 v66, 16, v67
	v_and_b32_e32 v67, 0xffff0000, v67
	v_lshlrev_b32_e32 v90, 16, v68
	v_and_b32_e32 v91, 0xffff0000, v68
	v_lshlrev_b32_e32 v68, 16, v69
	v_and_b32_e32 v69, 0xffff0000, v69
	s_waitcnt vmcnt(2)
	v_lshlrev_b32_e32 v92, 16, v70
	v_and_b32_e32 v93, 0xffff0000, v70
	v_lshlrev_b32_e32 v70, 16, v71
	v_and_b32_e32 v71, 0xffff0000, v71
	v_lshlrev_b32_e32 v94, 16, v72
	v_and_b32_e32 v95, 0xffff0000, v72
	v_lshlrev_b32_e32 v72, 16, v73
	v_and_b32_e32 v73, 0xffff0000, v73
	s_waitcnt vmcnt(1)
	v_lshlrev_b32_e32 v98, 16, v74
	v_and_b32_e32 v99, 0xffff0000, v74
	v_lshlrev_b32_e32 v74, 16, v75
	v_and_b32_e32 v75, 0xffff0000, v75
	v_lshlrev_b32_e32 v100, 16, v76
	v_and_b32_e32 v101, 0xffff0000, v76
	v_lshlrev_b32_e32 v76, 16, v77
	v_and_b32_e32 v77, 0xffff0000, v77
	s_waitcnt vmcnt(0)
	v_lshlrev_b32_e32 v102, 16, v78
	v_and_b32_e32 v103, 0xffff0000, v78
	v_lshlrev_b32_e32 v78, 16, v79
	v_and_b32_e32 v79, 0xffff0000, v79
	v_lshlrev_b32_e32 v104, 16, v80
	v_and_b32_e32 v105, 0xffff0000, v80
	v_lshlrev_b32_e32 v80, 16, v81
	v_and_b32_e32 v81, 0xffff0000, v81
	v_pk_mul_f32 v[62:63], v[62:63], v[66:67]
	v_pk_mul_f32 v[60:61], v[60:61], v[88:89]
	v_pk_mul_f32 v[58:59], v[58:59], v[68:69]
	v_pk_mul_f32 v[56:57], v[56:57], v[90:91]
	v_pk_mul_f32 v[46:47], v[46:47], v[70:71]
	v_pk_mul_f32 v[44:45], v[44:45], v[92:93]
	v_pk_mul_f32 v[42:43], v[42:43], v[72:73]
	v_pk_mul_f32 v[40:41], v[40:41], v[94:95]
	v_pk_mul_f32 v[54:55], v[54:55], v[74:75]
	v_pk_mul_f32 v[52:53], v[52:53], v[98:99]
	v_pk_mul_f32 v[50:51], v[50:51], v[76:77]
	v_pk_mul_f32 v[48:49], v[48:49], v[100:101]
	v_pk_mul_f32 v[66:67], v[38:39], v[78:79]
	v_pk_mul_f32 v[68:69], v[36:37], v[102:103]
	v_pk_mul_f32 v[70:71], v[34:35], v[80:81]
	v_pk_mul_f32 v[72:73], v[32:33], v[104:105]
	v_cvt_pk_bf16_f32 v32, v60, v61
	v_cvt_pk_bf16_f32 v33, v62, v63
	v_cvt_pk_bf16_f32 v34, v56, v57
	v_cvt_pk_bf16_f32 v35, v58, v59
	v_addc_co_u32_e32 v65, vcc, 0, v145, vcc
	v_cvt_pk_bf16_f32 v36, v44, v45
	v_cvt_pk_bf16_f32 v37, v46, v47
	v_cvt_pk_bf16_f32 v38, v40, v41
	v_cvt_pk_bf16_f32 v39, v42, v43
	v_cvt_pk_bf16_f32 v40, v52, v53
	v_cvt_pk_bf16_f32 v41, v54, v55
	v_cvt_pk_bf16_f32 v42, v48, v49
	v_cvt_pk_bf16_f32 v43, v50, v51
	v_cvt_pk_bf16_f32 v44, v68, v69
	v_cvt_pk_bf16_f32 v45, v66, v67
	v_cvt_pk_bf16_f32 v46, v72, v73
	v_cvt_pk_bf16_f32 v47, v70, v71
	global_store_dwordx4 v[96:97], v[32:35], off
	global_store_dwordx4 v[82:83], v[36:39], off offset:256
	global_store_dwordx4 v[84:85], v[40:43], off
	global_store_dwordx4 v[86:87], v[44:47], off offset:256
	v_add_co_u32_e32 v50, vcc, s80, v144
	global_load_dwordx4 v[32:35], v[64:65], off
	v_lshl_add_u64 v[48:49], v[144:145], 0, s[20:21]
	v_addc_co_u32_e32 v51, vcc, 0, v145, vcc
	v_lshl_add_u64 v[52:53], v[144:145], 0, s[22:23]
	global_load_dwordx4 v[36:39], v[48:49], off offset:256
	global_load_dwordx4 v[40:43], v[50:51], off
	global_load_dwordx4 v[44:47], v[52:53], off offset:256
	s_and_b64 vcc, exec, s[2:3]
	s_waitcnt vmcnt(3)
	v_lshlrev_b32_e32 v54, 16, v32
	v_and_b32_e32 v55, 0xffff0000, v32
	v_lshlrev_b32_e32 v32, 16, v33
	v_and_b32_e32 v33, 0xffff0000, v33
	v_lshlrev_b32_e32 v56, 16, v34
	v_and_b32_e32 v57, 0xffff0000, v34
	v_lshlrev_b32_e32 v34, 16, v35
	v_and_b32_e32 v35, 0xffff0000, v35
	s_waitcnt vmcnt(2)
	v_lshlrev_b32_e32 v58, 16, v36
	v_and_b32_e32 v59, 0xffff0000, v36
	v_lshlrev_b32_e32 v36, 16, v37
	v_and_b32_e32 v37, 0xffff0000, v37
	v_lshlrev_b32_e32 v60, 16, v38
	v_and_b32_e32 v61, 0xffff0000, v38
	v_lshlrev_b32_e32 v38, 16, v39
	v_and_b32_e32 v39, 0xffff0000, v39
	s_waitcnt vmcnt(1)
	v_lshlrev_b32_e32 v62, 16, v40
	v_and_b32_e32 v63, 0xffff0000, v40
	v_lshlrev_b32_e32 v40, 16, v41
	v_and_b32_e32 v41, 0xffff0000, v41
	v_lshlrev_b32_e32 v66, 16, v42
	v_and_b32_e32 v67, 0xffff0000, v42
	v_lshlrev_b32_e32 v42, 16, v43
	v_and_b32_e32 v43, 0xffff0000, v43
	s_waitcnt vmcnt(0)
	v_lshlrev_b32_e32 v68, 16, v44
	v_and_b32_e32 v69, 0xffff0000, v44
	v_lshlrev_b32_e32 v44, 16, v45
	v_and_b32_e32 v45, 0xffff0000, v45
	v_lshlrev_b32_e32 v70, 16, v46
	v_and_b32_e32 v71, 0xffff0000, v46
	v_lshlrev_b32_e32 v46, 16, v47
	v_and_b32_e32 v47, 0xffff0000, v47
	v_pk_mul_f32 v[30:31], v[30:31], v[32:33]
	v_pk_mul_f32 v[28:29], v[28:29], v[54:55]
	v_pk_mul_f32 v[26:27], v[26:27], v[34:35]
	v_pk_mul_f32 v[24:25], v[24:25], v[56:57]
	v_pk_mul_f32 v[14:15], v[14:15], v[36:37]
	v_pk_mul_f32 v[12:13], v[12:13], v[58:59]
	v_pk_mul_f32 v[10:11], v[10:11], v[38:39]
	v_pk_mul_f32 v[8:9], v[8:9], v[60:61]
	v_pk_mul_f32 v[22:23], v[22:23], v[40:41]
	v_pk_mul_f32 v[20:21], v[20:21], v[62:63]
	v_pk_mul_f32 v[18:19], v[18:19], v[42:43]
	v_pk_mul_f32 v[16:17], v[16:17], v[66:67]
	v_pk_mul_f32 v[32:33], v[6:7], v[44:45]
	v_pk_mul_f32 v[34:35], v[4:5], v[68:69]
	v_pk_mul_f32 v[36:37], v[2:3], v[46:47]
	v_pk_mul_f32 v[38:39], v[0:1], v[70:71]
	v_cvt_pk_bf16_f32 v0, v28, v29
	v_cvt_pk_bf16_f32 v1, v30, v31
	v_cvt_pk_bf16_f32 v2, v24, v25
	v_cvt_pk_bf16_f32 v3, v26, v27
	v_cvt_pk_bf16_f32 v4, v12, v13
	v_cvt_pk_bf16_f32 v5, v14, v15
	v_cvt_pk_bf16_f32 v6, v8, v9
	v_cvt_pk_bf16_f32 v7, v10, v11
	v_cvt_pk_bf16_f32 v8, v20, v21
	v_cvt_pk_bf16_f32 v9, v22, v23
	v_cvt_pk_bf16_f32 v10, v16, v17
	v_cvt_pk_bf16_f32 v11, v18, v19
	v_cvt_pk_bf16_f32 v12, v34, v35
	v_cvt_pk_bf16_f32 v13, v32, v33
	v_cvt_pk_bf16_f32 v14, v38, v39
	v_cvt_pk_bf16_f32 v15, v36, v37
	global_store_dwordx4 v[64:65], v[0:3], off
	global_store_dwordx4 v[48:49], v[4:7], off offset:256
	global_store_dwordx4 v[50:51], v[8:11], off
	global_store_dwordx4 v[52:53], v[12:15], off offset:256
	s_cbranch_vccz .LBB0_732
	s_waitcnt vmcnt(0)
	s_cmpk_gt_u32 s48, 0xff
	s_cbranch_scc1 .LBB0_739
	s_barrier

; #define PG8_STAGE(bufoff, gbase, voff) do { _Pragma("unroll") for (int _i = 0; _i < 2; ++_i) \
;         __builtin_amdgcn_global_load_lds((const unsigned*)((const char*)(gbase) + (voff)[_i]), (PG8_LAS unsigned*)(lds + (bufoff) + ldsw + _i * 8192), 16, 0, 0); } while (0)
; #define PG8_LDA(dst, b, h) do { _Pragma("unroll") for (int m = 0; m < 4; ++m) _Pragma("unroll") for (int k = 0; k < 2; ++k) dst[m][k] = *(const PG8_LAS bf16x8*)(lds + PG8_SA(b, h) + aoff + m * 2048 + k * 1024); } while (0)
; #define PG8_LDB(dst, b, h) do { _Pragma("unroll") for (int n = 0; n < 2; ++n) _Pragma("unroll") for (int k = 0; k < 2; ++k) dst[n][k] = *(const PG8_LAS bf16x8*)(lds + PG8_SB(b, h) + boff + n * 2048 + k * 1024); } while (0)
; #define PG8_MMA(ai, bj, At, Bt) do { __builtin_amdgcn_s_setprio(1); _Pragma("unroll") for (int m = 0; m < 4; ++m) _Pragma("unroll") for (int n = 0; n < 2; ++n) _Pragma("unroll") for (int k = 0; k < 2; ++k) \
;         acc[ai][bj][m][n] = __builtin_amdgcn_mfma_f32_16x16x32_bf16(Bt[n][k], At[m][k], acc[ai][bj][m][n], 0, 0, 0); __builtin_amdgcn_s_setprio(0); } while (0)
; #define PG8_WAIT_V(n) asm volatile("s_waitcnt vmcnt(" #n ")" ::: "memory")
; #define PG8_WAIT_L(n) asm volatile("s_waitcnt lgkmcnt(" #n ")" ::: "memory")
; #define PG8_BAR __builtin_amdgcn_s_barrier()
; #define PG8_SCHED __builtin_amdgcn_sched_barrier(0)
; template <class Epi, class Sched, bool ALIGN_EPI = false, bool SP2 = false>
; __device__ __forceinline__ void gemm_phase(PG8_LAS unsigned char* lds, const Gemm g, const Sched& S, const Epi& E) {
;     ...
;             PG8_LDB(B0, 0, 0); PG8_LDB(B1, 0, 1); PG8_SCHED; PG8_LDA(At, 0, 0); PG8_STAGE(PG8_SA(1, 1), a1 + hstep, voffA);
;             PG8_WAIT_V(8); PG8_WAIT_L(0); PG8_BAR; PG8_MMA(0, 0, At, B0); PG8_MMA(0, 1, At, B1); PG8_BAR; PG8_SCHED;
;             PG8_LDA(At, 0, 1); PG8_STAGE(PG8_SB(0, 0), b2, voffB); PG8_STAGE(PG8_SB(0, 1), b2 + hstep, voffB); PG8_STAGE(PG8_SA(0, 0), a2, voffA);
;             PG8_WAIT_V(8); PG8_WAIT_L(0); PG8_BAR; PG8_MMA(1, 0, At, B0); PG8_MMA(1, 1, At, B1); PG8_BAR; PG8_SCHED;
.LBB0_747:
	ds_read_b128 v[144:147], v150
	ds_read_b128 v[158:161], v150 offset:1024
	ds_read_b128 v[162:165], v150 offset:2048
	ds_read_b128 v[166:169], v150 offset:3072
	ds_read_b128 v[170:173], v152
	ds_read_b128 v[174:177], v152 offset:1024
	ds_read_b128 v[178:181], v152 offset:2048
	ds_read_b128 v[182:185], v152 offset:3072
	s_add_u32 s36, s26, 0xfffe0080
	s_addc_u32 s37, s27, -1
	s_cmp_eq_u32 s72, 4
	s_cselect_b32 s39, s15, s37
	s_cselect_b32 s38, s60, s36
	s_cselect_b32 s37, s13, s71
	s_cselect_b32 s36, s61, s70
	v_lshl_add_u64 v[148:149], s[26:27], 0, v[136:137]
	s_add_i32 m0, s25, 0xc000
	ds_read_b128 v[186:189], v154
	ds_read_b128 v[190:193], v154 offset:1024
	ds_read_b128 v[194:197], v154 offset:2048
	ds_read_b128 v[198:201], v154 offset:3072
	ds_read_b128 v[202:205], v154 offset:4096
	ds_read_b128 v[206:209], v154 offset:5120
	ds_read_b128 v[210:213], v154 offset:6144
	ds_read_b128 v[214:217], v154 offset:7168
	global_load_lds_dwordx4 v[148:149], off
	v_lshl_add_u64 v[148:149], s[26:27], 0, v[138:139]
	s_add_i32 m0, s25, 0xe000
	s_nop 0
	global_load_lds_dwordx4 v[148:149], off
	s_waitcnt vmcnt(8)
	s_waitcnt lgkmcnt(0)
	s_barrier
	s_setprio 1
	s_waitcnt lgkmcnt(0)
	v_mfma_f32_16x16x32_bf16 v[124:127], v[144:147], v[186:189], v[124:127]
	v_mfma_f32_16x16x32_bf16 v[120:123], v[162:165], v[186:189], v[120:123]
	v_mfma_f32_16x16x32_bf16 v[116:119], v[144:147], v[194:197], v[116:119]
	v_mfma_f32_16x16x32_bf16 v[104:107], v[162:165], v[194:197], v[104:107]
	v_mfma_f32_16x16x32_bf16 v[92:95], v[144:147], v[202:205], v[92:95]
	v_mfma_f32_16x16x32_bf16 v[88:91], v[162:165], v[202:205], v[88:91]
	v_mfma_f32_16x16x32_bf16 v[80:83], v[144:147], v[210:213], v[80:83]
	v_mfma_f32_16x16x32_bf16 v[72:75], v[162:165], v[210:213], v[72:75]
	v_mfma_f32_16x16x32_bf16 v[124:127], v[158:161], v[190:193], v[124:127]
	v_mfma_f32_16x16x32_bf16 v[120:123], v[166:169], v[190:193], v[120:123]
	v_mfma_f32_16x16x32_bf16 v[116:119], v[158:161], v[198:201], v[116:119]
	v_mfma_f32_16x16x32_bf16 v[104:107], v[166:169], v[198:201], v[104:107]
	v_mfma_f32_16x16x32_bf16 v[92:95], v[158:161], v[206:209], v[92:95]
	v_mfma_f32_16x16x32_bf16 v[88:91], v[166:169], v[206:209], v[88:91]
	v_mfma_f32_16x16x32_bf16 v[80:83], v[158:161], v[214:217], v[80:83]
	v_mfma_f32_16x16x32_bf16 v[72:75], v[166:169], v[214:217], v[72:75]
	s_setprio 0
	s_setprio 1
	v_mfma_f32_16x16x32_bf16 v[112:115], v[170:173], v[186:189], v[112:115]
	v_mfma_f32_16x16x32_bf16 v[108:111], v[178:181], v[186:189], v[108:111]
	v_mfma_f32_16x16x32_bf16 v[100:103], v[170:173], v[194:197], v[100:103]
	v_mfma_f32_16x16x32_bf16 v[96:99], v[178:181], v[194:197], v[96:99]
	v_mfma_f32_16x16x32_bf16 v[84:87], v[170:173], v[202:205], v[84:87]
	v_mfma_f32_16x16x32_bf16 v[76:79], v[178:181], v[202:205], v[76:79]
	v_mfma_f32_16x16x32_bf16 v[68:71], v[170:173], v[210:213], v[68:71]
	v_mfma_f32_16x16x32_bf16 v[64:67], v[178:181], v[210:213], v[64:67]
	v_mfma_f32_16x16x32_bf16 v[112:115], v[174:177], v[190:193], v[112:115]
	v_mfma_f32_16x16x32_bf16 v[108:111], v[182:185], v[190:193], v[108:111]
	v_mfma_f32_16x16x32_bf16 v[100:103], v[174:177], v[198:201], v[100:103]
	v_mfma_f32_16x16x32_bf16 v[96:99], v[182:185], v[198:201], v[96:99]
	v_mfma_f32_16x16x32_bf16 v[84:87], v[174:177], v[206:209], v[84:87]
	v_mfma_f32_16x16x32_bf16 v[76:79], v[182:185], v[206:209], v[76:79]
	v_mfma_f32_16x16x32_bf16 v[68:71], v[174:177], v[214:217], v[68:71]
	v_mfma_f32_16x16x32_bf16 v[64:67], v[182:185], v[214:217], v[64:67]
	s_setprio 0
	s_barrier
	s_add_i32 s73, s51, s41
	v_lshl_add_u64 v[148:149], s[36:37], 0, v[130:131]
	s_mov_b32 m0, s73
	ds_read_b128 v[186:189], v154 offset:16384
	ds_read_b128 v[190:193], v154 offset:17408
	ds_read_b128 v[194:197], v154 offset:18432
	ds_read_b128 v[198:201], v154 offset:19456
	ds_read_b128 v[202:205], v154 offset:20480
	ds_read_b128 v[206:209], v154 offset:21504
	ds_read_b128 v[210:213], v154 offset:22528
	ds_read_b128 v[214:217], v154 offset:23552
	global_load_lds_dwordx4 v[148:149], off
	s_add_i32 m0, s73, 0x2000
	s_add_u32 s74, s36, 0x20000
	v_lshl_add_u64 v[218:219], s[36:37], 0, v[134:135]
	s_addc_u32 s75, s37, 0
	s_add_i32 s73, s52, s41
	global_load_lds_dwordx4 v[218:219], off
	v_lshl_add_u64 v[220:221], s[74:75], 0, v[130:131]
	s_mov_b32 m0, s73
	v_lshl_add_u64 v[222:223], s[38:39], 0, v[132:133]
	global_load_lds_dwordx4 v[220:221], off
	v_lshl_add_u64 v[220:221], s[74:75], 0, v[134:135]
	s_add_i32 m0, s73, 0x2000
	s_nop 0
	global_load_lds_dwordx4 v[220:221], off
	s_waitcnt vmcnt(6)
	s_waitcnt lgkmcnt(0)
	s_barrier
; #define PG8_STAGE(bufoff, gbase, voff) do { _Pragma("unroll") for (int _i = 0; _i < 2; ++_i) \
;         __builtin_amdgcn_global_load_lds((const unsigned*)((const char*)(gbase) + (voff)[_i]), (PG8_LAS unsigned*)(lds + (bufoff) + ldsw + _i * 8192), 16, 0, 0); } while (0)
; #define PG8_LDA(dst, b, h) do { _Pragma("unroll") for (int m = 0; m < 4; ++m) _Pragma("unroll") for (int k = 0; k < 2; ++k) dst[m][k] = *(const PG8_LAS bf16x8*)(lds + PG8_SA(b, h) + aoff + m * 2048 + k * 1024); } while (0)
; #define PG8_LDB(dst, b, h) do { _Pragma("unroll") for (int n = 0; n < 2; ++n) _Pragma("unroll") for (int k = 0; k < 2; ++k) dst[n][k] = *(const PG8_LAS bf16x8*)(lds + PG8_SB(b, h) + boff + n * 2048 + k * 1024); } while (0)
; #define PG8_MMA(ai, bj, At, Bt) do { __builtin_amdgcn_s_setprio(1); _Pragma("unroll") for (int m = 0; m < 4; ++m) _Pragma("unroll") for (int n = 0; n < 2; ++n) _Pragma("unroll") for (int k = 0; k < 2; ++k) \
;         acc[ai][bj][m][n] = __builtin_amdgcn_mfma_f32_16x16x32_bf16(Bt[n][k], At[m][k], acc[ai][bj][m][n], 0, 0, 0); __builtin_amdgcn_s_setprio(0); } while (0)
; #define PG8_WAIT_V(n) asm volatile("s_waitcnt vmcnt(" #n ")" ::: "memory")
; #define PG8_WAIT_L(n) asm volatile("s_waitcnt lgkmcnt(" #n ")" ::: "memory")
; #define PG8_BAR __builtin_amdgcn_s_barrier()
; #define PG8_SCHED __builtin_amdgcn_sched_barrier(0)
; template <class Epi, class Sched, bool ALIGN_EPI = false, bool SP2 = false>
; __device__ __forceinline__ void gemm_phase(PG8_LAS unsigned char* lds, const Gemm g, const Sched& S, const Epi& E) {
;     ...
;             PG8_WAIT_V(8); PG8_WAIT_L(0); PG8_BAR; PG8_MMA(1, 0, At, B0); PG8_MMA(1, 1, At, B1); PG8_BAR; PG8_SCHED;
;             PG8_LDB(B0, 1, 0); PG8_LDB(B1, 1, 1); PG8_SCHED; PG8_LDA(At, 1, 0); PG8_STAGE(PG8_SA(0, 1), a2 + hstep, voffA);
;             PG8_WAIT_V(8); PG8_WAIT_L(0); PG8_BAR; PG8_MMA(0, 0, At, B0); PG8_MMA(0, 1, At, B1); PG8_BAR; PG8_SCHED;
	s_setprio 1
	s_waitcnt lgkmcnt(0)
	v_mfma_f32_16x16x32_bf16 v[60:63], v[144:147], v[186:189], v[60:63]
	v_mfma_f32_16x16x32_bf16 v[56:59], v[162:165], v[186:189], v[56:59]
	v_mfma_f32_16x16x32_bf16 v[48:51], v[144:147], v[194:197], v[48:51]
	v_mfma_f32_16x16x32_bf16 v[40:43], v[162:165], v[194:197], v[40:43]
	v_mfma_f32_16x16x32_bf16 v[28:31], v[144:147], v[202:205], v[28:31]
	v_mfma_f32_16x16x32_bf16 v[24:27], v[162:165], v[202:205], v[24:27]
	v_lshl_add_u64 v[220:221], s[38:39], 0, v[128:129]
	s_mov_b32 m0, s25
	s_nop 0
	global_load_lds_dwordx4 v[220:221], off
	v_mfma_f32_16x16x32_bf16 v[16:19], v[144:147], v[210:213], v[16:19]
	v_mfma_f32_16x16x32_bf16 v[8:11], v[162:165], v[210:213], v[8:11]
	v_mfma_f32_16x16x32_bf16 v[60:63], v[158:161], v[190:193], v[60:63]
	v_mfma_f32_16x16x32_bf16 v[56:59], v[166:169], v[190:193], v[56:59]
	v_mfma_f32_16x16x32_bf16 v[48:51], v[158:161], v[198:201], v[48:51]
	v_mfma_f32_16x16x32_bf16 v[40:43], v[166:169], v[198:201], v[40:43]
	v_mfma_f32_16x16x32_bf16 v[28:31], v[158:161], v[206:209], v[28:31]
	v_mfma_f32_16x16x32_bf16 v[24:27], v[166:169], v[206:209], v[24:27]
	v_mfma_f32_16x16x32_bf16 v[16:19], v[158:161], v[214:217], v[16:19]
	v_mfma_f32_16x16x32_bf16 v[8:11], v[166:169], v[214:217], v[8:11]
	s_setprio 0
	s_setprio 1
	v_mfma_f32_16x16x32_bf16 v[52:55], v[170:173], v[186:189], v[52:55]
	v_mfma_f32_16x16x32_bf16 v[44:47], v[178:181], v[186:189], v[44:47]
	v_mfma_f32_16x16x32_bf16 v[36:39], v[170:173], v[194:197], v[36:39]
	v_mfma_f32_16x16x32_bf16 v[32:35], v[178:181], v[194:197], v[32:35]
	v_mfma_f32_16x16x32_bf16 v[20:23], v[170:173], v[202:205], v[20:23]
	v_mfma_f32_16x16x32_bf16 v[12:15], v[178:181], v[202:205], v[12:15]
	s_mov_b32 m0, s44
	s_nop 0
	global_load_lds_dwordx4 v[222:223], off
	v_mfma_f32_16x16x32_bf16 v[4:7], v[170:173], v[210:213], v[4:7]
	v_mfma_f32_16x16x32_bf16 v[0:3], v[178:181], v[210:213], v[0:3]
	v_mfma_f32_16x16x32_bf16 v[52:55], v[174:177], v[190:193], v[52:55]
	v_mfma_f32_16x16x32_bf16 v[44:47], v[182:185], v[190:193], v[44:47]
	v_mfma_f32_16x16x32_bf16 v[36:39], v[174:177], v[198:201], v[36:39]
	v_mfma_f32_16x16x32_bf16 v[32:35], v[182:185], v[198:201], v[32:35]
	v_mfma_f32_16x16x32_bf16 v[20:23], v[174:177], v[206:209], v[20:23]
	v_mfma_f32_16x16x32_bf16 v[12:15], v[182:185], v[206:209], v[12:15]
	v_mfma_f32_16x16x32_bf16 v[4:7], v[174:177], v[214:217], v[4:7]
	v_mfma_f32_16x16x32_bf16 v[0:3], v[182:185], v[214:217], v[0:3]
	s_setprio 0
	s_barrier
	s_add_i32 s73, 0, 0x18000
	v_add_u32_e32 v155, s73, v153
	s_add_i32 s74, 0, 0x1c000
	ds_read_b128 v[144:147], v155
	ds_read_b128 v[158:161], v155 offset:1024
	ds_read_b128 v[162:165], v155 offset:2048
	ds_read_b128 v[166:169], v155 offset:3072
	v_add_u32_e32 v155, s74, v153
	ds_read_b128 v[170:173], v155
	ds_read_b128 v[174:177], v155 offset:1024
	ds_read_b128 v[178:181], v155 offset:2048
	ds_read_b128 v[182:185], v155 offset:3072
	s_add_u32 s38, s38, 0x20000
	s_addc_u32 s39, s39, 0
	s_mov_b32 m0, s45
	v_lshl_add_u64 v[224:225], s[38:39], 0, v[128:129]
	ds_read_b128 v[186:189], v154 offset:32768
	ds_read_b128 v[190:193], v154 offset:33792
	ds_read_b128 v[194:197], v154 offset:34816
	ds_read_b128 v[198:201], v154 offset:35840
	ds_read_b128 v[202:205], v154 offset:36864
	ds_read_b128 v[206:209], v154 offset:37888
	ds_read_b128 v[210:213], v154 offset:38912
	ds_read_b128 v[214:217], v154 offset:39936
	global_load_lds_dwordx4 v[224:225], off
	v_lshl_add_u64 v[224:225], s[38:39], 0, v[132:133]
	s_mov_b32 m0, s46
	s_nop 0
	global_load_lds_dwordx4 v[224:225], off
	s_waitcnt vmcnt(8)
	s_waitcnt lgkmcnt(0)
	s_barrier
	s_setprio 1
	s_waitcnt lgkmcnt(0)
	v_mfma_f32_16x16x32_bf16 v[124:127], v[144:147], v[186:189], v[124:127]
	v_mfma_f32_16x16x32_bf16 v[120:123], v[162:165], v[186:189], v[120:123]
	v_mfma_f32_16x16x32_bf16 v[116:119], v[144:147], v[194:197], v[116:119]
	v_mfma_f32_16x16x32_bf16 v[104:107], v[162:165], v[194:197], v[104:107]
	v_mfma_f32_16x16x32_bf16 v[92:95], v[144:147], v[202:205], v[92:95]
	v_mfma_f32_16x16x32_bf16 v[88:91], v[162:165], v[202:205], v[88:91]
	v_mfma_f32_16x16x32_bf16 v[80:83], v[144:147], v[210:213], v[80:83]
	v_mfma_f32_16x16x32_bf16 v[72:75], v[162:165], v[210:213], v[72:75]
	v_mfma_f32_16x16x32_bf16 v[124:127], v[158:161], v[190:193], v[124:127]
	v_mfma_f32_16x16x32_bf16 v[120:123], v[166:169], v[190:193], v[120:123]
	v_mfma_f32_16x16x32_bf16 v[116:119], v[158:161], v[198:201], v[116:119]
	v_mfma_f32_16x16x32_bf16 v[104:107], v[166:169], v[198:201], v[104:107]
	v_mfma_f32_16x16x32_bf16 v[92:95], v[158:161], v[206:209], v[92:95]
	v_mfma_f32_16x16x32_bf16 v[88:91], v[166:169], v[206:209], v[88:91]
	v_mfma_f32_16x16x32_bf16 v[80:83], v[158:161], v[214:217], v[80:83]
	v_mfma_f32_16x16x32_bf16 v[72:75], v[166:169], v[214:217], v[72:75]
	s_setprio 0
	s_setprio 1
	v_mfma_f32_16x16x32_bf16 v[112:115], v[170:173], v[186:189], v[112:115]
	v_mfma_f32_16x16x32_bf16 v[108:111], v[178:181], v[186:189], v[108:111]
	v_mfma_f32_16x16x32_bf16 v[100:103], v[170:173], v[194:197], v[100:103]
	v_mfma_f32_16x16x32_bf16 v[96:99], v[178:181], v[194:197], v[96:99]
	v_mfma_f32_16x16x32_bf16 v[84:87], v[170:173], v[202:205], v[84:87]
	v_mfma_f32_16x16x32_bf16 v[76:79], v[178:181], v[202:205], v[76:79]
	v_mfma_f32_16x16x32_bf16 v[68:71], v[170:173], v[210:213], v[68:71]
	v_mfma_f32_16x16x32_bf16 v[64:67], v[178:181], v[210:213], v[64:67]
	v_mfma_f32_16x16x32_bf16 v[112:115], v[174:177], v[190:193], v[112:115]
	v_mfma_f32_16x16x32_bf16 v[108:111], v[182:185], v[190:193], v[108:111]
	v_mfma_f32_16x16x32_bf16 v[100:103], v[174:177], v[198:201], v[100:103]
	v_mfma_f32_16x16x32_bf16 v[96:99], v[182:185], v[198:201], v[96:99]
	v_mfma_f32_16x16x32_bf16 v[84:87], v[174:177], v[206:209], v[84:87]
	v_mfma_f32_16x16x32_bf16 v[76:79], v[182:185], v[206:209], v[76:79]
	v_mfma_f32_16x16x32_bf16 v[68:71], v[174:177], v[214:217], v[68:71]
	v_mfma_f32_16x16x32_bf16 v[64:67], v[182:185], v[214:217], v[64:67]
	s_setprio 0
	s_barrier
; #define PG8_STAGE(bufoff, gbase, voff) do { _Pragma("unroll") for (int _i = 0; _i < 2; ++_i) \
;         __builtin_amdgcn_global_load_lds((const unsigned*)((const char*)(gbase) + (voff)[_i]), (PG8_LAS unsigned*)(lds + (bufoff) + ldsw + _i * 8192), 16, 0, 0); } while (0)
; #define PG8_LDA(dst, b, h) do { _Pragma("unroll") for (int m = 0; m < 4; ++m) _Pragma("unroll") for (int k = 0; k < 2; ++k) dst[m][k] = *(const PG8_LAS bf16x8*)(lds + PG8_SA(b, h) + aoff + m * 2048 + k * 1024); } while (0)
; #define PG8_MMA(ai, bj, At, Bt) do { __builtin_amdgcn_s_setprio(1); _Pragma("unroll") for (int m = 0; m < 4; ++m) _Pragma("unroll") for (int n = 0; n < 2; ++n) _Pragma("unroll") for (int k = 0; k < 2; ++k) \
;         acc[ai][bj][m][n] = __builtin_amdgcn_mfma_f32_16x16x32_bf16(Bt[n][k], At[m][k], acc[ai][bj][m][n], 0, 0, 0); __builtin_amdgcn_s_setprio(0); } while (0)
; #define PG8_WAIT_V(n) asm volatile("s_waitcnt vmcnt(" #n ")" ::: "memory")
; #define PG8_BAR __builtin_amdgcn_s_barrier()
;     __device__ __forceinline__ void operator()(const f32x4 (&acc)[2][2][4][2], const Unit& u, int wr, int wc, int fr, int fq) const {
;         const int row0 = u.pm * BM + wr * 64 + fr, col0 = u.pn * BM + wc * 32 + 8 * fq;
;         const bf16_t* const G = (const bf16_t*)(ws + (ADD ? WS_GB : WS_GA)); bf16_t* const Mg = (bf16_t*)(ws + WS_GA);
; #pragma unroll
;         for (int ai = 0; ai < 2; ++ai)
; #pragma unroll
;         for (int mh = 0; mh < 4; mh += 2) {
;             u32x2 pg[4][2][2], pm_[4][2][2];
; #pragma unroll
;             for (int m = mh; m < mh + 2; ++m)
; #pragma unroll
;                 for (int bj = 0; bj < 2; ++bj)
; #pragma unroll
;                     for (int n = 0; n < 2; ++n) { const size_t off = (size_t)(row0 + ai * HALF + m * 16) * 1024 + col0 + bj * HALF + n * 4;
;                         pg[m][bj][n] = *(const u32x2*)(G + off); if (ADD) pm_[m][bj][n] = *(const u32x2*)(Mg + off); }
; template <class Epi, class Sched, bool ALIGN_EPI = false, bool SP2 = false>
; __device__ __forceinline__ void gemm_phase(PG8_LAS unsigned char* lds, const Gemm g, const Sched& S, const Epi& E) {
;     ...
;             PG8_LDA(At, 1, 1); PG8_STAGE(PG8_SB(1, 0), b3, voffB); PG8_STAGE(PG8_SB(1, 1), b3 + hstep, voffB); PG8_STAGE(PG8_SA(1, 0), a3, voffA);
;             PG8_WAIT_V(8); PG8_WAIT_L(0); PG8_BAR; PG8_MMA(1, 0, At, B0); PG8_MMA(1, 1, At, B1); PG8_BAR; PG8_SCHED;
	s_add_i32 s38, s73, s41
	v_lshl_add_u64 v[148:149], v[148:149], 0, s[4:5]
	s_mov_b32 m0, s38
	ds_read_b128 v[186:189], v154 offset:49152
	ds_read_b128 v[190:193], v154 offset:50176
	ds_read_b128 v[194:197], v154 offset:51200
	ds_read_b128 v[198:201], v154 offset:52224
	ds_read_b128 v[202:205], v154 offset:53248
	ds_read_b128 v[206:209], v154 offset:54272
	ds_read_b128 v[210:213], v154 offset:55296
	ds_read_b128 v[214:217], v154 offset:56320
	global_load_lds_dwordx4 v[148:149], off
	s_add_i32 m0, s38, 0x2000
	s_add_u32 s36, s36, 0x20080
	v_lshl_add_u64 v[148:149], v[218:219], 0, s[4:5]
	s_addc_u32 s37, s37, 0
	s_add_i32 s38, s74, s41
	global_load_lds_dwordx4 v[148:149], off
	v_lshl_add_u64 v[148:149], s[36:37], 0, v[130:131]
	s_mov_b32 m0, s38
	s_nop 0
	global_load_lds_dwordx4 v[148:149], off
	v_lshl_add_u64 v[148:149], s[36:37], 0, v[134:135]
	s_add_i32 m0, s38, 0x2000
	s_nop 0
	global_load_lds_dwordx4 v[148:149], off
	s_waitcnt vmcnt(6)
	s_waitcnt lgkmcnt(0)
	s_barrier
	s_setprio 1
	s_waitcnt lgkmcnt(0)
	v_mfma_f32_16x16x32_bf16 v[60:63], v[144:147], v[186:189], v[60:63]
	v_mfma_f32_16x16x32_bf16 v[56:59], v[162:165], v[186:189], v[56:59]
	v_mfma_f32_16x16x32_bf16 v[48:51], v[144:147], v[194:197], v[48:51]
	v_mfma_f32_16x16x32_bf16 v[40:43], v[162:165], v[194:197], v[40:43]
	v_mfma_f32_16x16x32_bf16 v[28:31], v[144:147], v[202:205], v[28:31]
	v_mfma_f32_16x16x32_bf16 v[24:27], v[162:165], v[202:205], v[24:27]
	v_lshl_add_u64 v[148:149], v[220:221], 0, s[4:5]
	s_mov_b32 m0, s48
	s_nop 0
	global_load_lds_dwordx4 v[148:149], off
	v_mfma_f32_16x16x32_bf16 v[16:19], v[144:147], v[210:213], v[16:19]
	v_mfma_f32_16x16x32_bf16 v[8:11], v[162:165], v[210:213], v[8:11]
	v_mfma_f32_16x16x32_bf16 v[60:63], v[158:161], v[190:193], v[60:63]
	v_mfma_f32_16x16x32_bf16 v[56:59], v[166:169], v[190:193], v[56:59]
	v_mfma_f32_16x16x32_bf16 v[48:51], v[158:161], v[198:201], v[48:51]
	v_mfma_f32_16x16x32_bf16 v[40:43], v[166:169], v[198:201], v[40:43]
	v_mfma_f32_16x16x32_bf16 v[28:31], v[158:161], v[206:209], v[28:31]
	v_mfma_f32_16x16x32_bf16 v[24:27], v[166:169], v[206:209], v[24:27]
	v_mfma_f32_16x16x32_bf16 v[16:19], v[158:161], v[214:217], v[16:19]
	v_mfma_f32_16x16x32_bf16 v[8:11], v[166:169], v[214:217], v[8:11]
	s_setprio 0
	s_setprio 1
	v_mfma_f32_16x16x32_bf16 v[52:55], v[170:173], v[186:189], v[52:55]
	v_mfma_f32_16x16x32_bf16 v[44:47], v[178:181], v[186:189], v[44:47]
	v_mfma_f32_16x16x32_bf16 v[36:39], v[170:173], v[194:197], v[36:39]
	v_mfma_f32_16x16x32_bf16 v[32:35], v[178:181], v[194:197], v[32:35]
	v_mfma_f32_16x16x32_bf16 v[20:23], v[170:173], v[202:205], v[20:23]
	v_mfma_f32_16x16x32_bf16 v[12:15], v[178:181], v[202:205], v[12:15]
	v_lshl_add_u64 v[148:149], v[222:223], 0, s[4:5]
	s_mov_b32 m0, s49
	s_nop 0
	global_load_lds_dwordx4 v[148:149], off
	v_mfma_f32_16x16x32_bf16 v[4:7], v[170:173], v[210:213], v[4:7]
	v_mfma_f32_16x16x32_bf16 v[0:3], v[178:181], v[210:213], v[0:3]
	v_mfma_f32_16x16x32_bf16 v[52:55], v[174:177], v[190:193], v[52:55]
	v_mfma_f32_16x16x32_bf16 v[44:47], v[182:185], v[190:193], v[44:47]
	v_mfma_f32_16x16x32_bf16 v[36:39], v[174:177], v[198:201], v[36:39]
	v_mfma_f32_16x16x32_bf16 v[32:35], v[182:185], v[198:201], v[32:35]
	v_mfma_f32_16x16x32_bf16 v[20:23], v[174:177], v[206:209], v[20:23]
	v_mfma_f32_16x16x32_bf16 v[12:15], v[182:185], v[206:209], v[12:15]
	v_mfma_f32_16x16x32_bf16 v[4:7], v[174:177], v[214:217], v[4:7]
	v_mfma_f32_16x16x32_bf16 v[0:3], v[182:185], v[214:217], v[0:3]
	s_setprio 0
	s_barrier
	s_add_i32 s72, s72, 2
	s_add_u32 s26, s26, 0x100
	s_addc_u32 s27, s27, 0
	s_add_u32 s70, s70, 0x100
	s_addc_u32 s71, s71, 0
	s_cmp_gt_u32 s72, 5
	s_cbranch_scc0 .LBB0_747
	v_lshl_add_u32 v146, s24, 8, v156
	v_lshl_or_b32 v144, s53, 8, v151
	v_ashrrev_i32_e32 v147, 31, v146
	v_ashrrev_i32_e32 v145, 31, v144
	v_lshlrev_b64 v[148:149], 10, v[146:147]
	v_lshl_add_u64 v[148:149], v[148:149], 0, v[144:145]
	v_lshlrev_b64 v[170:171], 1, v[148:149]
	v_lshl_add_u64 v[148:149], s[6:7], 0, v[170:171]
	v_or_b32_e32 v170, 0x100, v170
	v_lshl_add_u64 v[166:167], s[6:7], 0, v[170:171]
	v_or_b32_e32 v178, 16, v146
	global_load_dwordx4 v[158:161], v[148:149], off
	v_lshlrev_b64 v[162:163], 11, v[146:147]
	global_load_dwordx4 v[166:169], v[166:167], off
	v_lshl_add_u64 v[148:149], v[144:145], 1, s[0:1]
	v_ashrrev_i32_e32 v179, 31, v178
	v_lshl_add_u64 v[190:191], v[148:149], 0, v[162:163]
	v_lshlrev_b64 v[174:175], 10, v[178:179]
	global_load_dwordx4 v[162:165], v[190:191], off
	v_lshl_add_u64 v[170:171], s[0:1], 0, v[170:171]
	v_lshl_add_u64 v[174:175], v[174:175], 0, v[144:145]
	global_load_dwordx4 v[170:173], v[170:171], off
	v_lshlrev_b64 v[186:187], 1, v[174:175]
	v_lshlrev_b64 v[178:179], 11, v[178:179]
	v_lshl_add_u64 v[174:175], s[6:7], 0, v[186:187]
	v_lshl_add_u64 v[192:193], v[148:149], 0, v[178:179]
	global_load_dwordx4 v[174:177], v[174:175], off
	v_or_b32_e32 v186, 0x100, v186
	global_load_dwordx4 v[178:181], v[192:193], off
	v_lshl_add_u64 v[182:183], s[6:7], 0, v[186:187]
	v_lshl_add_u64 v[186:187], s[0:1], 0, v[186:187]
	global_load_dwordx4 v[182:185], v[182:183], off
	s_and_b64 vcc, exec, s[2:3]
	global_load_dwordx4 v[186:189], v[186:187], off
	s_mov_b32 s53, s12
	s_mov_b32 s24, s14
	s_mov_b64 s[36:37], s[22:23]
	s_mov_b64 s[26:27], s[20:21]
	s_waitcnt vmcnt(0)
; __device__ __forceinline__ u32x2 pack4(f32x4 v) { u32x2 w; w.x = cvt_pk_bf16(v[0], v[1]); w.y = cvt_pk_bf16(v[2], v[3]); return w; }
; __device__ __forceinline__ f32x4 unpack4(u32x2 w) { f32x4 v; v[0] = __uint_as_float(w.x << 16); v[1] = __uint_as_float(w.x & 0xffff0000u); v[2] = __uint_as_float(w.y << 16); v[3] = __uint_as_float(w.y & 0xffff0000u); return v; }
;     __device__ __forceinline__ void operator()(const f32x4 (&acc)[2][2][4][2], const Unit& u, int wr, int wc, int fr, int fq) const {
;     ...
;             for (int m = mh; m < mh + 2; ++m)
; #pragma unroll
;                 for (int bj = 0; bj < 2; ++bj)
; #pragma unroll
;                     for (int n = 0; n < 2; ++n) { const size_t off = (size_t)(row0 + ai * HALF + m * 16) * 1024 + col0 + bj * HALF + n * 4;
;                         f32x4 o = unpack4(pg[m][bj][n]) * acc[ai][bj][m][n]; if (ADD) o = o + unpack4(pm_[m][bj][n]);
;                         *(u32x2*)(Mg + off) = pack4(o); }
;             asm volatile("" ::: "memory");
	v_lshlrev_b32_e32 v194, 16, v158
	v_and_b32_e32 v195, 0xffff0000, v158
	v_lshlrev_b32_e32 v158, 16, v159
	v_and_b32_e32 v159, 0xffff0000, v159
	v_lshlrev_b32_e32 v198, 16, v160
	v_and_b32_e32 v199, 0xffff0000, v160
	v_lshlrev_b32_e32 v160, 16, v161
	v_lshlrev_b32_e32 v196, 16, v162
	v_and_b32_e32 v197, 0xffff0000, v162
	v_lshlrev_b32_e32 v162, 16, v163
	v_and_b32_e32 v163, 0xffff0000, v163
	v_and_b32_e32 v161, 0xffff0000, v161
	v_lshlrev_b32_e32 v200, 16, v164
	v_and_b32_e32 v201, 0xffff0000, v164
	v_lshlrev_b32_e32 v164, 16, v165
	v_and_b32_e32 v165, 0xffff0000, v165
	v_pk_fma_f32 v[126:127], v[126:127], v[158:159], v[162:163]
	v_pk_fma_f32 v[124:125], v[124:125], v[194:195], v[196:197]
	v_pk_fma_f32 v[158:159], v[122:123], v[160:161], v[164:165]
	v_lshlrev_b32_e32 v160, 16, v166
	v_and_b32_e32 v161, 0xffff0000, v166
	v_lshlrev_b32_e32 v162, 16, v167
	v_and_b32_e32 v163, 0xffff0000, v167
	v_lshlrev_b32_e32 v164, 16, v170
	v_and_b32_e32 v165, 0xffff0000, v170
	v_lshlrev_b32_e32 v166, 16, v171
	v_and_b32_e32 v167, 0xffff0000, v171
	v_lshlrev_b32_e32 v170, 16, v168
	v_and_b32_e32 v171, 0xffff0000, v168
	v_lshlrev_b32_e32 v168, 16, v169
	v_and_b32_e32 v169, 0xffff0000, v169
	v_lshlrev_b32_e32 v194, 16, v172
	v_and_b32_e32 v195, 0xffff0000, v172
	v_lshlrev_b32_e32 v172, 16, v173
	v_and_b32_e32 v173, 0xffff0000, v173
	v_pk_fma_f32 v[122:123], v[120:121], v[198:199], v[200:201]
	v_cvt_pk_bf16_f32 v120, v124, v125
	v_pk_fma_f32 v[114:115], v[114:115], v[162:163], v[166:167]
	v_pk_fma_f32 v[112:113], v[112:113], v[160:161], v[164:165]
	v_pk_fma_f32 v[124:125], v[110:111], v[168:169], v[172:173]
	v_pk_fma_f32 v[110:111], v[108:109], v[170:171], v[194:195]
	v_lshlrev_b32_e32 v196, 16, v174
	v_and_b32_e32 v197, 0xffff0000, v174
	v_lshlrev_b32_e32 v174, 16, v175
	v_and_b32_e32 v175, 0xffff0000, v175
	v_lshlrev_b32_e32 v198, 16, v178
	v_and_b32_e32 v199, 0xffff0000, v178
	v_lshlrev_b32_e32 v178, 16, v179
	v_cvt_pk_bf16_f32 v108, v112, v113
	v_cvt_pk_bf16_f32 v109, v114, v115
	v_cvt_pk_bf16_f32 v110, v110, v111
	v_cvt_pk_bf16_f32 v111, v124, v125
	v_and_b32_e32 v179, 0xffff0000, v179
	global_store_dwordx4 v[190:191], v[108:111], off offset:256
	v_lshlrev_b32_e32 v112, 16, v177
	v_and_b32_e32 v113, 0xffff0000, v177
	v_pk_fma_f32 v[110:111], v[118:119], v[174:175], v[178:179]
	v_pk_fma_f32 v[108:109], v[116:117], v[196:197], v[198:199]
	v_lshlrev_b32_e32 v114, 16, v180
	v_cvt_pk_bf16_f32 v108, v108, v109
	v_cvt_pk_bf16_f32 v109, v110, v111
	v_lshlrev_b32_e32 v110, 16, v176
	v_and_b32_e32 v111, 0xffff0000, v176
	v_and_b32_e32 v115, 0xffff0000, v180
	v_lshlrev_b32_e32 v116, 16, v181
	v_and_b32_e32 v117, 0xffff0000, v181
	v_pk_fma_f32 v[106:107], v[106:107], v[112:113], v[116:117]
	v_pk_fma_f32 v[104:105], v[104:105], v[110:111], v[114:115]
	v_cvt_pk_bf16_f32 v111, v106, v107
	v_cvt_pk_bf16_f32 v110, v104, v105
	global_store_dwordx4 v[192:193], v[108:111], off
	v_lshlrev_b32_e32 v104, 16, v182
	v_and_b32_e32 v105, 0xffff0000, v182
	v_lshlrev_b32_e32 v106, 16, v183
	v_and_b32_e32 v107, 0xffff0000, v183
	v_lshlrev_b32_e32 v108, 16, v186
	v_and_b32_e32 v109, 0xffff0000, v186
	v_lshlrev_b32_e32 v110, 16, v187
	v_and_b32_e32 v111, 0xffff0000, v187
	v_pk_fma_f32 v[102:103], v[102:103], v[106:107], v[110:111]
	v_pk_fma_f32 v[100:101], v[100:101], v[104:105], v[108:109]
	v_lshlrev_b32_e32 v104, 16, v185
	v_cvt_pk_bf16_f32 v100, v100, v101
	v_cvt_pk_bf16_f32 v101, v102, v103
	v_lshlrev_b32_e32 v102, 16, v184
	v_and_b32_e32 v103, 0xffff0000, v184
	v_and_b32_e32 v105, 0xffff0000, v185
	v_lshlrev_b32_e32 v106, 16, v188
	v_and_b32_e32 v107, 0xffff0000, v188
	v_lshlrev_b32_e32 v108, 16, v189
	v_and_b32_e32 v109, 0xffff0000, v189
	v_pk_fma_f32 v[98:99], v[98:99], v[104:105], v[108:109]
	v_pk_fma_f32 v[96:97], v[96:97], v[102:103], v[106:107]
	v_cvt_pk_bf16_f32 v103, v98, v99
	v_cvt_pk_bf16_f32 v102, v96, v97
	global_store_dwordx4 v[192:193], v[100:103], off offset:256
	v_cvt_pk_bf16_f32 v121, v126, v127
	v_cvt_pk_bf16_f32 v122, v122, v123
	v_or_b32_e32 v100, 32, v146
	v_ashrrev_i32_e32 v101, 31, v100
	v_lshlrev_b64 v[96:97], 10, v[100:101]
	v_cvt_pk_bf16_f32 v123, v158, v159
	v_lshl_add_u64 v[96:97], v[96:97], 0, v[144:145]
	global_store_dwordx4 v[190:191], v[120:123], off
	v_lshlrev_b64 v[108:109], 1, v[96:97]
	v_lshlrev_b64 v[100:101], 11, v[100:101]
	v_lshl_add_u64 v[96:97], s[6:7], 0, v[108:109]
	v_lshl_add_u64 v[158:159], v[148:149], 0, v[100:101]
	global_load_dwordx4 v[96:99], v[96:97], off
	v_or_b32_e32 v108, 0x100, v108
	global_load_dwordx4 v[100:103], v[158:159], off
	v_lshl_add_u64 v[104:105], s[6:7], 0, v[108:109]
	v_lshl_add_u64 v[108:109], s[0:1], 0, v[108:109]
	v_or_b32_e32 v116, 48, v146
	global_load_dwordx4 v[104:107], v[104:105], off
	v_ashrrev_i32_e32 v117, 31, v116
	global_load_dwordx4 v[108:111], v[108:109], off
	v_lshlrev_b64 v[112:113], 10, v[116:117]
	v_lshl_add_u64 v[112:113], v[112:113], 0, v[144:145]
	v_lshlrev_b64 v[124:125], 1, v[112:113]
	v_lshlrev_b64 v[116:117], 11, v[116:117]
	v_lshl_add_u64 v[112:113], s[6:7], 0, v[124:125]
	v_lshl_add_u64 v[160:161], v[148:149], 0, v[116:117]
	global_load_dwordx4 v[112:115], v[112:113], off
	v_or_b32_e32 v124, 0x100, v124
	global_load_dwordx4 v[116:119], v[160:161], off
	v_lshl_add_u64 v[120:121], s[6:7], 0, v[124:125]
	v_lshl_add_u64 v[124:125], s[0:1], 0, v[124:125]
	global_load_dwordx4 v[120:123], v[120:121], off
	s_waitcnt vmcnt(6)
	v_lshlrev_b32_e32 v162, 16, v96
	global_load_dwordx4 v[124:127], v[124:125], off
	v_and_b32_e32 v163, 0xffff0000, v96
	v_lshlrev_b32_e32 v96, 16, v97
	v_and_b32_e32 v97, 0xffff0000, v97
	s_waitcnt vmcnt(6)
; __device__ __forceinline__ u32x2 pack4(f32x4 v) { u32x2 w; w.x = cvt_pk_bf16(v[0], v[1]); w.y = cvt_pk_bf16(v[2], v[3]); return w; }
; __device__ __forceinline__ f32x4 unpack4(u32x2 w) { f32x4 v; v[0] = __uint_as_float(w.x << 16); v[1] = __uint_as_float(w.x & 0xffff0000u); v[2] = __uint_as_float(w.y << 16); v[3] = __uint_as_float(w.y & 0xffff0000u); return v; }
;     __device__ __forceinline__ void operator()(const f32x4 (&acc)[2][2][4][2], const Unit& u, int wr, int wc, int fr, int fq) const {
;     ...
;             for (int m = mh; m < mh + 2; ++m)
; #pragma unroll
;                 for (int bj = 0; bj < 2; ++bj)
; #pragma unroll
;                     for (int n = 0; n < 2; ++n) { const size_t off = (size_t)(row0 + ai * HALF + m * 16) * 1024 + col0 + bj * HALF + n * 4;
;                         pg[m][bj][n] = *(const u32x2*)(G + off); if (ADD) pm_[m][bj][n] = *(const u32x2*)(Mg + off); }
;             asm volatile("" ::: "memory");
; #pragma unroll
;             for (int m = mh; m < mh + 2; ++m)
; #pragma unroll
;                 for (int bj = 0; bj < 2; ++bj)
; #pragma unroll
;                     for (int n = 0; n < 2; ++n) { const size_t off = (size_t)(row0 + ai * HALF + m * 16) * 1024 + col0 + bj * HALF + n * 4;
;                         f32x4 o = unpack4(pg[m][bj][n]) * acc[ai][bj][m][n]; if (ADD) o = o + unpack4(pm_[m][bj][n]);
;                         *(u32x2*)(Mg + off) = pack4(o); }
;             asm volatile("" ::: "memory");
	v_lshlrev_b32_e32 v164, 16, v100
	v_and_b32_e32 v165, 0xffff0000, v100
	v_lshlrev_b32_e32 v100, 16, v101
	v_and_b32_e32 v101, 0xffff0000, v101
	v_pk_fma_f32 v[94:95], v[94:95], v[96:97], v[100:101]
	v_pk_fma_f32 v[92:93], v[92:93], v[162:163], v[164:165]
	v_lshlrev_b32_e32 v96, 16, v99
	v_cvt_pk_bf16_f32 v92, v92, v93
	v_cvt_pk_bf16_f32 v93, v94, v95
	v_lshlrev_b32_e32 v94, 16, v98
	v_and_b32_e32 v95, 0xffff0000, v98
	v_and_b32_e32 v97, 0xffff0000, v99
	v_lshlrev_b32_e32 v98, 16, v102
	v_and_b32_e32 v99, 0xffff0000, v102
	v_lshlrev_b32_e32 v100, 16, v103
	v_and_b32_e32 v101, 0xffff0000, v103
	v_pk_fma_f32 v[90:91], v[90:91], v[96:97], v[100:101]
	v_pk_fma_f32 v[88:89], v[88:89], v[94:95], v[98:99]
	v_cvt_pk_bf16_f32 v95, v90, v91
	v_cvt_pk_bf16_f32 v94, v88, v89
	global_store_dwordx4 v[158:159], v[92:95], off
	s_waitcnt vmcnt(6)
	v_lshlrev_b32_e32 v88, 16, v104
	v_and_b32_e32 v89, 0xffff0000, v104
	v_lshlrev_b32_e32 v90, 16, v105
	v_and_b32_e32 v91, 0xffff0000, v105
	s_waitcnt vmcnt(5)
	v_lshlrev_b32_e32 v92, 16, v108
	v_and_b32_e32 v93, 0xffff0000, v108
	v_lshlrev_b32_e32 v94, 16, v109
	v_and_b32_e32 v95, 0xffff0000, v109
	v_pk_fma_f32 v[86:87], v[86:87], v[90:91], v[94:95]
	v_pk_fma_f32 v[84:85], v[84:85], v[88:89], v[92:93]
	v_lshlrev_b32_e32 v88, 16, v107
	v_cvt_pk_bf16_f32 v84, v84, v85
	v_cvt_pk_bf16_f32 v85, v86, v87
	v_lshlrev_b32_e32 v86, 16, v106
	v_and_b32_e32 v87, 0xffff0000, v106
	v_and_b32_e32 v89, 0xffff0000, v107
	v_lshlrev_b32_e32 v90, 16, v110
	v_and_b32_e32 v91, 0xffff0000, v110
	v_lshlrev_b32_e32 v92, 16, v111
	v_and_b32_e32 v93, 0xffff0000, v111
	v_pk_fma_f32 v[78:79], v[78:79], v[88:89], v[92:93]
	v_pk_fma_f32 v[76:77], v[76:77], v[86:87], v[90:91]
	v_cvt_pk_bf16_f32 v87, v78, v79
	v_cvt_pk_bf16_f32 v86, v76, v77
	global_store_dwordx4 v[158:159], v[84:87], off offset:256
	s_waitcnt vmcnt(5)
	v_lshlrev_b32_e32 v76, 16, v112
	v_and_b32_e32 v77, 0xffff0000, v112
	v_lshlrev_b32_e32 v78, 16, v113
	v_and_b32_e32 v79, 0xffff0000, v113
	s_waitcnt vmcnt(4)
	v_lshlrev_b32_e32 v84, 16, v116
	v_and_b32_e32 v85, 0xffff0000, v116
	v_lshlrev_b32_e32 v86, 16, v117
	v_and_b32_e32 v87, 0xffff0000, v117
	v_pk_fma_f32 v[78:79], v[82:83], v[78:79], v[86:87]
	v_pk_fma_f32 v[76:77], v[80:81], v[76:77], v[84:85]
	v_lshlrev_b32_e32 v80, 16, v115
	v_cvt_pk_bf16_f32 v76, v76, v77
	v_cvt_pk_bf16_f32 v77, v78, v79
	v_lshlrev_b32_e32 v78, 16, v114
	v_and_b32_e32 v79, 0xffff0000, v114
	v_and_b32_e32 v81, 0xffff0000, v115
	v_lshlrev_b32_e32 v82, 16, v118
	v_and_b32_e32 v83, 0xffff0000, v118
	v_lshlrev_b32_e32 v84, 16, v119
	v_and_b32_e32 v85, 0xffff0000, v119
	v_pk_fma_f32 v[74:75], v[74:75], v[80:81], v[84:85]
	v_pk_fma_f32 v[72:73], v[72:73], v[78:79], v[82:83]
	v_cvt_pk_bf16_f32 v79, v74, v75
	v_cvt_pk_bf16_f32 v78, v72, v73
	global_store_dwordx4 v[160:161], v[76:79], off
	s_waitcnt vmcnt(4)
	v_lshlrev_b32_e32 v72, 16, v120
	v_and_b32_e32 v73, 0xffff0000, v120
	v_lshlrev_b32_e32 v74, 16, v121
	v_and_b32_e32 v75, 0xffff0000, v121
	s_waitcnt vmcnt(3)
	v_lshlrev_b32_e32 v76, 16, v124
	v_and_b32_e32 v77, 0xffff0000, v124
	v_lshlrev_b32_e32 v78, 16, v125
	v_and_b32_e32 v79, 0xffff0000, v125
	v_pk_fma_f32 v[70:71], v[70:71], v[74:75], v[78:79]
	v_pk_fma_f32 v[68:69], v[68:69], v[72:73], v[76:77]
	v_lshlrev_b32_e32 v72, 16, v123
	v_cvt_pk_bf16_f32 v68, v68, v69
	v_cvt_pk_bf16_f32 v69, v70, v71
	v_lshlrev_b32_e32 v70, 16, v122
	v_and_b32_e32 v71, 0xffff0000, v122
	v_and_b32_e32 v73, 0xffff0000, v123
	v_lshlrev_b32_e32 v74, 16, v126
	v_and_b32_e32 v75, 0xffff0000, v126
	v_lshlrev_b32_e32 v76, 16, v127
	v_and_b32_e32 v77, 0xffff0000, v127
	v_pk_fma_f32 v[66:67], v[66:67], v[72:73], v[76:77]
	v_pk_fma_f32 v[64:65], v[64:65], v[70:71], v[74:75]
	v_cvt_pk_bf16_f32 v71, v66, v67
	v_cvt_pk_bf16_f32 v70, v64, v65
	global_store_dwordx4 v[160:161], v[68:71], off offset:256
	v_add_u32_e32 v84, 0x90, v146
	v_ashrrev_i32_e32 v85, 31, v84
	v_add_u32_e32 v68, 0x80, v146
	v_ashrrev_i32_e32 v69, 31, v68
	v_lshlrev_b64 v[64:65], 10, v[68:69]
	v_lshl_add_u64 v[64:65], v[64:65], 0, v[144:145]
	v_lshlrev_b64 v[76:77], 1, v[64:65]
	v_lshlrev_b64 v[68:69], 11, v[68:69]
	v_lshl_add_u64 v[64:65], s[6:7], 0, v[76:77]
	v_lshl_add_u64 v[96:97], v[148:149], 0, v[68:69]
	global_load_dwordx4 v[64:67], v[64:65], off
	v_or_b32_e32 v76, 0x100, v76
	global_load_dwordx4 v[68:71], v[96:97], off
	v_lshl_add_u64 v[72:73], s[6:7], 0, v[76:77]
	v_lshl_add_u64 v[76:77], s[0:1], 0, v[76:77]
	global_load_dwordx4 v[72:75], v[72:73], off
	v_lshlrev_b64 v[80:81], 10, v[84:85]
	global_load_dwordx4 v[76:79], v[76:77], off
	v_lshl_add_u64 v[80:81], v[80:81], 0, v[144:145]
	v_lshlrev_b64 v[92:93], 1, v[80:81]
	v_lshlrev_b64 v[84:85], 11, v[84:85]
	v_lshl_add_u64 v[80:81], s[6:7], 0, v[92:93]
	v_lshl_add_u64 v[98:99], v[148:149], 0, v[84:85]
	global_load_dwordx4 v[80:83], v[80:81], off
	v_or_b32_e32 v92, 0x100, v92
	global_load_dwordx4 v[84:87], v[98:99], off
	v_lshl_add_u64 v[88:89], s[6:7], 0, v[92:93]
	v_lshl_add_u64 v[92:93], s[0:1], 0, v[92:93]
	global_load_dwordx4 v[88:91], v[88:89], off
	s_waitcnt vmcnt(6)
	v_lshlrev_b32_e32 v100, 16, v64
	global_load_dwordx4 v[92:95], v[92:93], off
	v_and_b32_e32 v101, 0xffff0000, v64
	v_lshlrev_b32_e32 v64, 16, v65
	v_and_b32_e32 v65, 0xffff0000, v65
	s_waitcnt vmcnt(6)
; __device__ __forceinline__ u32x2 pack4(f32x4 v) { u32x2 w; w.x = cvt_pk_bf16(v[0], v[1]); w.y = cvt_pk_bf16(v[2], v[3]); return w; }
; __device__ __forceinline__ f32x4 unpack4(u32x2 w) { f32x4 v; v[0] = __uint_as_float(w.x << 16); v[1] = __uint_as_float(w.x & 0xffff0000u); v[2] = __uint_as_float(w.y << 16); v[3] = __uint_as_float(w.y & 0xffff0000u); return v; }
;     __device__ __forceinline__ void operator()(const f32x4 (&acc)[2][2][4][2], const Unit& u, int wr, int wc, int fr, int fq) const {
;     ...
;             for (int m = mh; m < mh + 2; ++m)
; #pragma unroll
;                 for (int bj = 0; bj < 2; ++bj)
; #pragma unroll
;                     for (int n = 0; n < 2; ++n) { const size_t off = (size_t)(row0 + ai * HALF + m * 16) * 1024 + col0 + bj * HALF + n * 4;
;                         pg[m][bj][n] = *(const u32x2*)(G + off); if (ADD) pm_[m][bj][n] = *(const u32x2*)(Mg + off); }
;             asm volatile("" ::: "memory");
; #pragma unroll
;             for (int m = mh; m < mh + 2; ++m)
; #pragma unroll
;                 for (int bj = 0; bj < 2; ++bj)
; #pragma unroll
;                     for (int n = 0; n < 2; ++n) { const size_t off = (size_t)(row0 + ai * HALF + m * 16) * 1024 + col0 + bj * HALF + n * 4;
;                         f32x4 o = unpack4(pg[m][bj][n]) * acc[ai][bj][m][n]; if (ADD) o = o + unpack4(pm_[m][bj][n]);
;                         *(u32x2*)(Mg + off) = pack4(o); }
;             asm volatile("" ::: "memory");
	v_lshlrev_b32_e32 v102, 16, v68
	v_and_b32_e32 v103, 0xffff0000, v68
	v_lshlrev_b32_e32 v68, 16, v69
	v_and_b32_e32 v69, 0xffff0000, v69
	v_pk_fma_f32 v[62:63], v[62:63], v[64:65], v[68:69]
	v_pk_fma_f32 v[60:61], v[60:61], v[100:101], v[102:103]
	v_lshlrev_b32_e32 v64, 16, v67
	v_cvt_pk_bf16_f32 v60, v60, v61
	v_cvt_pk_bf16_f32 v61, v62, v63
	v_lshlrev_b32_e32 v62, 16, v66
	v_and_b32_e32 v63, 0xffff0000, v66
	v_and_b32_e32 v65, 0xffff0000, v67
	v_lshlrev_b32_e32 v66, 16, v70
	v_and_b32_e32 v67, 0xffff0000, v70
	v_lshlrev_b32_e32 v68, 16, v71
	v_and_b32_e32 v69, 0xffff0000, v71
	v_pk_fma_f32 v[58:59], v[58:59], v[64:65], v[68:69]
	v_pk_fma_f32 v[56:57], v[56:57], v[62:63], v[66:67]
	v_cvt_pk_bf16_f32 v63, v58, v59
	v_cvt_pk_bf16_f32 v62, v56, v57
	global_store_dwordx4 v[96:97], v[60:63], off
	s_waitcnt vmcnt(6)
	v_lshlrev_b32_e32 v56, 16, v72
	v_and_b32_e32 v57, 0xffff0000, v72
	v_lshlrev_b32_e32 v58, 16, v73
	v_and_b32_e32 v59, 0xffff0000, v73
	s_waitcnt vmcnt(5)
	v_lshlrev_b32_e32 v60, 16, v76
	v_and_b32_e32 v61, 0xffff0000, v76
	v_lshlrev_b32_e32 v62, 16, v77
	v_and_b32_e32 v63, 0xffff0000, v77
	v_pk_fma_f32 v[54:55], v[54:55], v[58:59], v[62:63]
	v_pk_fma_f32 v[52:53], v[52:53], v[56:57], v[60:61]
	v_lshlrev_b32_e32 v56, 16, v75
	v_cvt_pk_bf16_f32 v52, v52, v53
	v_cvt_pk_bf16_f32 v53, v54, v55
	v_lshlrev_b32_e32 v54, 16, v74
	v_and_b32_e32 v55, 0xffff0000, v74
	v_and_b32_e32 v57, 0xffff0000, v75
	v_lshlrev_b32_e32 v58, 16, v78
	v_and_b32_e32 v59, 0xffff0000, v78
	v_lshlrev_b32_e32 v60, 16, v79
	v_and_b32_e32 v61, 0xffff0000, v79
	v_pk_fma_f32 v[46:47], v[46:47], v[56:57], v[60:61]
	v_pk_fma_f32 v[44:45], v[44:45], v[54:55], v[58:59]
	v_cvt_pk_bf16_f32 v55, v46, v47
	v_cvt_pk_bf16_f32 v54, v44, v45
	global_store_dwordx4 v[96:97], v[52:55], off offset:256
	s_waitcnt vmcnt(5)
	v_lshlrev_b32_e32 v44, 16, v80
	v_and_b32_e32 v45, 0xffff0000, v80
	v_lshlrev_b32_e32 v46, 16, v81
	v_and_b32_e32 v47, 0xffff0000, v81
	s_waitcnt vmcnt(4)
	v_lshlrev_b32_e32 v52, 16, v84
	v_and_b32_e32 v53, 0xffff0000, v84
	v_lshlrev_b32_e32 v54, 16, v85
	v_and_b32_e32 v55, 0xffff0000, v85
	v_pk_fma_f32 v[46:47], v[50:51], v[46:47], v[54:55]
	v_pk_fma_f32 v[44:45], v[48:49], v[44:45], v[52:53]
	v_lshlrev_b32_e32 v48, 16, v83
	v_cvt_pk_bf16_f32 v44, v44, v45
	v_cvt_pk_bf16_f32 v45, v46, v47
	v_lshlrev_b32_e32 v46, 16, v82
	v_and_b32_e32 v47, 0xffff0000, v82
	v_and_b32_e32 v49, 0xffff0000, v83
	v_lshlrev_b32_e32 v50, 16, v86
	v_and_b32_e32 v51, 0xffff0000, v86
	v_lshlrev_b32_e32 v52, 16, v87
	v_and_b32_e32 v53, 0xffff0000, v87
	v_pk_fma_f32 v[42:43], v[42:43], v[48:49], v[52:53]
	v_pk_fma_f32 v[40:41], v[40:41], v[46:47], v[50:51]
	v_cvt_pk_bf16_f32 v47, v42, v43
	v_cvt_pk_bf16_f32 v46, v40, v41
	global_store_dwordx4 v[98:99], v[44:47], off
	s_waitcnt vmcnt(4)
	v_lshlrev_b32_e32 v40, 16, v88
	v_and_b32_e32 v41, 0xffff0000, v88
	v_lshlrev_b32_e32 v42, 16, v89
	v_and_b32_e32 v43, 0xffff0000, v89
	s_waitcnt vmcnt(3)
	v_lshlrev_b32_e32 v44, 16, v92
	v_and_b32_e32 v45, 0xffff0000, v92
	v_lshlrev_b32_e32 v46, 16, v93
	v_and_b32_e32 v47, 0xffff0000, v93
	v_pk_fma_f32 v[38:39], v[38:39], v[42:43], v[46:47]
	v_pk_fma_f32 v[36:37], v[36:37], v[40:41], v[44:45]
	v_lshlrev_b32_e32 v40, 16, v91
	v_cvt_pk_bf16_f32 v36, v36, v37
	v_cvt_pk_bf16_f32 v37, v38, v39
	v_lshlrev_b32_e32 v38, 16, v90
	v_and_b32_e32 v39, 0xffff0000, v90
	v_and_b32_e32 v41, 0xffff0000, v91
	v_lshlrev_b32_e32 v42, 16, v94
	v_and_b32_e32 v43, 0xffff0000, v94
	v_lshlrev_b32_e32 v44, 16, v95
	v_and_b32_e32 v45, 0xffff0000, v95
	v_pk_fma_f32 v[34:35], v[34:35], v[40:41], v[44:45]
	v_pk_fma_f32 v[32:33], v[32:33], v[38:39], v[42:43]
	v_cvt_pk_bf16_f32 v39, v34, v35
	v_cvt_pk_bf16_f32 v38, v32, v33
	global_store_dwordx4 v[98:99], v[36:39], off offset:256
	v_add_u32_e32 v52, 0xb0, v146
	v_ashrrev_i32_e32 v53, 31, v52
	v_add_u32_e32 v36, 0xa0, v146
	v_ashrrev_i32_e32 v37, 31, v36
	v_lshlrev_b64 v[32:33], 10, v[36:37]
	v_lshl_add_u64 v[32:33], v[32:33], 0, v[144:145]
	v_lshlrev_b64 v[44:45], 1, v[32:33]
	v_lshlrev_b64 v[36:37], 11, v[36:37]
	v_lshl_add_u64 v[32:33], s[6:7], 0, v[44:45]
	v_lshl_add_u64 v[64:65], v[148:149], 0, v[36:37]
	global_load_dwordx4 v[32:35], v[32:33], off
	v_or_b32_e32 v44, 0x100, v44
	global_load_dwordx4 v[36:39], v[64:65], off
	v_lshl_add_u64 v[40:41], s[6:7], 0, v[44:45]
	v_lshl_add_u64 v[44:45], s[0:1], 0, v[44:45]
	global_load_dwordx4 v[40:43], v[40:41], off
	v_lshlrev_b64 v[48:49], 10, v[52:53]
	global_load_dwordx4 v[44:47], v[44:45], off
	v_lshl_add_u64 v[48:49], v[48:49], 0, v[144:145]
	v_lshlrev_b64 v[60:61], 1, v[48:49]
	v_lshlrev_b64 v[52:53], 11, v[52:53]
	v_lshl_add_u64 v[48:49], s[6:7], 0, v[60:61]
	v_lshl_add_u64 v[66:67], v[148:149], 0, v[52:53]
	global_load_dwordx4 v[48:51], v[48:49], off
	v_or_b32_e32 v60, 0x100, v60
	global_load_dwordx4 v[52:55], v[66:67], off
	v_lshl_add_u64 v[56:57], s[6:7], 0, v[60:61]
	v_lshl_add_u64 v[60:61], s[0:1], 0, v[60:61]
	global_load_dwordx4 v[56:59], v[56:57], off
	s_waitcnt vmcnt(6)
; __device__ __forceinline__ u32x2 pack4(f32x4 v) { u32x2 w; w.x = cvt_pk_bf16(v[0], v[1]); w.y = cvt_pk_bf16(v[2], v[3]); return w; }
; __device__ __forceinline__ f32x4 unpack4(u32x2 w) { f32x4 v; v[0] = __uint_as_float(w.x << 16); v[1] = __uint_as_float(w.x & 0xffff0000u); v[2] = __uint_as_float(w.y << 16); v[3] = __uint_as_float(w.y & 0xffff0000u); return v; }
; #define PG8_WAIT_V(n) asm volatile("s_waitcnt vmcnt(" #n ")" ::: "memory")
; #define PG8_BAR __builtin_amdgcn_s_barrier()
;     __device__ __forceinline__ void operator()(const f32x4 (&acc)[2][2][4][2], const Unit& u, int wr, int wc, int fr, int fq) const {
;     ...
;             for (int m = mh; m < mh + 2; ++m)
; #pragma unroll
;                 for (int bj = 0; bj < 2; ++bj)
; #pragma unroll
;                     for (int n = 0; n < 2; ++n) { const size_t off = (size_t)(row0 + ai * HALF + m * 16) * 1024 + col0 + bj * HALF + n * 4;
;                         f32x4 o = unpack4(pg[m][bj][n]) * acc[ai][bj][m][n]; if (ADD) o = o + unpack4(pm_[m][bj][n]);
;                         *(u32x2*)(Mg + off) = pack4(o); }
;             asm volatile("" ::: "memory");
; template <class Epi, class Sched, bool ALIGN_EPI = false, bool SP2 = false>
; __device__ __forceinline__ void gemm_phase(PG8_LAS unsigned char* lds, const Gemm g, const Sched& S, const Epi& E) {
;     ...
;         if (!has_next) break;
; #pragma unroll
;         for (int a = 0; a < 2; ++a)
; #pragma unroll
;             for (int b = 0; b < 2; ++b)
; #pragma unroll
;                 for (int m = 0; m < 4; ++m)
; #pragma unroll
;                     for (int n = 0; n < 2; ++n) acc[a][b][m][n] = (f32x4){0.f, 0.f, 0.f, 0.f};
;         cur = nxt; cA = nA; cB = nB; ++ui;
;         if constexpr (ALIGN_EPI) { if (wr == 1) PG8_BAR; }
;     }
;     PG8_WAIT_V(0);
;     if constexpr (!ALIGN_EPI) { if (wr == 0) PG8_BAR; }
;     PG8_BAR;
	v_lshlrev_b32_e32 v68, 16, v32
	global_load_dwordx4 v[60:63], v[60:61], off
	v_and_b32_e32 v69, 0xffff0000, v32
	v_lshlrev_b32_e32 v32, 16, v33
	v_and_b32_e32 v33, 0xffff0000, v33
	s_waitcnt vmcnt(6)
	v_lshlrev_b32_e32 v70, 16, v36
	v_and_b32_e32 v71, 0xffff0000, v36
	v_lshlrev_b32_e32 v36, 16, v37
	v_and_b32_e32 v37, 0xffff0000, v37
	v_pk_fma_f32 v[30:31], v[30:31], v[32:33], v[36:37]
	v_pk_fma_f32 v[28:29], v[28:29], v[68:69], v[70:71]
	v_lshlrev_b32_e32 v32, 16, v35
	v_cvt_pk_bf16_f32 v28, v28, v29
	v_cvt_pk_bf16_f32 v29, v30, v31
	v_lshlrev_b32_e32 v30, 16, v34
	v_and_b32_e32 v31, 0xffff0000, v34
	v_and_b32_e32 v33, 0xffff0000, v35
	v_lshlrev_b32_e32 v34, 16, v38
	v_and_b32_e32 v35, 0xffff0000, v38
	v_lshlrev_b32_e32 v36, 16, v39
	v_and_b32_e32 v37, 0xffff0000, v39
	v_pk_fma_f32 v[26:27], v[26:27], v[32:33], v[36:37]
	v_pk_fma_f32 v[24:25], v[24:25], v[30:31], v[34:35]
	v_cvt_pk_bf16_f32 v31, v26, v27
	v_cvt_pk_bf16_f32 v30, v24, v25
	global_store_dwordx4 v[64:65], v[28:31], off
	s_waitcnt vmcnt(6)
	v_lshlrev_b32_e32 v24, 16, v40
	v_and_b32_e32 v25, 0xffff0000, v40
	v_lshlrev_b32_e32 v26, 16, v41
	v_and_b32_e32 v27, 0xffff0000, v41
	s_waitcnt vmcnt(5)
	v_lshlrev_b32_e32 v28, 16, v44
	v_and_b32_e32 v29, 0xffff0000, v44
	v_lshlrev_b32_e32 v30, 16, v45
	v_and_b32_e32 v31, 0xffff0000, v45
	v_pk_fma_f32 v[22:23], v[22:23], v[26:27], v[30:31]
	v_pk_fma_f32 v[20:21], v[20:21], v[24:25], v[28:29]
	v_lshlrev_b32_e32 v24, 16, v43
	v_cvt_pk_bf16_f32 v20, v20, v21
	v_cvt_pk_bf16_f32 v21, v22, v23
	v_lshlrev_b32_e32 v22, 16, v42
	v_and_b32_e32 v23, 0xffff0000, v42
	v_and_b32_e32 v25, 0xffff0000, v43
	v_lshlrev_b32_e32 v26, 16, v46
	v_and_b32_e32 v27, 0xffff0000, v46
	v_lshlrev_b32_e32 v28, 16, v47
	v_and_b32_e32 v29, 0xffff0000, v47
	v_pk_fma_f32 v[14:15], v[14:15], v[24:25], v[28:29]
	v_pk_fma_f32 v[12:13], v[12:13], v[22:23], v[26:27]
	v_cvt_pk_bf16_f32 v23, v14, v15
	v_cvt_pk_bf16_f32 v22, v12, v13
	global_store_dwordx4 v[64:65], v[20:23], off offset:256
	s_waitcnt vmcnt(5)
	v_lshlrev_b32_e32 v12, 16, v48
	v_and_b32_e32 v13, 0xffff0000, v48
	v_lshlrev_b32_e32 v14, 16, v49
	v_and_b32_e32 v15, 0xffff0000, v49
	s_waitcnt vmcnt(4)
	v_lshlrev_b32_e32 v20, 16, v52
	v_and_b32_e32 v21, 0xffff0000, v52
	v_lshlrev_b32_e32 v22, 16, v53
	v_and_b32_e32 v23, 0xffff0000, v53
	v_pk_fma_f32 v[14:15], v[18:19], v[14:15], v[22:23]
	v_pk_fma_f32 v[12:13], v[16:17], v[12:13], v[20:21]
	v_lshlrev_b32_e32 v16, 16, v51
	v_cvt_pk_bf16_f32 v12, v12, v13
	v_cvt_pk_bf16_f32 v13, v14, v15
	v_lshlrev_b32_e32 v14, 16, v50
	v_and_b32_e32 v15, 0xffff0000, v50
	v_and_b32_e32 v17, 0xffff0000, v51
	v_lshlrev_b32_e32 v18, 16, v54
	v_and_b32_e32 v19, 0xffff0000, v54
	v_lshlrev_b32_e32 v20, 16, v55
	v_and_b32_e32 v21, 0xffff0000, v55
	v_pk_fma_f32 v[10:11], v[10:11], v[16:17], v[20:21]
	v_pk_fma_f32 v[8:9], v[8:9], v[14:15], v[18:19]
	v_cvt_pk_bf16_f32 v15, v10, v11
	v_cvt_pk_bf16_f32 v14, v8, v9
	global_store_dwordx4 v[66:67], v[12:15], off
	s_waitcnt vmcnt(4)
	v_lshlrev_b32_e32 v8, 16, v56
	v_and_b32_e32 v9, 0xffff0000, v56
	v_lshlrev_b32_e32 v10, 16, v57
	v_and_b32_e32 v11, 0xffff0000, v57
	s_waitcnt vmcnt(3)
	v_lshlrev_b32_e32 v12, 16, v60
	v_and_b32_e32 v13, 0xffff0000, v60
	v_lshlrev_b32_e32 v14, 16, v61
	v_and_b32_e32 v15, 0xffff0000, v61
	v_pk_fma_f32 v[6:7], v[6:7], v[10:11], v[14:15]
	v_pk_fma_f32 v[4:5], v[4:5], v[8:9], v[12:13]
	v_lshlrev_b32_e32 v8, 16, v59
	v_cvt_pk_bf16_f32 v4, v4, v5
	v_cvt_pk_bf16_f32 v5, v6, v7
	v_lshlrev_b32_e32 v6, 16, v58
	v_and_b32_e32 v7, 0xffff0000, v58
	v_and_b32_e32 v9, 0xffff0000, v59
	v_lshlrev_b32_e32 v10, 16, v62
	v_and_b32_e32 v11, 0xffff0000, v62
	v_lshlrev_b32_e32 v12, 16, v63
	v_and_b32_e32 v13, 0xffff0000, v63
	v_pk_fma_f32 v[2:3], v[2:3], v[8:9], v[12:13]
	v_pk_fma_f32 v[0:1], v[0:1], v[6:7], v[10:11]
	v_cvt_pk_bf16_f32 v7, v2, v3
	v_cvt_pk_bf16_f32 v6, v0, v1
	global_store_dwordx4 v[66:67], v[4:7], off offset:256
	s_cbranch_vccz .LBB0_744
	s_waitcnt vmcnt(0)
	s_cmpk_gt_u32 s40, 0xff
	s_cbranch_scc1 .LBB0_751
	s_barrier

; #define PG8_STAGE(bufoff, gbase, voff) do { _Pragma("unroll") for (int _i = 0; _i < 2; ++_i) \
;         __builtin_amdgcn_global_load_lds((const unsigned*)((const char*)(gbase) + (voff)[_i]), (PG8_LAS unsigned*)(lds + (bufoff) + ldsw + _i * 8192), 16, 0, 0); } while (0)
; #define PG8_LDA(dst, b, h) do { _Pragma("unroll") for (int m = 0; m < 4; ++m) _Pragma("unroll") for (int k = 0; k < 2; ++k) dst[m][k] = *(const PG8_LAS bf16x8*)(lds + PG8_SA(b, h) + aoff + m * 2048 + k * 1024); } while (0)
; #define PG8_LDB(dst, b, h) do { _Pragma("unroll") for (int n = 0; n < 2; ++n) _Pragma("unroll") for (int k = 0; k < 2; ++k) dst[n][k] = *(const PG8_LAS bf16x8*)(lds + PG8_SB(b, h) + boff + n * 2048 + k * 1024); } while (0)
; #define PG8_MMA(ai, bj, At, Bt) do { __builtin_amdgcn_s_setprio(1); _Pragma("unroll") for (int m = 0; m < 4; ++m) _Pragma("unroll") for (int n = 0; n < 2; ++n) _Pragma("unroll") for (int k = 0; k < 2; ++k) \
;         acc[ai][bj][m][n] = __builtin_amdgcn_mfma_f32_16x16x32_bf16(Bt[n][k], At[m][k], acc[ai][bj][m][n], 0, 0, 0); __builtin_amdgcn_s_setprio(0); } while (0)
; #define PG8_WAIT_V(n) asm volatile("s_waitcnt vmcnt(" #n ")" ::: "memory")
; #define PG8_WAIT_L(n) asm volatile("s_waitcnt lgkmcnt(" #n ")" ::: "memory")
; #define PG8_BAR __builtin_amdgcn_s_barrier()
; #define PG8_SCHED __builtin_amdgcn_sched_barrier(0)
; template <class Epi, class Sched, bool ALIGN_EPI = false, bool SP2 = false>
; __device__ __forceinline__ void gemm_phase(PG8_LAS unsigned char* lds, const Gemm g, const Sched& S, const Epi& E) {
;     ...
;             PG8_LDB(B0, 0, 0); PG8_LDB(B1, 0, 1); PG8_SCHED; PG8_LDA(At, 0, 0); PG8_STAGE(PG8_SA(1, 1), a1 + hstep, voffA);
;             PG8_WAIT_V(8); PG8_WAIT_L(0); PG8_BAR; PG8_MMA(0, 0, At, B0); PG8_MMA(0, 1, At, B1); PG8_BAR; PG8_SCHED;
;             PG8_LDA(At, 0, 1); PG8_STAGE(PG8_SB(0, 0), b2, voffB); PG8_STAGE(PG8_SB(0, 1), b2 + hstep, voffB); PG8_STAGE(PG8_SA(0, 0), a2, voffA);
;             PG8_WAIT_V(8); PG8_WAIT_L(0); PG8_BAR; PG8_MMA(1, 0, At, B0); PG8_MMA(1, 1, At, B1); PG8_BAR; PG8_SCHED;
.LBB0_813:
	ds_read_b128 v[128:131], v173
	ds_read_b128 v[132:135], v173 offset:1024
	ds_read_b128 v[136:139], v173 offset:2048
	ds_read_b128 v[140:143], v173 offset:3072
	ds_read_b128 v[160:163], v174
	ds_read_b128 v[164:167], v174 offset:1024
	ds_read_b128 v[178:181], v174 offset:2048
	ds_read_b128 v[182:185], v174 offset:3072
	s_add_u32 s26, s24, 0xfffc0080
	s_addc_u32 s27, s25, -1
	s_cmp_eq_u32 s70, 12
	s_cselect_b32 s37, s15, s27
	s_cselect_b32 s36, s60, s26
	s_cselect_b32 s27, s13, s69
	s_cselect_b32 s26, s61, s68
	v_lshl_add_u64 v[168:169], s[24:25], 0, v[152:153]
	s_add_i32 m0, s42, 0xc000
	ds_read_b128 v[186:189], v175
	ds_read_b128 v[190:193], v175 offset:1024
	ds_read_b128 v[194:197], v175 offset:2048
	ds_read_b128 v[198:201], v175 offset:3072
	ds_read_b128 v[202:205], v175 offset:4096
	ds_read_b128 v[206:209], v175 offset:5120
	ds_read_b128 v[210:213], v175 offset:6144
	ds_read_b128 v[214:217], v175 offset:7168
	global_load_lds_dwordx4 v[168:169], off
	v_lshl_add_u64 v[168:169], s[24:25], 0, v[154:155]
	s_add_i32 m0, s42, 0xe000
	s_nop 0
	global_load_lds_dwordx4 v[168:169], off
	s_waitcnt vmcnt(8)
	s_waitcnt lgkmcnt(0)
	s_barrier
	s_setprio 1
	s_waitcnt lgkmcnt(0)
	v_mfma_f32_16x16x32_bf16 v[124:127], v[128:131], v[186:189], v[124:127]
	v_mfma_f32_16x16x32_bf16 v[120:123], v[136:139], v[186:189], v[120:123]
	v_mfma_f32_16x16x32_bf16 v[108:111], v[128:131], v[194:197], v[108:111]
	v_mfma_f32_16x16x32_bf16 v[104:107], v[136:139], v[194:197], v[104:107]
	v_mfma_f32_16x16x32_bf16 v[92:95], v[128:131], v[202:205], v[92:95]
	v_mfma_f32_16x16x32_bf16 v[88:91], v[136:139], v[202:205], v[88:91]
	v_mfma_f32_16x16x32_bf16 v[76:79], v[128:131], v[210:213], v[76:79]
	v_mfma_f32_16x16x32_bf16 v[72:75], v[136:139], v[210:213], v[72:75]
	v_mfma_f32_16x16x32_bf16 v[124:127], v[132:135], v[190:193], v[124:127]
	v_mfma_f32_16x16x32_bf16 v[120:123], v[140:143], v[190:193], v[120:123]
	v_mfma_f32_16x16x32_bf16 v[108:111], v[132:135], v[198:201], v[108:111]
	v_mfma_f32_16x16x32_bf16 v[104:107], v[140:143], v[198:201], v[104:107]
	v_mfma_f32_16x16x32_bf16 v[92:95], v[132:135], v[206:209], v[92:95]
	v_mfma_f32_16x16x32_bf16 v[88:91], v[140:143], v[206:209], v[88:91]
	v_mfma_f32_16x16x32_bf16 v[76:79], v[132:135], v[214:217], v[76:79]
	v_mfma_f32_16x16x32_bf16 v[72:75], v[140:143], v[214:217], v[72:75]
	s_setprio 0
	s_setprio 1
	v_mfma_f32_16x16x32_bf16 v[116:119], v[160:163], v[186:189], v[116:119]
	v_mfma_f32_16x16x32_bf16 v[112:115], v[178:181], v[186:189], v[112:115]
	v_mfma_f32_16x16x32_bf16 v[100:103], v[160:163], v[194:197], v[100:103]
	v_mfma_f32_16x16x32_bf16 v[96:99], v[178:181], v[194:197], v[96:99]
	v_mfma_f32_16x16x32_bf16 v[84:87], v[160:163], v[202:205], v[84:87]
	v_mfma_f32_16x16x32_bf16 v[80:83], v[178:181], v[202:205], v[80:83]
	v_mfma_f32_16x16x32_bf16 v[68:71], v[160:163], v[210:213], v[68:71]
	v_mfma_f32_16x16x32_bf16 v[64:67], v[178:181], v[210:213], v[64:67]
	v_mfma_f32_16x16x32_bf16 v[116:119], v[164:167], v[190:193], v[116:119]
	v_mfma_f32_16x16x32_bf16 v[112:115], v[182:185], v[190:193], v[112:115]
	v_mfma_f32_16x16x32_bf16 v[100:103], v[164:167], v[198:201], v[100:103]
	v_mfma_f32_16x16x32_bf16 v[96:99], v[182:185], v[198:201], v[96:99]
	v_mfma_f32_16x16x32_bf16 v[84:87], v[164:167], v[206:209], v[84:87]
	v_mfma_f32_16x16x32_bf16 v[80:83], v[182:185], v[206:209], v[80:83]
	v_mfma_f32_16x16x32_bf16 v[68:71], v[164:167], v[214:217], v[68:71]
	v_mfma_f32_16x16x32_bf16 v[64:67], v[182:185], v[214:217], v[64:67]
	s_setprio 0
	s_barrier
	s_add_i32 s71, s52, s39
	v_lshl_add_u64 v[168:169], s[26:27], 0, v[148:149]
	s_mov_b32 m0, s71
	ds_read_b128 v[186:189], v175 offset:16384
	ds_read_b128 v[190:193], v175 offset:17408
	ds_read_b128 v[194:197], v175 offset:18432
	ds_read_b128 v[198:201], v175 offset:19456
	ds_read_b128 v[202:205], v175 offset:20480
	ds_read_b128 v[206:209], v175 offset:21504
	ds_read_b128 v[210:213], v175 offset:22528
	ds_read_b128 v[214:217], v175 offset:23552
	global_load_lds_dwordx4 v[168:169], off
	s_add_i32 m0, s71, 0x2000
	s_add_u32 s72, s26, 0x40000
	v_lshl_add_u64 v[218:219], s[26:27], 0, v[144:145]
	s_addc_u32 s73, s27, 0
	s_add_i32 s71, s53, s39
	global_load_lds_dwordx4 v[218:219], off
	v_lshl_add_u64 v[220:221], s[72:73], 0, v[148:149]
	s_mov_b32 m0, s71
	v_lshl_add_u64 v[222:223], s[36:37], 0, v[146:147]
	global_load_lds_dwordx4 v[220:221], off
	v_lshl_add_u64 v[220:221], s[72:73], 0, v[144:145]
	s_add_i32 m0, s71, 0x2000
	s_nop 0
	global_load_lds_dwordx4 v[220:221], off
	s_waitcnt vmcnt(6)
	s_waitcnt lgkmcnt(0)
	s_barrier
; #define PG8_STAGE(bufoff, gbase, voff) do { _Pragma("unroll") for (int _i = 0; _i < 2; ++_i) \
;         __builtin_amdgcn_global_load_lds((const unsigned*)((const char*)(gbase) + (voff)[_i]), (PG8_LAS unsigned*)(lds + (bufoff) + ldsw + _i * 8192), 16, 0, 0); } while (0)
; #define PG8_LDA(dst, b, h) do { _Pragma("unroll") for (int m = 0; m < 4; ++m) _Pragma("unroll") for (int k = 0; k < 2; ++k) dst[m][k] = *(const PG8_LAS bf16x8*)(lds + PG8_SA(b, h) + aoff + m * 2048 + k * 1024); } while (0)
; #define PG8_LDB(dst, b, h) do { _Pragma("unroll") for (int n = 0; n < 2; ++n) _Pragma("unroll") for (int k = 0; k < 2; ++k) dst[n][k] = *(const PG8_LAS bf16x8*)(lds + PG8_SB(b, h) + boff + n * 2048 + k * 1024); } while (0)
; #define PG8_MMA(ai, bj, At, Bt) do { __builtin_amdgcn_s_setprio(1); _Pragma("unroll") for (int m = 0; m < 4; ++m) _Pragma("unroll") for (int n = 0; n < 2; ++n) _Pragma("unroll") for (int k = 0; k < 2; ++k) \
;         acc[ai][bj][m][n] = __builtin_amdgcn_mfma_f32_16x16x32_bf16(Bt[n][k], At[m][k], acc[ai][bj][m][n], 0, 0, 0); __builtin_amdgcn_s_setprio(0); } while (0)
; #define PG8_WAIT_V(n) asm volatile("s_waitcnt vmcnt(" #n ")" ::: "memory")
; #define PG8_WAIT_L(n) asm volatile("s_waitcnt lgkmcnt(" #n ")" ::: "memory")
; #define PG8_BAR __builtin_amdgcn_s_barrier()
; #define PG8_SCHED __builtin_amdgcn_sched_barrier(0)
; template <class Epi, class Sched, bool ALIGN_EPI = false, bool SP2 = false>
; __device__ __forceinline__ void gemm_phase(PG8_LAS unsigned char* lds, const Gemm g, const Sched& S, const Epi& E) {
;     ...
;             PG8_WAIT_V(8); PG8_WAIT_L(0); PG8_BAR; PG8_MMA(1, 0, At, B0); PG8_MMA(1, 1, At, B1); PG8_BAR; PG8_SCHED;
;             PG8_LDB(B0, 1, 0); PG8_LDB(B1, 1, 1); PG8_SCHED; PG8_LDA(At, 1, 0); PG8_STAGE(PG8_SA(0, 1), a2 + hstep, voffA);
;             PG8_WAIT_V(8); PG8_WAIT_L(0); PG8_BAR; PG8_MMA(0, 0, At, B0); PG8_MMA(0, 1, At, B1); PG8_BAR; PG8_SCHED;
	s_setprio 1
	s_waitcnt lgkmcnt(0)
	v_mfma_f32_16x16x32_bf16 v[60:63], v[128:131], v[186:189], v[60:63]
	v_mfma_f32_16x16x32_bf16 v[56:59], v[136:139], v[186:189], v[56:59]
	v_mfma_f32_16x16x32_bf16 v[44:47], v[128:131], v[194:197], v[44:47]
	v_mfma_f32_16x16x32_bf16 v[40:43], v[136:139], v[194:197], v[40:43]
	v_mfma_f32_16x16x32_bf16 v[28:31], v[128:131], v[202:205], v[28:31]
	v_mfma_f32_16x16x32_bf16 v[24:27], v[136:139], v[202:205], v[24:27]
	v_lshl_add_u64 v[220:221], s[36:37], 0, v[150:151]
	s_mov_b32 m0, s42
	s_nop 0
	global_load_lds_dwordx4 v[220:221], off
	v_mfma_f32_16x16x32_bf16 v[12:15], v[128:131], v[210:213], v[12:15]
	v_mfma_f32_16x16x32_bf16 v[8:11], v[136:139], v[210:213], v[8:11]
	v_mfma_f32_16x16x32_bf16 v[60:63], v[132:135], v[190:193], v[60:63]
	v_mfma_f32_16x16x32_bf16 v[56:59], v[140:143], v[190:193], v[56:59]
	v_mfma_f32_16x16x32_bf16 v[44:47], v[132:135], v[198:201], v[44:47]
	v_mfma_f32_16x16x32_bf16 v[40:43], v[140:143], v[198:201], v[40:43]
	v_mfma_f32_16x16x32_bf16 v[28:31], v[132:135], v[206:209], v[28:31]
	v_mfma_f32_16x16x32_bf16 v[24:27], v[140:143], v[206:209], v[24:27]
	v_mfma_f32_16x16x32_bf16 v[12:15], v[132:135], v[214:217], v[12:15]
	v_mfma_f32_16x16x32_bf16 v[8:11], v[140:143], v[214:217], v[8:11]
	s_setprio 0
	s_setprio 1
	v_mfma_f32_16x16x32_bf16 v[52:55], v[160:163], v[186:189], v[52:55]
	v_mfma_f32_16x16x32_bf16 v[48:51], v[178:181], v[186:189], v[48:51]
	v_mfma_f32_16x16x32_bf16 v[36:39], v[160:163], v[194:197], v[36:39]
	v_mfma_f32_16x16x32_bf16 v[32:35], v[178:181], v[194:197], v[32:35]
	v_mfma_f32_16x16x32_bf16 v[20:23], v[160:163], v[202:205], v[20:23]
	v_mfma_f32_16x16x32_bf16 v[16:19], v[178:181], v[202:205], v[16:19]
	s_mov_b32 m0, s43
	s_nop 0
	global_load_lds_dwordx4 v[222:223], off
	v_mfma_f32_16x16x32_bf16 v[4:7], v[160:163], v[210:213], v[4:7]
	v_mfma_f32_16x16x32_bf16 v[0:3], v[178:181], v[210:213], v[0:3]
	v_mfma_f32_16x16x32_bf16 v[52:55], v[164:167], v[190:193], v[52:55]
	v_mfma_f32_16x16x32_bf16 v[48:51], v[182:185], v[190:193], v[48:51]
	v_mfma_f32_16x16x32_bf16 v[36:39], v[164:167], v[198:201], v[36:39]
	v_mfma_f32_16x16x32_bf16 v[32:35], v[182:185], v[198:201], v[32:35]
	v_mfma_f32_16x16x32_bf16 v[20:23], v[164:167], v[206:209], v[20:23]
	v_mfma_f32_16x16x32_bf16 v[16:19], v[182:185], v[206:209], v[16:19]
	v_mfma_f32_16x16x32_bf16 v[4:7], v[164:167], v[214:217], v[4:7]
	v_mfma_f32_16x16x32_bf16 v[0:3], v[182:185], v[214:217], v[0:3]
	s_setprio 0
	s_barrier
	s_add_i32 s71, 0, 0x18000
	s_add_i32 s72, 0, 0x1c000
	v_add_u32_e32 v140, s71, v171
	v_add_u32_e32 v177, s72, v171
	ds_read_b128 v[128:131], v140
	ds_read_b128 v[132:135], v140 offset:1024
	ds_read_b128 v[136:139], v140 offset:2048
	ds_read_b128 v[140:143], v140 offset:3072
	ds_read_b128 v[160:163], v177
	ds_read_b128 v[164:167], v177 offset:1024
	ds_read_b128 v[178:181], v177 offset:2048
	ds_read_b128 v[182:185], v177 offset:3072
	s_add_u32 s36, s36, 0x40000
	s_addc_u32 s37, s37, 0
	s_mov_b32 m0, s44
	v_lshl_add_u64 v[224:225], s[36:37], 0, v[150:151]
	ds_read_b128 v[186:189], v175 offset:32768
	ds_read_b128 v[190:193], v175 offset:33792
	ds_read_b128 v[194:197], v175 offset:34816
	ds_read_b128 v[198:201], v175 offset:35840
	ds_read_b128 v[202:205], v175 offset:36864
	ds_read_b128 v[206:209], v175 offset:37888
	ds_read_b128 v[210:213], v175 offset:38912
	ds_read_b128 v[214:217], v175 offset:39936
	global_load_lds_dwordx4 v[224:225], off
	v_lshl_add_u64 v[224:225], s[36:37], 0, v[146:147]
	s_mov_b32 m0, s45
	s_nop 0
	global_load_lds_dwordx4 v[224:225], off
	s_waitcnt vmcnt(8)
	s_waitcnt lgkmcnt(0)
	s_barrier
	s_setprio 1
	s_waitcnt lgkmcnt(0)
	v_mfma_f32_16x16x32_bf16 v[124:127], v[128:131], v[186:189], v[124:127]
	v_mfma_f32_16x16x32_bf16 v[120:123], v[136:139], v[186:189], v[120:123]
	v_mfma_f32_16x16x32_bf16 v[108:111], v[128:131], v[194:197], v[108:111]
	v_mfma_f32_16x16x32_bf16 v[104:107], v[136:139], v[194:197], v[104:107]
	v_mfma_f32_16x16x32_bf16 v[92:95], v[128:131], v[202:205], v[92:95]
	v_mfma_f32_16x16x32_bf16 v[88:91], v[136:139], v[202:205], v[88:91]
	v_mfma_f32_16x16x32_bf16 v[76:79], v[128:131], v[210:213], v[76:79]
	v_mfma_f32_16x16x32_bf16 v[72:75], v[136:139], v[210:213], v[72:75]
	v_mfma_f32_16x16x32_bf16 v[124:127], v[132:135], v[190:193], v[124:127]
	v_mfma_f32_16x16x32_bf16 v[120:123], v[140:143], v[190:193], v[120:123]
	v_mfma_f32_16x16x32_bf16 v[108:111], v[132:135], v[198:201], v[108:111]
	v_mfma_f32_16x16x32_bf16 v[104:107], v[140:143], v[198:201], v[104:107]
	v_mfma_f32_16x16x32_bf16 v[92:95], v[132:135], v[206:209], v[92:95]
	v_mfma_f32_16x16x32_bf16 v[88:91], v[140:143], v[206:209], v[88:91]
	v_mfma_f32_16x16x32_bf16 v[76:79], v[132:135], v[214:217], v[76:79]
	v_mfma_f32_16x16x32_bf16 v[72:75], v[140:143], v[214:217], v[72:75]
	s_setprio 0
	s_setprio 1
	v_mfma_f32_16x16x32_bf16 v[116:119], v[160:163], v[186:189], v[116:119]
	v_mfma_f32_16x16x32_bf16 v[112:115], v[178:181], v[186:189], v[112:115]
	v_mfma_f32_16x16x32_bf16 v[100:103], v[160:163], v[194:197], v[100:103]
	v_mfma_f32_16x16x32_bf16 v[96:99], v[178:181], v[194:197], v[96:99]
	v_mfma_f32_16x16x32_bf16 v[84:87], v[160:163], v[202:205], v[84:87]
	v_mfma_f32_16x16x32_bf16 v[80:83], v[178:181], v[202:205], v[80:83]
	v_mfma_f32_16x16x32_bf16 v[68:71], v[160:163], v[210:213], v[68:71]
	v_mfma_f32_16x16x32_bf16 v[64:67], v[178:181], v[210:213], v[64:67]
	v_mfma_f32_16x16x32_bf16 v[116:119], v[164:167], v[190:193], v[116:119]
	v_mfma_f32_16x16x32_bf16 v[112:115], v[182:185], v[190:193], v[112:115]
	v_mfma_f32_16x16x32_bf16 v[100:103], v[164:167], v[198:201], v[100:103]
	v_mfma_f32_16x16x32_bf16 v[96:99], v[182:185], v[198:201], v[96:99]
	v_mfma_f32_16x16x32_bf16 v[84:87], v[164:167], v[206:209], v[84:87]
	v_mfma_f32_16x16x32_bf16 v[80:83], v[182:185], v[206:209], v[80:83]
	v_mfma_f32_16x16x32_bf16 v[68:71], v[164:167], v[214:217], v[68:71]
	v_mfma_f32_16x16x32_bf16 v[64:67], v[182:185], v[214:217], v[64:67]
	s_setprio 0
	s_barrier
; #define PG8_STAGE(bufoff, gbase, voff) do { _Pragma("unroll") for (int _i = 0; _i < 2; ++_i) \
;         __builtin_amdgcn_global_load_lds((const unsigned*)((const char*)(gbase) + (voff)[_i]), (PG8_LAS unsigned*)(lds + (bufoff) + ldsw + _i * 8192), 16, 0, 0); } while (0)
; #define PG8_LDA(dst, b, h) do { _Pragma("unroll") for (int m = 0; m < 4; ++m) _Pragma("unroll") for (int k = 0; k < 2; ++k) dst[m][k] = *(const PG8_LAS bf16x8*)(lds + PG8_SA(b, h) + aoff + m * 2048 + k * 1024); } while (0)
; #define PG8_MMA(ai, bj, At, Bt) do { __builtin_amdgcn_s_setprio(1); _Pragma("unroll") for (int m = 0; m < 4; ++m) _Pragma("unroll") for (int n = 0; n < 2; ++n) _Pragma("unroll") for (int k = 0; k < 2; ++k) \
;         acc[ai][bj][m][n] = __builtin_amdgcn_mfma_f32_16x16x32_bf16(Bt[n][k], At[m][k], acc[ai][bj][m][n], 0, 0, 0); __builtin_amdgcn_s_setprio(0); } while (0)
; #define PG8_WAIT_V(n) asm volatile("s_waitcnt vmcnt(" #n ")" ::: "memory")
; #define PG8_WAIT_L(n) asm volatile("s_waitcnt lgkmcnt(" #n ")" ::: "memory")
; #define PG8_BAR __builtin_amdgcn_s_barrier()
; #define PG8_SCHED __builtin_amdgcn_sched_barrier(0)
; template <class Epi, class Sched, bool ALIGN_EPI = false, bool SP2 = false>
; __device__ __forceinline__ void gemm_phase(PG8_LAS unsigned char* lds, const Gemm g, const Sched& S, const Epi& E) {
;     ...
;         for (int t = 0; t < nt; t += 2) {
;             const bool last = (t == nt - 2);
;             const char* a1 = cA + (size_t)(t + 1) * kstep;
;             const char* a2 = last ? nA : cA + (size_t)(t + 2) * kstep; const char* b2 = last ? nB : cB + (size_t)(t + 2) * kstep;
;     ...
;             PG8_LDA(At, 1, 1); PG8_STAGE(PG8_SB(1, 0), b3, voffB); PG8_STAGE(PG8_SB(1, 1), b3 + hstep, voffB); PG8_STAGE(PG8_SA(1, 0), a3, voffA);
;             PG8_WAIT_V(8); PG8_WAIT_L(0); PG8_BAR; PG8_MMA(1, 0, At, B0); PG8_MMA(1, 1, At, B1); PG8_BAR; PG8_SCHED;
	s_add_i32 s36, s71, s39
	v_lshl_add_u64 v[168:169], v[168:169], 0, s[6:7]
	s_mov_b32 m0, s36
	ds_read_b128 v[186:189], v175 offset:49152
	ds_read_b128 v[190:193], v175 offset:50176
	ds_read_b128 v[194:197], v175 offset:51200
	ds_read_b128 v[198:201], v175 offset:52224
	ds_read_b128 v[202:205], v175 offset:53248
	ds_read_b128 v[206:209], v175 offset:54272
	ds_read_b128 v[210:213], v175 offset:55296
	ds_read_b128 v[214:217], v175 offset:56320
	global_load_lds_dwordx4 v[168:169], off
	s_add_i32 m0, s36, 0x2000
	s_add_u32 s26, s26, 0x40080
	v_lshl_add_u64 v[168:169], v[218:219], 0, s[6:7]
	s_addc_u32 s27, s27, 0
	s_add_i32 s36, s72, s39
	global_load_lds_dwordx4 v[168:169], off
	v_lshl_add_u64 v[168:169], s[26:27], 0, v[148:149]
	s_mov_b32 m0, s36
	s_nop 0
	global_load_lds_dwordx4 v[168:169], off
	v_lshl_add_u64 v[168:169], s[26:27], 0, v[144:145]
	s_add_i32 m0, s36, 0x2000
	s_nop 0
	global_load_lds_dwordx4 v[168:169], off
	s_waitcnt vmcnt(6)
	s_waitcnt lgkmcnt(0)
	s_barrier
	s_setprio 1
	s_waitcnt lgkmcnt(0)
	v_mfma_f32_16x16x32_bf16 v[60:63], v[128:131], v[186:189], v[60:63]
	v_mfma_f32_16x16x32_bf16 v[56:59], v[136:139], v[186:189], v[56:59]
	v_mfma_f32_16x16x32_bf16 v[44:47], v[128:131], v[194:197], v[44:47]
	v_mfma_f32_16x16x32_bf16 v[40:43], v[136:139], v[194:197], v[40:43]
	v_mfma_f32_16x16x32_bf16 v[28:31], v[128:131], v[202:205], v[28:31]
	v_mfma_f32_16x16x32_bf16 v[24:27], v[136:139], v[202:205], v[24:27]
	v_lshl_add_u64 v[168:169], v[220:221], 0, s[6:7]
	s_mov_b32 m0, s47
	s_nop 0
	global_load_lds_dwordx4 v[168:169], off
	v_mfma_f32_16x16x32_bf16 v[12:15], v[128:131], v[210:213], v[12:15]
	v_mfma_f32_16x16x32_bf16 v[8:11], v[136:139], v[210:213], v[8:11]
	v_mfma_f32_16x16x32_bf16 v[60:63], v[132:135], v[190:193], v[60:63]
	v_mfma_f32_16x16x32_bf16 v[56:59], v[140:143], v[190:193], v[56:59]
	v_mfma_f32_16x16x32_bf16 v[44:47], v[132:135], v[198:201], v[44:47]
	v_mfma_f32_16x16x32_bf16 v[40:43], v[140:143], v[198:201], v[40:43]
	v_mfma_f32_16x16x32_bf16 v[28:31], v[132:135], v[206:209], v[28:31]
	v_mfma_f32_16x16x32_bf16 v[24:27], v[140:143], v[206:209], v[24:27]
	v_mfma_f32_16x16x32_bf16 v[12:15], v[132:135], v[214:217], v[12:15]
	v_mfma_f32_16x16x32_bf16 v[8:11], v[140:143], v[214:217], v[8:11]
	s_setprio 0
	s_setprio 1
	v_mfma_f32_16x16x32_bf16 v[52:55], v[160:163], v[186:189], v[52:55]
	v_mfma_f32_16x16x32_bf16 v[48:51], v[178:181], v[186:189], v[48:51]
	v_mfma_f32_16x16x32_bf16 v[36:39], v[160:163], v[194:197], v[36:39]
	v_mfma_f32_16x16x32_bf16 v[32:35], v[178:181], v[194:197], v[32:35]
	v_mfma_f32_16x16x32_bf16 v[20:23], v[160:163], v[202:205], v[20:23]
	v_mfma_f32_16x16x32_bf16 v[16:19], v[178:181], v[202:205], v[16:19]
	v_lshl_add_u64 v[168:169], v[222:223], 0, s[6:7]
	s_mov_b32 m0, s48
	s_nop 0
	global_load_lds_dwordx4 v[168:169], off
	v_mfma_f32_16x16x32_bf16 v[4:7], v[160:163], v[210:213], v[4:7]
	v_mfma_f32_16x16x32_bf16 v[0:3], v[178:181], v[210:213], v[0:3]
	v_mfma_f32_16x16x32_bf16 v[52:55], v[164:167], v[190:193], v[52:55]
	v_mfma_f32_16x16x32_bf16 v[48:51], v[182:185], v[190:193], v[48:51]
	v_mfma_f32_16x16x32_bf16 v[36:39], v[164:167], v[198:201], v[36:39]
	v_mfma_f32_16x16x32_bf16 v[32:35], v[182:185], v[198:201], v[32:35]
	v_mfma_f32_16x16x32_bf16 v[20:23], v[164:167], v[206:209], v[20:23]
	v_mfma_f32_16x16x32_bf16 v[16:19], v[182:185], v[206:209], v[16:19]
	v_mfma_f32_16x16x32_bf16 v[4:7], v[164:167], v[214:217], v[4:7]
	v_mfma_f32_16x16x32_bf16 v[0:3], v[182:185], v[214:217], v[0:3]
	s_setprio 0
	s_barrier
	s_add_i32 s70, s70, 2
	s_add_u32 s24, s24, 0x100
	s_addc_u32 s25, s25, 0
	s_add_u32 s68, s68, 0x100
	s_addc_u32 s69, s69, 0
	s_cmp_gt_u32 s70, 13
	s_cbranch_scc0 .LBB0_813
; __device__ __forceinline__ u32x2 pack4(f32x4 v) { u32x2 w; w.x = cvt_pk_bf16(v[0], v[1]); w.y = cvt_pk_bf16(v[2], v[3]); return w; }
;     __device__ __forceinline__ void operator()(const f32x4 (&acc)[2][2][4][2], const Unit& u, int wr, int wc, int fr, int fq) const {
;         const int row0 = u.pm * BM + wr * 64 + fr, col0 = u.pn * BM + wc * 32 + 8 * fq;
;         const float* base = (u.pm * BM < split) ? base0 : base1; bf16_t* const xn = (bf16_t*)(ws + WS_XN); float* const ssq = (float*)(ws + WS_SSQ);
; #pragma unroll
;         for (int ai = 0; ai < 2; ++ai)
; #pragma unroll
;         for (int mh = 0; mh < 4; mh += 2) {
;             f32x4 pre[4][2][2];
; #pragma unroll
;             for (int m = mh; m < mh + 2; ++m)
; #pragma unroll
;                 for (int bj = 0; bj < 2; ++bj)
; #pragma unroll
;                     for (int n = 0; n < 2; ++n) pre[m][bj][n] = *(const f32x4*)(base + (size_t)(row0 + ai * HALF + m * 16) * 1024 + col0 + bj * HALF + n * 4);
;             asm volatile("" ::: "memory");
; #pragma unroll
;             for (int m = mh; m < mh + 2; ++m) { const int row = row0 + ai * HALF + m * 16; const size_t off = (size_t)row * 1024 + col0; float ss = 0.f;
; #pragma unroll
;                 for (int bj = 0; bj < 2; ++bj) { u32x4e w;
; #pragma unroll
;                     for (int n = 0; n < 2; ++n) { const f32x4 o = pre[m][bj][n] + acc[ai][bj][m][n] * s;
;                         *(f32x4*)(out + off + bj * HALF + n * 4) = o;
;                         if (NORMOUT) { const u32x2 p = pack4(o); w[2 * n] = p.x; w[2 * n + 1] = p.y; ss += (o[0] * o[0] + o[1] * o[1]) + (o[2] * o[2] + o[3] * o[3]); } }
;                     if (NORMOUT) *(u32x4e*)(xn + off + bj * HALF) = w; }
;                 if (NORMOUT) { ss += __shfl_xor(ss, 16); ss += __shfl_xor(ss, 32); if (fq == 0) ssq[(size_t)row * 16 + u.pn * 4 + wc] = ss; } }
	v_lshl_add_u32 v164, s22, 8, v170
	v_lshl_or_b32 v160, s23, 8, v172
	v_ashrrev_i32_e32 v161, 31, v160
	v_ashrrev_i32_e32 v165, 31, v164
	v_lshl_add_u64 v[162:163], v[160:161], 2, s[56:57]
	v_lshlrev_b64 v[128:129], 12, v[164:165]
	v_lshl_add_u64 v[196:197], v[162:163], 0, v[128:129]
	global_load_dwordx4 v[180:183], v[196:197], off
	global_load_dwordx4 v[184:187], v[196:197], off offset:16
	global_load_dwordx4 v[188:191], v[196:197], off offset:512
	global_load_dwordx4 v[192:195], v[196:197], off offset:528
	v_or_b32_e32 v166, 16, v164
	v_ashrrev_i32_e32 v167, 31, v166
	v_lshlrev_b64 v[128:129], 12, v[166:167]
	v_lshl_add_u64 v[168:169], v[162:163], 0, v[128:129]
	global_load_dwordx4 v[136:139], v[168:169], off offset:16
	global_load_dwordx4 v[140:143], v[168:169], off
	global_load_dwordx4 v[128:131], v[168:169], off offset:528
	global_load_dwordx4 v[132:135], v[168:169], off offset:512
	v_and_b32_e32 v178, 64, v176
	v_xor_b32_e32 v177, 16, v176
	v_add_u32_e32 v178, 64, v178
	v_xor_b32_e32 v179, 32, v176
	v_cmp_lt_i32_e32 vcc, v177, v178
	v_lshlrev_b64 v[198:199], 10, v[164:165]
	v_lshl_add_u64 v[198:199], v[198:199], 0, v[160:161]
	v_cndmask_b32_e32 v177, v176, v177, vcc
	v_cmp_lt_i32_e32 vcc, v179, v178
	v_lshlrev_b32_e32 v178, 2, v177
	v_lshl_add_u64 v[198:199], v[198:199], 1, s[64:65]
	v_cndmask_b32_e32 v179, v176, v179, vcc
	v_lshlrev_b32_e32 v177, 2, v179
	s_lshl_b32 s22, s23, 2
	s_ashr_i32 s23, s22, 31
	s_lshl_b64 s[22:23], s[22:23], 2
	s_add_u32 s22, s50, s22
	s_addc_u32 s23, s51, s23
	s_waitcnt vmcnt(0)
	v_pk_add_f32 v[126:127], v[182:183], v[126:127]
	v_pk_add_f32 v[124:125], v[180:181], v[124:125]
	v_pk_add_f32 v[122:123], v[186:187], v[122:123]
	v_pk_add_f32 v[120:121], v[184:185], v[120:121]
	v_pk_add_f32 v[118:119], v[190:191], v[118:119]
	v_pk_add_f32 v[116:117], v[188:189], v[116:117]
	v_pk_add_f32 v[182:183], v[194:195], v[114:115]
	v_pk_add_f32 v[180:181], v[192:193], v[112:113]
	global_store_dwordx4 v[196:197], v[124:127], off
	v_cvt_pk_bf16_f32 v112, v124, v125
	v_cvt_pk_bf16_f32 v113, v126, v127
	v_mul_f32_e32 v125, v125, v125
	v_mul_f32_e32 v127, v127, v127
	global_store_dwordx4 v[196:197], v[120:123], off offset:16
	v_cvt_pk_bf16_f32 v114, v120, v121
	v_cvt_pk_bf16_f32 v115, v122, v123
	v_mul_f32_e32 v121, v121, v121
	v_mul_f32_e32 v123, v123, v123
	v_mul_f32_e32 v179, v117, v117
	v_mul_f32_e32 v184, v119, v119
	v_fmac_f32_e32 v125, v124, v124
	v_fmac_f32_e32 v127, v126, v126
	v_fmac_f32_e32 v121, v120, v120
	v_fmac_f32_e32 v123, v122, v122
	v_mul_f32_e32 v185, v181, v181
	v_mul_f32_e32 v186, v183, v183
	v_fmac_f32_e32 v179, v116, v116
	v_fmac_f32_e32 v184, v118, v118
	v_add_f32_e32 v120, v125, v127
	v_add_f32_e32 v121, v121, v123
	v_fmac_f32_e32 v185, v180, v180
	v_fmac_f32_e32 v186, v182, v182
	v_add_f32_e32 v122, v179, v184
	v_add_f32_e32 v120, v120, v121
	v_add_f32_e32 v120, v122, v120
	v_add_f32_e32 v121, v185, v186
	v_add_f32_e32 v120, v121, v120
	ds_bpermute_b32 v121, v178, v120
	global_store_dwordx4 v[198:199], v[112:115], off
	global_store_dwordx4 v[196:197], v[116:119], off offset:512
	global_store_dwordx4 v[196:197], v[180:183], off offset:528
	v_cvt_pk_bf16_f32 v114, v116, v117
	v_cvt_pk_bf16_f32 v115, v118, v119
	s_waitcnt lgkmcnt(0)
	v_add_f32_e32 v112, v120, v121
	ds_bpermute_b32 v113, v177, v112
	v_cvt_pk_bf16_f32 v116, v180, v181
	v_cvt_pk_bf16_f32 v117, v182, v183
	global_store_dwordx4 v[198:199], v[114:117], off offset:256
	s_and_saveexec_b64 s[24:25], s[2:3]
	s_cbranch_execz .LBB0_816
	v_lshlrev_b64 v[114:115], 6, v[164:165]
	v_lshl_add_u64 v[114:115], s[22:23], 0, v[114:115]
	s_waitcnt lgkmcnt(0)
	v_add_f32_e32 v112, v112, v113
	global_store_dword v[114:115], v112, off

; #define PG8_STAGE(bufoff, gbase, voff) do { _Pragma("unroll") for (int _i = 0; _i < 2; ++_i) \
;         __builtin_amdgcn_global_load_lds((const unsigned*)((const char*)(gbase) + (voff)[_i]), (PG8_LAS unsigned*)(lds + (bufoff) + ldsw + _i * 8192), 16, 0, 0); } while (0)
; #define PG8_LDA(dst, b, h) do { _Pragma("unroll") for (int m = 0; m < 4; ++m) _Pragma("unroll") for (int k = 0; k < 2; ++k) dst[m][k] = *(const PG8_LAS bf16x8*)(lds + PG8_SA(b, h) + aoff + m * 2048 + k * 1024); } while (0)
; #define PG8_LDB(dst, b, h) do { _Pragma("unroll") for (int n = 0; n < 2; ++n) _Pragma("unroll") for (int k = 0; k < 2; ++k) dst[n][k] = *(const PG8_LAS bf16x8*)(lds + PG8_SB(b, h) + boff + n * 2048 + k * 1024); } while (0)
; #define PG8_MMA(ai, bj, At, Bt) do { __builtin_amdgcn_s_setprio(1); _Pragma("unroll") for (int m = 0; m < 4; ++m) _Pragma("unroll") for (int n = 0; n < 2; ++n) _Pragma("unroll") for (int k = 0; k < 2; ++k) \
;         acc[ai][bj][m][n] = __builtin_amdgcn_mfma_f32_16x16x32_bf16(Bt[n][k], At[m][k], acc[ai][bj][m][n], 0, 0, 0); __builtin_amdgcn_s_setprio(0); } while (0)
; #define PG8_WAIT_V(n) asm volatile("s_waitcnt vmcnt(" #n ")" ::: "memory")
; #define PG8_WAIT_L(n) asm volatile("s_waitcnt lgkmcnt(" #n ")" ::: "memory")
; #define PG8_BAR __builtin_amdgcn_s_barrier()
; #define PG8_SCHED __builtin_amdgcn_sched_barrier(0)
; template <class Epi, class Sched, bool ALIGN_EPI = false, bool SP2 = false>
; __device__ __forceinline__ void gemm_phase(PG8_LAS unsigned char* lds, const Gemm g, const Sched& S, const Epi& E) {
;     ...
;             PG8_LDB(B0, 0, 0); PG8_LDB(B1, 0, 1); PG8_SCHED; PG8_LDA(At, 0, 0); PG8_STAGE(PG8_SA(1, 1), a1 + hstep, voffA);
;             PG8_WAIT_V(8); PG8_WAIT_L(0); PG8_BAR; PG8_MMA(0, 0, At, B0); PG8_MMA(0, 1, At, B1); PG8_BAR; PG8_SCHED;
;             PG8_LDA(At, 0, 1); PG8_STAGE(PG8_SB(0, 0), b2, voffB); PG8_STAGE(PG8_SB(0, 1), b2 + hstep, voffB); PG8_STAGE(PG8_SA(0, 0), a2, voffA);
;             PG8_WAIT_V(8); PG8_WAIT_L(0); PG8_BAR; PG8_MMA(1, 0, At, B0); PG8_MMA(1, 1, At, B1); PG8_BAR; PG8_SCHED;
.LBB0_895:
	ds_read_b128 v[128:131], v183
	ds_read_b128 v[132:135], v183 offset:1024
	ds_read_b128 v[136:139], v183 offset:2048
	ds_read_b128 v[140:143], v183 offset:3072
	ds_read_b128 v[162:165], v184
	ds_read_b128 v[166:169], v184 offset:1024
	ds_read_b128 v[170:173], v184 offset:2048
	ds_read_b128 v[174:177], v184 offset:3072
	s_add_u32 s26, s4, 0xfffc0080
	s_addc_u32 s27, s5, -1
	s_cmp_eq_u32 s67, 12
	s_cselect_b32 s37, s1, s27
	s_cselect_b32 s36, s21, s26
	s_cselect_b32 s27, s19, s66
	s_cselect_b32 s26, s60, s61
	v_lshl_add_u64 v[222:223], s[4:5], 0, v[154:155]
	s_add_i32 m0, s41, 0xc000
	ds_read_b128 v[190:193], v185
	ds_read_b128 v[194:197], v185 offset:1024
	ds_read_b128 v[198:201], v185 offset:2048
	ds_read_b128 v[202:205], v185 offset:3072
	ds_read_b128 v[206:209], v185 offset:4096
	ds_read_b128 v[210:213], v185 offset:5120
	ds_read_b128 v[214:217], v185 offset:6144
	ds_read_b128 v[218:221], v185 offset:7168
	global_load_lds_dwordx4 v[222:223], off
	v_lshl_add_u64 v[222:223], s[4:5], 0, v[156:157]
	s_add_i32 m0, s41, 0xe000
	s_nop 0
	global_load_lds_dwordx4 v[222:223], off
	s_waitcnt vmcnt(8)
	s_waitcnt lgkmcnt(0)
	s_barrier
	s_setprio 1
	s_waitcnt lgkmcnt(0)
	v_mfma_f32_16x16x32_bf16 v[124:127], v[128:131], v[190:193], v[124:127]
	v_mfma_f32_16x16x32_bf16 v[120:123], v[136:139], v[190:193], v[120:123]
	v_mfma_f32_16x16x32_bf16 v[108:111], v[128:131], v[198:201], v[108:111]
	v_mfma_f32_16x16x32_bf16 v[104:107], v[136:139], v[198:201], v[104:107]
	v_mfma_f32_16x16x32_bf16 v[92:95], v[128:131], v[206:209], v[92:95]
	v_mfma_f32_16x16x32_bf16 v[88:91], v[136:139], v[206:209], v[88:91]
	v_mfma_f32_16x16x32_bf16 v[76:79], v[128:131], v[214:217], v[76:79]
	v_mfma_f32_16x16x32_bf16 v[72:75], v[136:139], v[214:217], v[72:75]
	v_mfma_f32_16x16x32_bf16 v[124:127], v[132:135], v[194:197], v[124:127]
	v_mfma_f32_16x16x32_bf16 v[120:123], v[140:143], v[194:197], v[120:123]
	v_mfma_f32_16x16x32_bf16 v[108:111], v[132:135], v[202:205], v[108:111]
	v_mfma_f32_16x16x32_bf16 v[104:107], v[140:143], v[202:205], v[104:107]
	v_mfma_f32_16x16x32_bf16 v[92:95], v[132:135], v[210:213], v[92:95]
	v_mfma_f32_16x16x32_bf16 v[88:91], v[140:143], v[210:213], v[88:91]
	v_mfma_f32_16x16x32_bf16 v[76:79], v[132:135], v[218:221], v[76:79]
	v_mfma_f32_16x16x32_bf16 v[72:75], v[140:143], v[218:221], v[72:75]
	s_setprio 0
	s_setprio 1
	v_mfma_f32_16x16x32_bf16 v[116:119], v[162:165], v[190:193], v[116:119]
	v_mfma_f32_16x16x32_bf16 v[112:115], v[170:173], v[190:193], v[112:115]
	v_mfma_f32_16x16x32_bf16 v[100:103], v[162:165], v[198:201], v[100:103]
	v_mfma_f32_16x16x32_bf16 v[96:99], v[170:173], v[198:201], v[96:99]
	v_mfma_f32_16x16x32_bf16 v[84:87], v[162:165], v[206:209], v[84:87]
	v_mfma_f32_16x16x32_bf16 v[80:83], v[170:173], v[206:209], v[80:83]
	v_mfma_f32_16x16x32_bf16 v[68:71], v[162:165], v[214:217], v[68:71]
	v_mfma_f32_16x16x32_bf16 v[64:67], v[170:173], v[214:217], v[64:67]
	v_mfma_f32_16x16x32_bf16 v[116:119], v[166:169], v[194:197], v[116:119]
	v_mfma_f32_16x16x32_bf16 v[112:115], v[174:177], v[194:197], v[112:115]
	v_mfma_f32_16x16x32_bf16 v[100:103], v[166:169], v[202:205], v[100:103]
	v_mfma_f32_16x16x32_bf16 v[96:99], v[174:177], v[202:205], v[96:99]
	v_mfma_f32_16x16x32_bf16 v[84:87], v[166:169], v[210:213], v[84:87]
	v_mfma_f32_16x16x32_bf16 v[80:83], v[174:177], v[210:213], v[80:83]
	v_mfma_f32_16x16x32_bf16 v[68:71], v[166:169], v[218:221], v[68:71]
	v_mfma_f32_16x16x32_bf16 v[64:67], v[174:177], v[218:221], v[64:67]
	s_setprio 0
	s_barrier
	s_add_i32 s68, s49, s38
	v_lshl_add_u64 v[222:223], s[26:27], 0, v[148:149]
	s_mov_b32 m0, s68
	ds_read_b128 v[190:193], v185 offset:16384
	ds_read_b128 v[194:197], v185 offset:17408
	ds_read_b128 v[198:201], v185 offset:18432
	ds_read_b128 v[202:205], v185 offset:19456
	ds_read_b128 v[206:209], v185 offset:20480
	ds_read_b128 v[210:213], v185 offset:21504
	ds_read_b128 v[214:217], v185 offset:22528
	ds_read_b128 v[218:221], v185 offset:23552
	global_load_lds_dwordx4 v[222:223], off
	s_add_i32 m0, s68, 0x2000
	s_add_u32 s68, s26, 0x40000
	v_lshl_add_u64 v[224:225], s[26:27], 0, v[144:145]
	s_addc_u32 s69, s27, 0
	s_add_i32 s70, s50, s38
	global_load_lds_dwordx4 v[224:225], off
	v_lshl_add_u64 v[226:227], s[68:69], 0, v[148:149]
	s_mov_b32 m0, s70
	v_lshl_add_u64 v[228:229], s[36:37], 0, v[146:147]
	global_load_lds_dwordx4 v[226:227], off
	v_lshl_add_u64 v[226:227], s[68:69], 0, v[144:145]
	s_add_i32 m0, s70, 0x2000
	s_nop 0
	global_load_lds_dwordx4 v[226:227], off
	s_waitcnt vmcnt(6)
	s_waitcnt lgkmcnt(0)
	s_barrier
; #define PG8_STAGE(bufoff, gbase, voff) do { _Pragma("unroll") for (int _i = 0; _i < 2; ++_i) \
;         __builtin_amdgcn_global_load_lds((const unsigned*)((const char*)(gbase) + (voff)[_i]), (PG8_LAS unsigned*)(lds + (bufoff) + ldsw + _i * 8192), 16, 0, 0); } while (0)
; #define PG8_LDA(dst, b, h) do { _Pragma("unroll") for (int m = 0; m < 4; ++m) _Pragma("unroll") for (int k = 0; k < 2; ++k) dst[m][k] = *(const PG8_LAS bf16x8*)(lds + PG8_SA(b, h) + aoff + m * 2048 + k * 1024); } while (0)
; #define PG8_LDB(dst, b, h) do { _Pragma("unroll") for (int n = 0; n < 2; ++n) _Pragma("unroll") for (int k = 0; k < 2; ++k) dst[n][k] = *(const PG8_LAS bf16x8*)(lds + PG8_SB(b, h) + boff + n * 2048 + k * 1024); } while (0)
; #define PG8_MMA(ai, bj, At, Bt) do { __builtin_amdgcn_s_setprio(1); _Pragma("unroll") for (int m = 0; m < 4; ++m) _Pragma("unroll") for (int n = 0; n < 2; ++n) _Pragma("unroll") for (int k = 0; k < 2; ++k) \
;         acc[ai][bj][m][n] = __builtin_amdgcn_mfma_f32_16x16x32_bf16(Bt[n][k], At[m][k], acc[ai][bj][m][n], 0, 0, 0); __builtin_amdgcn_s_setprio(0); } while (0)
; #define PG8_WAIT_V(n) asm volatile("s_waitcnt vmcnt(" #n ")" ::: "memory")
; #define PG8_WAIT_L(n) asm volatile("s_waitcnt lgkmcnt(" #n ")" ::: "memory")
; #define PG8_BAR __builtin_amdgcn_s_barrier()
; #define PG8_SCHED __builtin_amdgcn_sched_barrier(0)
; template <class Epi, class Sched, bool ALIGN_EPI = false, bool SP2 = false>
; __device__ __forceinline__ void gemm_phase(PG8_LAS unsigned char* lds, const Gemm g, const Sched& S, const Epi& E) {
;     ...
;             PG8_WAIT_V(8); PG8_WAIT_L(0); PG8_BAR; PG8_MMA(1, 0, At, B0); PG8_MMA(1, 1, At, B1); PG8_BAR; PG8_SCHED;
;             PG8_LDB(B0, 1, 0); PG8_LDB(B1, 1, 1); PG8_SCHED; PG8_LDA(At, 1, 0); PG8_STAGE(PG8_SA(0, 1), a2 + hstep, voffA);
;             PG8_WAIT_V(8); PG8_WAIT_L(0); PG8_BAR; PG8_MMA(0, 0, At, B0); PG8_MMA(0, 1, At, B1); PG8_BAR; PG8_SCHED;
	s_setprio 1
	s_waitcnt lgkmcnt(0)
	v_mfma_f32_16x16x32_bf16 v[60:63], v[128:131], v[190:193], v[60:63]
	v_mfma_f32_16x16x32_bf16 v[56:59], v[136:139], v[190:193], v[56:59]
	v_mfma_f32_16x16x32_bf16 v[44:47], v[128:131], v[198:201], v[44:47]
	v_mfma_f32_16x16x32_bf16 v[40:43], v[136:139], v[198:201], v[40:43]
	v_mfma_f32_16x16x32_bf16 v[28:31], v[128:131], v[206:209], v[28:31]
	v_mfma_f32_16x16x32_bf16 v[24:27], v[136:139], v[206:209], v[24:27]
	v_lshl_add_u64 v[226:227], s[36:37], 0, v[150:151]
	s_mov_b32 m0, s41
	s_nop 0
	global_load_lds_dwordx4 v[226:227], off
	v_mfma_f32_16x16x32_bf16 v[12:15], v[128:131], v[214:217], v[12:15]
	v_mfma_f32_16x16x32_bf16 v[8:11], v[136:139], v[214:217], v[8:11]
	v_mfma_f32_16x16x32_bf16 v[60:63], v[132:135], v[194:197], v[60:63]
	v_mfma_f32_16x16x32_bf16 v[56:59], v[140:143], v[194:197], v[56:59]
	v_mfma_f32_16x16x32_bf16 v[44:47], v[132:135], v[202:205], v[44:47]
	v_mfma_f32_16x16x32_bf16 v[40:43], v[140:143], v[202:205], v[40:43]
	v_mfma_f32_16x16x32_bf16 v[28:31], v[132:135], v[210:213], v[28:31]
	v_mfma_f32_16x16x32_bf16 v[24:27], v[140:143], v[210:213], v[24:27]
	v_mfma_f32_16x16x32_bf16 v[12:15], v[132:135], v[218:221], v[12:15]
	v_mfma_f32_16x16x32_bf16 v[8:11], v[140:143], v[218:221], v[8:11]
	s_setprio 0
	s_setprio 1
	v_mfma_f32_16x16x32_bf16 v[52:55], v[162:165], v[190:193], v[52:55]
	v_mfma_f32_16x16x32_bf16 v[48:51], v[170:173], v[190:193], v[48:51]
	v_mfma_f32_16x16x32_bf16 v[36:39], v[162:165], v[198:201], v[36:39]
	v_mfma_f32_16x16x32_bf16 v[32:35], v[170:173], v[198:201], v[32:35]
	v_mfma_f32_16x16x32_bf16 v[20:23], v[162:165], v[206:209], v[20:23]
	v_mfma_f32_16x16x32_bf16 v[16:19], v[170:173], v[206:209], v[16:19]
	s_mov_b32 m0, s42
	s_nop 0
	global_load_lds_dwordx4 v[228:229], off
	v_mfma_f32_16x16x32_bf16 v[4:7], v[162:165], v[214:217], v[4:7]
	v_mfma_f32_16x16x32_bf16 v[0:3], v[170:173], v[214:217], v[0:3]
	v_mfma_f32_16x16x32_bf16 v[52:55], v[166:169], v[194:197], v[52:55]
	v_mfma_f32_16x16x32_bf16 v[48:51], v[174:177], v[194:197], v[48:51]
	v_mfma_f32_16x16x32_bf16 v[36:39], v[166:169], v[202:205], v[36:39]
	v_mfma_f32_16x16x32_bf16 v[32:35], v[174:177], v[202:205], v[32:35]
	v_mfma_f32_16x16x32_bf16 v[20:23], v[166:169], v[210:213], v[20:23]
	v_mfma_f32_16x16x32_bf16 v[16:19], v[174:177], v[210:213], v[16:19]
	v_mfma_f32_16x16x32_bf16 v[4:7], v[166:169], v[218:221], v[4:7]
	v_mfma_f32_16x16x32_bf16 v[0:3], v[174:177], v[218:221], v[0:3]
	s_setprio 0
	s_barrier
	s_add_i32 s68, 0, 0x18000
	s_add_i32 s69, 0, 0x1c000
	v_add_u32_e32 v140, s68, v181
	v_add_u32_e32 v174, s69, v181
	ds_read_b128 v[128:131], v140
	ds_read_b128 v[132:135], v140 offset:1024
	ds_read_b128 v[136:139], v140 offset:2048
	ds_read_b128 v[140:143], v140 offset:3072
	ds_read_b128 v[162:165], v174
	ds_read_b128 v[166:169], v174 offset:1024
	ds_read_b128 v[170:173], v174 offset:2048
	ds_read_b128 v[174:177], v174 offset:3072
	s_add_u32 s36, s36, 0x40000
	s_addc_u32 s37, s37, 0
	s_mov_b32 m0, s43
	v_lshl_add_u64 v[232:233], s[36:37], 0, v[150:151]
	ds_read_b128 v[190:193], v185 offset:32768
	ds_read_b128 v[194:197], v185 offset:33792
	ds_read_b128 v[198:201], v185 offset:34816
	ds_read_b128 v[202:205], v185 offset:35840
	ds_read_b128 v[206:209], v185 offset:36864
	ds_read_b128 v[210:213], v185 offset:37888
	ds_read_b128 v[214:217], v185 offset:38912
	ds_read_b128 v[218:221], v185 offset:39936
	global_load_lds_dwordx4 v[232:233], off
	v_lshl_add_u64 v[232:233], s[36:37], 0, v[146:147]
	s_mov_b32 m0, s44
	s_nop 0
	global_load_lds_dwordx4 v[232:233], off
	s_waitcnt vmcnt(8)
	s_waitcnt lgkmcnt(0)
	s_barrier
	s_setprio 1
	s_waitcnt lgkmcnt(0)
	v_mfma_f32_16x16x32_bf16 v[124:127], v[128:131], v[190:193], v[124:127]
	v_mfma_f32_16x16x32_bf16 v[120:123], v[136:139], v[190:193], v[120:123]
	v_mfma_f32_16x16x32_bf16 v[108:111], v[128:131], v[198:201], v[108:111]
	v_mfma_f32_16x16x32_bf16 v[104:107], v[136:139], v[198:201], v[104:107]
	v_mfma_f32_16x16x32_bf16 v[92:95], v[128:131], v[206:209], v[92:95]
	v_mfma_f32_16x16x32_bf16 v[88:91], v[136:139], v[206:209], v[88:91]
	v_mfma_f32_16x16x32_bf16 v[76:79], v[128:131], v[214:217], v[76:79]
	v_mfma_f32_16x16x32_bf16 v[72:75], v[136:139], v[214:217], v[72:75]
	v_mfma_f32_16x16x32_bf16 v[124:127], v[132:135], v[194:197], v[124:127]
	v_mfma_f32_16x16x32_bf16 v[120:123], v[140:143], v[194:197], v[120:123]
	v_mfma_f32_16x16x32_bf16 v[108:111], v[132:135], v[202:205], v[108:111]
	v_mfma_f32_16x16x32_bf16 v[104:107], v[140:143], v[202:205], v[104:107]
	v_mfma_f32_16x16x32_bf16 v[92:95], v[132:135], v[210:213], v[92:95]
	v_mfma_f32_16x16x32_bf16 v[88:91], v[140:143], v[210:213], v[88:91]
	v_mfma_f32_16x16x32_bf16 v[76:79], v[132:135], v[218:221], v[76:79]
	v_mfma_f32_16x16x32_bf16 v[72:75], v[140:143], v[218:221], v[72:75]
	s_setprio 0
	s_setprio 1
	v_mfma_f32_16x16x32_bf16 v[116:119], v[162:165], v[190:193], v[116:119]
	v_mfma_f32_16x16x32_bf16 v[112:115], v[170:173], v[190:193], v[112:115]
	v_mfma_f32_16x16x32_bf16 v[100:103], v[162:165], v[198:201], v[100:103]
	v_mfma_f32_16x16x32_bf16 v[96:99], v[170:173], v[198:201], v[96:99]
	v_mfma_f32_16x16x32_bf16 v[84:87], v[162:165], v[206:209], v[84:87]
	v_mfma_f32_16x16x32_bf16 v[80:83], v[170:173], v[206:209], v[80:83]
	v_mfma_f32_16x16x32_bf16 v[68:71], v[162:165], v[214:217], v[68:71]
	v_mfma_f32_16x16x32_bf16 v[64:67], v[170:173], v[214:217], v[64:67]
	v_mfma_f32_16x16x32_bf16 v[116:119], v[166:169], v[194:197], v[116:119]
	v_mfma_f32_16x16x32_bf16 v[112:115], v[174:177], v[194:197], v[112:115]
	v_mfma_f32_16x16x32_bf16 v[100:103], v[166:169], v[202:205], v[100:103]
	v_mfma_f32_16x16x32_bf16 v[96:99], v[174:177], v[202:205], v[96:99]
	v_mfma_f32_16x16x32_bf16 v[84:87], v[166:169], v[210:213], v[84:87]
	v_mfma_f32_16x16x32_bf16 v[80:83], v[174:177], v[210:213], v[80:83]
	v_mfma_f32_16x16x32_bf16 v[68:71], v[166:169], v[218:221], v[68:71]
	v_mfma_f32_16x16x32_bf16 v[64:67], v[174:177], v[218:221], v[64:67]
	s_setprio 0
	s_barrier
; #define PG8_STAGE(bufoff, gbase, voff) do { _Pragma("unroll") for (int _i = 0; _i < 2; ++_i) \
;         __builtin_amdgcn_global_load_lds((const unsigned*)((const char*)(gbase) + (voff)[_i]), (PG8_LAS unsigned*)(lds + (bufoff) + ldsw + _i * 8192), 16, 0, 0); } while (0)
; #define PG8_LDA(dst, b, h) do { _Pragma("unroll") for (int m = 0; m < 4; ++m) _Pragma("unroll") for (int k = 0; k < 2; ++k) dst[m][k] = *(const PG8_LAS bf16x8*)(lds + PG8_SA(b, h) + aoff + m * 2048 + k * 1024); } while (0)
; #define PG8_MMA(ai, bj, At, Bt) do { __builtin_amdgcn_s_setprio(1); _Pragma("unroll") for (int m = 0; m < 4; ++m) _Pragma("unroll") for (int n = 0; n < 2; ++n) _Pragma("unroll") for (int k = 0; k < 2; ++k) \
;         acc[ai][bj][m][n] = __builtin_amdgcn_mfma_f32_16x16x32_bf16(Bt[n][k], At[m][k], acc[ai][bj][m][n], 0, 0, 0); __builtin_amdgcn_s_setprio(0); } while (0)
; #define PG8_WAIT_V(n) asm volatile("s_waitcnt vmcnt(" #n ")" ::: "memory")
; #define PG8_WAIT_L(n) asm volatile("s_waitcnt lgkmcnt(" #n ")" ::: "memory")
; #define PG8_BAR __builtin_amdgcn_s_barrier()
; #define PG8_SCHED __builtin_amdgcn_sched_barrier(0)
; template <class Epi, class Sched, bool ALIGN_EPI = false, bool SP2 = false>
; __device__ __forceinline__ void gemm_phase(PG8_LAS unsigned char* lds, const Gemm g, const Sched& S, const Epi& E) {
;     ...
;             PG8_LDA(At, 1, 1); PG8_STAGE(PG8_SB(1, 0), b3, voffB); PG8_STAGE(PG8_SB(1, 1), b3 + hstep, voffB); PG8_STAGE(PG8_SA(1, 0), a3, voffA);
;             PG8_WAIT_V(8); PG8_WAIT_L(0); PG8_BAR; PG8_MMA(1, 0, At, B0); PG8_MMA(1, 1, At, B1); PG8_BAR; PG8_SCHED;
	s_add_i32 s36, s68, s38
	v_lshl_add_u64 v[222:223], v[222:223], 0, s[12:13]
	s_mov_b32 m0, s36
	ds_read_b128 v[190:193], v185 offset:49152
	ds_read_b128 v[194:197], v185 offset:50176
	ds_read_b128 v[198:201], v185 offset:51200
	ds_read_b128 v[202:205], v185 offset:52224
	ds_read_b128 v[206:209], v185 offset:53248
	ds_read_b128 v[210:213], v185 offset:54272
	ds_read_b128 v[214:217], v185 offset:55296
	ds_read_b128 v[218:221], v185 offset:56320
	global_load_lds_dwordx4 v[222:223], off
	s_add_i32 m0, s36, 0x2000
	s_add_u32 s26, s26, 0x40080
	v_lshl_add_u64 v[222:223], v[224:225], 0, s[12:13]
	s_addc_u32 s27, s27, 0
	s_add_i32 s36, s69, s38
	global_load_lds_dwordx4 v[222:223], off
	v_lshl_add_u64 v[222:223], s[26:27], 0, v[148:149]
	s_mov_b32 m0, s36
	s_nop 0
	global_load_lds_dwordx4 v[222:223], off
	v_lshl_add_u64 v[222:223], s[26:27], 0, v[144:145]
	s_add_i32 m0, s36, 0x2000
	s_nop 0
	global_load_lds_dwordx4 v[222:223], off
	s_waitcnt vmcnt(6)
	s_waitcnt lgkmcnt(0)
	s_barrier
	s_setprio 1
	s_waitcnt lgkmcnt(0)
	v_mfma_f32_16x16x32_bf16 v[60:63], v[128:131], v[190:193], v[60:63]
	v_mfma_f32_16x16x32_bf16 v[56:59], v[136:139], v[190:193], v[56:59]
	v_mfma_f32_16x16x32_bf16 v[44:47], v[128:131], v[198:201], v[44:47]
	v_mfma_f32_16x16x32_bf16 v[40:43], v[136:139], v[198:201], v[40:43]
	v_mfma_f32_16x16x32_bf16 v[28:31], v[128:131], v[206:209], v[28:31]
	v_mfma_f32_16x16x32_bf16 v[24:27], v[136:139], v[206:209], v[24:27]
	v_lshl_add_u64 v[222:223], v[226:227], 0, s[12:13]
	s_mov_b32 m0, s46
	s_nop 0
	global_load_lds_dwordx4 v[222:223], off
	v_mfma_f32_16x16x32_bf16 v[12:15], v[128:131], v[214:217], v[12:15]
	v_mfma_f32_16x16x32_bf16 v[8:11], v[136:139], v[214:217], v[8:11]
	v_mfma_f32_16x16x32_bf16 v[60:63], v[132:135], v[194:197], v[60:63]
	v_mfma_f32_16x16x32_bf16 v[56:59], v[140:143], v[194:197], v[56:59]
	v_mfma_f32_16x16x32_bf16 v[44:47], v[132:135], v[202:205], v[44:47]
	v_mfma_f32_16x16x32_bf16 v[40:43], v[140:143], v[202:205], v[40:43]
	v_mfma_f32_16x16x32_bf16 v[28:31], v[132:135], v[210:213], v[28:31]
	v_mfma_f32_16x16x32_bf16 v[24:27], v[140:143], v[210:213], v[24:27]
	v_mfma_f32_16x16x32_bf16 v[12:15], v[132:135], v[218:221], v[12:15]
	v_mfma_f32_16x16x32_bf16 v[8:11], v[140:143], v[218:221], v[8:11]
	s_setprio 0
	s_setprio 1
	v_mfma_f32_16x16x32_bf16 v[52:55], v[162:165], v[190:193], v[52:55]
	v_mfma_f32_16x16x32_bf16 v[48:51], v[170:173], v[190:193], v[48:51]
	v_mfma_f32_16x16x32_bf16 v[36:39], v[162:165], v[198:201], v[36:39]
	v_mfma_f32_16x16x32_bf16 v[32:35], v[170:173], v[198:201], v[32:35]
	v_mfma_f32_16x16x32_bf16 v[20:23], v[162:165], v[206:209], v[20:23]
	v_mfma_f32_16x16x32_bf16 v[16:19], v[170:173], v[206:209], v[16:19]
	v_lshl_add_u64 v[222:223], v[228:229], 0, s[12:13]
	s_mov_b32 m0, s47
	s_nop 0
	global_load_lds_dwordx4 v[222:223], off
	v_mfma_f32_16x16x32_bf16 v[4:7], v[162:165], v[214:217], v[4:7]
	v_mfma_f32_16x16x32_bf16 v[0:3], v[170:173], v[214:217], v[0:3]
	v_mfma_f32_16x16x32_bf16 v[52:55], v[166:169], v[194:197], v[52:55]
	v_mfma_f32_16x16x32_bf16 v[48:51], v[174:177], v[194:197], v[48:51]
	v_mfma_f32_16x16x32_bf16 v[36:39], v[166:169], v[202:205], v[36:39]
	v_mfma_f32_16x16x32_bf16 v[32:35], v[174:177], v[202:205], v[32:35]
	v_mfma_f32_16x16x32_bf16 v[20:23], v[166:169], v[210:213], v[20:23]
	v_mfma_f32_16x16x32_bf16 v[16:19], v[174:177], v[210:213], v[16:19]
	v_mfma_f32_16x16x32_bf16 v[4:7], v[166:169], v[218:221], v[4:7]
	v_mfma_f32_16x16x32_bf16 v[0:3], v[174:177], v[218:221], v[0:3]
	s_setprio 0
	s_barrier
	s_add_i32 s67, s67, 2
	s_add_u32 s4, s4, 0x100
	s_addc_u32 s5, s5, 0
	s_add_u32 s61, s61, 0x100
	s_addc_u32 s66, s66, 0
	s_cmp_gt_u32 s67, 13
	s_cbranch_scc0 .LBB0_895
	s_and_b64 vcc, exec, s[14:15]
	s_cbranch_vccz .LBB0_898
	s_barrier

; #define PG8_STAGE(bufoff, gbase, voff) do { _Pragma("unroll") for (int _i = 0; _i < 2; ++_i) \
;         __builtin_amdgcn_global_load_lds((const unsigned*)((const char*)(gbase) + (voff)[_i]), (PG8_LAS unsigned*)(lds + (bufoff) + ldsw + _i * 8192), 16, 0, 0); } while (0)
; #define PG8_LDA(dst, b, h) do { _Pragma("unroll") for (int m = 0; m < 4; ++m) _Pragma("unroll") for (int k = 0; k < 2; ++k) dst[m][k] = *(const PG8_LAS bf16x8*)(lds + PG8_SA(b, h) + aoff + m * 2048 + k * 1024); } while (0)
; #define PG8_LDB(dst, b, h) do { _Pragma("unroll") for (int n = 0; n < 2; ++n) _Pragma("unroll") for (int k = 0; k < 2; ++k) dst[n][k] = *(const PG8_LAS bf16x8*)(lds + PG8_SB(b, h) + boff + n * 2048 + k * 1024); } while (0)
; #define PG8_MMA(ai, bj, At, Bt) do { __builtin_amdgcn_s_setprio(1); _Pragma("unroll") for (int m = 0; m < 4; ++m) _Pragma("unroll") for (int n = 0; n < 2; ++n) _Pragma("unroll") for (int k = 0; k < 2; ++k) \
;         acc[ai][bj][m][n] = __builtin_amdgcn_mfma_f32_16x16x32_bf16(Bt[n][k], At[m][k], acc[ai][bj][m][n], 0, 0, 0); __builtin_amdgcn_s_setprio(0); } while (0)
; #define PG8_WAIT_V(n) asm volatile("s_waitcnt vmcnt(" #n ")" ::: "memory")
; #define PG8_WAIT_L(n) asm volatile("s_waitcnt lgkmcnt(" #n ")" ::: "memory")
; #define PG8_BAR __builtin_amdgcn_s_barrier()
; #define PG8_SCHED __builtin_amdgcn_sched_barrier(0)
; template <class Epi, class Sched, bool ALIGN_EPI = false, bool SP2 = false>
; __device__ __forceinline__ void gemm_phase(PG8_LAS unsigned char* lds, const Gemm g, const Sched& S, const Epi& E) {
;     ...
;             PG8_LDB(B0, 0, 0); PG8_LDB(B1, 0, 1); PG8_SCHED; PG8_LDA(At, 0, 0); PG8_STAGE(PG8_SA(1, 1), a1 + hstep, voffA);
;             PG8_WAIT_V(8); PG8_WAIT_L(0); PG8_BAR; PG8_MMA(0, 0, At, B0); PG8_MMA(0, 1, At, B1); PG8_BAR; PG8_SCHED;
;             PG8_LDA(At, 0, 1); PG8_STAGE(PG8_SB(0, 0), b2, voffB); PG8_STAGE(PG8_SB(0, 1), b2 + hstep, voffB); PG8_STAGE(PG8_SA(0, 0), a2, voffA);
;             PG8_WAIT_V(8); PG8_WAIT_L(0); PG8_BAR; PG8_MMA(1, 0, At, B0); PG8_MMA(1, 1, At, B1); PG8_BAR; PG8_SCHED;
.LBB0_970:
	ds_read_b128 v[144:147], v154
	ds_read_b128 v[162:165], v154 offset:1024
	ds_read_b128 v[166:169], v154 offset:2048
	ds_read_b128 v[170:173], v154 offset:3072
	ds_read_b128 v[174:177], v155
	ds_read_b128 v[178:181], v155 offset:1024
	ds_read_b128 v[182:185], v155 offset:2048
	ds_read_b128 v[186:189], v155 offset:3072
	s_add_u32 s44, s4, 0xfff50080
	s_addc_u32 s45, s5, -1
	s_cmp_eq_u32 s73, 40
	s_cselect_b32 s47, s39, s45
	s_cselect_b32 s46, s38, s44
	s_cselect_b32 s45, s41, s72
	s_cselect_b32 s44, s40, s43
	v_lshl_add_u64 v[148:149], s[4:5], 0, v[136:137]
	s_add_i32 m0, s48, 0xc000
	ds_read_b128 v[190:193], v156
	ds_read_b128 v[194:197], v156 offset:1024
	ds_read_b128 v[198:201], v156 offset:2048
	ds_read_b128 v[202:205], v156 offset:3072
	ds_read_b128 v[206:209], v156 offset:4096
	ds_read_b128 v[210:213], v156 offset:5120
	ds_read_b128 v[214:217], v156 offset:6144
	ds_read_b128 v[218:221], v156 offset:7168
	global_load_lds_dwordx4 v[148:149], off
	v_lshl_add_u64 v[148:149], s[4:5], 0, v[138:139]
	s_add_i32 m0, s48, 0xe000
	s_nop 0
	global_load_lds_dwordx4 v[148:149], off
	s_waitcnt vmcnt(8)
	s_waitcnt lgkmcnt(0)
	s_barrier
	s_setprio 1
	s_waitcnt lgkmcnt(0)
	v_mfma_f32_16x16x32_bf16 v[124:127], v[144:147], v[190:193], v[124:127]
	v_mfma_f32_16x16x32_bf16 v[120:123], v[166:169], v[190:193], v[120:123]
	v_mfma_f32_16x16x32_bf16 v[104:107], v[144:147], v[198:201], v[104:107]
	v_mfma_f32_16x16x32_bf16 v[108:111], v[166:169], v[198:201], v[108:111]
	v_mfma_f32_16x16x32_bf16 v[88:91], v[144:147], v[206:209], v[88:91]
	v_mfma_f32_16x16x32_bf16 v[92:95], v[166:169], v[206:209], v[92:95]
	v_mfma_f32_16x16x32_bf16 v[72:75], v[144:147], v[214:217], v[72:75]
	v_mfma_f32_16x16x32_bf16 v[76:79], v[166:169], v[214:217], v[76:79]
	v_mfma_f32_16x16x32_bf16 v[124:127], v[162:165], v[194:197], v[124:127]
	v_mfma_f32_16x16x32_bf16 v[120:123], v[170:173], v[194:197], v[120:123]
	v_mfma_f32_16x16x32_bf16 v[104:107], v[162:165], v[202:205], v[104:107]
	v_mfma_f32_16x16x32_bf16 v[108:111], v[170:173], v[202:205], v[108:111]
	v_mfma_f32_16x16x32_bf16 v[88:91], v[162:165], v[210:213], v[88:91]
	v_mfma_f32_16x16x32_bf16 v[92:95], v[170:173], v[210:213], v[92:95]
	v_mfma_f32_16x16x32_bf16 v[72:75], v[162:165], v[218:221], v[72:75]
	v_mfma_f32_16x16x32_bf16 v[76:79], v[170:173], v[218:221], v[76:79]
	s_setprio 0
	s_setprio 1
	v_mfma_f32_16x16x32_bf16 v[116:119], v[174:177], v[190:193], v[116:119]
	v_mfma_f32_16x16x32_bf16 v[112:115], v[182:185], v[190:193], v[112:115]
	v_mfma_f32_16x16x32_bf16 v[100:103], v[174:177], v[198:201], v[100:103]
	v_mfma_f32_16x16x32_bf16 v[96:99], v[182:185], v[198:201], v[96:99]
	v_mfma_f32_16x16x32_bf16 v[84:87], v[174:177], v[206:209], v[84:87]
	v_mfma_f32_16x16x32_bf16 v[80:83], v[182:185], v[206:209], v[80:83]
	v_mfma_f32_16x16x32_bf16 v[68:71], v[174:177], v[214:217], v[68:71]
	v_mfma_f32_16x16x32_bf16 v[64:67], v[182:185], v[214:217], v[64:67]
	v_mfma_f32_16x16x32_bf16 v[116:119], v[178:181], v[194:197], v[116:119]
	v_mfma_f32_16x16x32_bf16 v[112:115], v[186:189], v[194:197], v[112:115]
	v_mfma_f32_16x16x32_bf16 v[100:103], v[178:181], v[202:205], v[100:103]
	v_mfma_f32_16x16x32_bf16 v[96:99], v[186:189], v[202:205], v[96:99]
	v_mfma_f32_16x16x32_bf16 v[84:87], v[178:181], v[210:213], v[84:87]
	v_mfma_f32_16x16x32_bf16 v[80:83], v[186:189], v[210:213], v[80:83]
	v_mfma_f32_16x16x32_bf16 v[68:71], v[178:181], v[218:221], v[68:71]
	v_mfma_f32_16x16x32_bf16 v[64:67], v[186:189], v[218:221], v[64:67]
	s_setprio 0
	s_barrier
	s_add_i32 s74, s66, s33
	v_lshl_add_u64 v[148:149], s[44:45], 0, v[130:131]
	s_mov_b32 m0, s74
	ds_read_b128 v[190:193], v156 offset:16384
	ds_read_b128 v[194:197], v156 offset:17408
	ds_read_b128 v[198:201], v156 offset:18432
	ds_read_b128 v[202:205], v156 offset:19456
	ds_read_b128 v[206:209], v156 offset:20480
	ds_read_b128 v[210:213], v156 offset:21504
	ds_read_b128 v[214:217], v156 offset:22528
	ds_read_b128 v[218:221], v156 offset:23552
	global_load_lds_dwordx4 v[148:149], off
	s_add_i32 m0, s74, 0x2000
	s_add_u32 s74, s44, 0xb0000
	v_lshl_add_u64 v[222:223], s[44:45], 0, v[134:135]
	s_addc_u32 s75, s45, 0
	s_add_i32 s76, s67, s33
	global_load_lds_dwordx4 v[222:223], off
	v_lshl_add_u64 v[224:225], s[74:75], 0, v[130:131]
	s_mov_b32 m0, s76
	v_lshl_add_u64 v[226:227], s[46:47], 0, v[132:133]
	global_load_lds_dwordx4 v[224:225], off
	v_lshl_add_u64 v[224:225], s[74:75], 0, v[134:135]
	s_add_i32 m0, s76, 0x2000
	s_nop 0
	global_load_lds_dwordx4 v[224:225], off
	s_waitcnt vmcnt(6)
	s_waitcnt lgkmcnt(0)
	s_barrier
; #define PG8_STAGE(bufoff, gbase, voff) do { _Pragma("unroll") for (int _i = 0; _i < 2; ++_i) \
;         __builtin_amdgcn_global_load_lds((const unsigned*)((const char*)(gbase) + (voff)[_i]), (PG8_LAS unsigned*)(lds + (bufoff) + ldsw + _i * 8192), 16, 0, 0); } while (0)
; #define PG8_LDA(dst, b, h) do { _Pragma("unroll") for (int m = 0; m < 4; ++m) _Pragma("unroll") for (int k = 0; k < 2; ++k) dst[m][k] = *(const PG8_LAS bf16x8*)(lds + PG8_SA(b, h) + aoff + m * 2048 + k * 1024); } while (0)
; #define PG8_LDB(dst, b, h) do { _Pragma("unroll") for (int n = 0; n < 2; ++n) _Pragma("unroll") for (int k = 0; k < 2; ++k) dst[n][k] = *(const PG8_LAS bf16x8*)(lds + PG8_SB(b, h) + boff + n * 2048 + k * 1024); } while (0)
; #define PG8_MMA(ai, bj, At, Bt) do { __builtin_amdgcn_s_setprio(1); _Pragma("unroll") for (int m = 0; m < 4; ++m) _Pragma("unroll") for (int n = 0; n < 2; ++n) _Pragma("unroll") for (int k = 0; k < 2; ++k) \
;         acc[ai][bj][m][n] = __builtin_amdgcn_mfma_f32_16x16x32_bf16(Bt[n][k], At[m][k], acc[ai][bj][m][n], 0, 0, 0); __builtin_amdgcn_s_setprio(0); } while (0)
; #define PG8_WAIT_V(n) asm volatile("s_waitcnt vmcnt(" #n ")" ::: "memory")
; #define PG8_WAIT_L(n) asm volatile("s_waitcnt lgkmcnt(" #n ")" ::: "memory")
; #define PG8_BAR __builtin_amdgcn_s_barrier()
; #define PG8_SCHED __builtin_amdgcn_sched_barrier(0)
; template <class Epi, class Sched, bool ALIGN_EPI = false, bool SP2 = false>
; __device__ __forceinline__ void gemm_phase(PG8_LAS unsigned char* lds, const Gemm g, const Sched& S, const Epi& E) {
;     ...
;             PG8_WAIT_V(8); PG8_WAIT_L(0); PG8_BAR; PG8_MMA(1, 0, At, B0); PG8_MMA(1, 1, At, B1); PG8_BAR; PG8_SCHED;
;             PG8_LDB(B0, 1, 0); PG8_LDB(B1, 1, 1); PG8_SCHED; PG8_LDA(At, 1, 0); PG8_STAGE(PG8_SA(0, 1), a2 + hstep, voffA);
;             PG8_WAIT_V(8); PG8_WAIT_L(0); PG8_BAR; PG8_MMA(0, 0, At, B0); PG8_MMA(0, 1, At, B1); PG8_BAR; PG8_SCHED;
	s_setprio 1
	s_waitcnt lgkmcnt(0)
	v_mfma_f32_16x16x32_bf16 v[56:59], v[144:147], v[190:193], v[56:59]
	v_mfma_f32_16x16x32_bf16 v[60:63], v[166:169], v[190:193], v[60:63]
	v_mfma_f32_16x16x32_bf16 v[40:43], v[144:147], v[198:201], v[40:43]
	v_mfma_f32_16x16x32_bf16 v[44:47], v[166:169], v[198:201], v[44:47]
	v_mfma_f32_16x16x32_bf16 v[24:27], v[144:147], v[206:209], v[24:27]
	v_mfma_f32_16x16x32_bf16 v[28:31], v[166:169], v[206:209], v[28:31]
	v_lshl_add_u64 v[224:225], s[46:47], 0, v[128:129]
	s_mov_b32 m0, s48
	s_nop 0
	global_load_lds_dwordx4 v[224:225], off
	v_mfma_f32_16x16x32_bf16 v[8:11], v[144:147], v[214:217], v[8:11]
	v_mfma_f32_16x16x32_bf16 v[12:15], v[166:169], v[214:217], v[12:15]
	v_mfma_f32_16x16x32_bf16 v[56:59], v[162:165], v[194:197], v[56:59]
	v_mfma_f32_16x16x32_bf16 v[60:63], v[170:173], v[194:197], v[60:63]
	v_mfma_f32_16x16x32_bf16 v[40:43], v[162:165], v[202:205], v[40:43]
	v_mfma_f32_16x16x32_bf16 v[44:47], v[170:173], v[202:205], v[44:47]
	v_mfma_f32_16x16x32_bf16 v[24:27], v[162:165], v[210:213], v[24:27]
	v_mfma_f32_16x16x32_bf16 v[28:31], v[170:173], v[210:213], v[28:31]
	v_mfma_f32_16x16x32_bf16 v[8:11], v[162:165], v[218:221], v[8:11]
	v_mfma_f32_16x16x32_bf16 v[12:15], v[170:173], v[218:221], v[12:15]
	s_setprio 0
	s_setprio 1
	v_mfma_f32_16x16x32_bf16 v[52:55], v[174:177], v[190:193], v[52:55]
	v_mfma_f32_16x16x32_bf16 v[48:51], v[182:185], v[190:193], v[48:51]
	v_mfma_f32_16x16x32_bf16 v[36:39], v[174:177], v[198:201], v[36:39]
	v_mfma_f32_16x16x32_bf16 v[32:35], v[182:185], v[198:201], v[32:35]
	v_mfma_f32_16x16x32_bf16 v[20:23], v[174:177], v[206:209], v[20:23]
	v_mfma_f32_16x16x32_bf16 v[16:19], v[182:185], v[206:209], v[16:19]
	s_mov_b32 m0, s49
	s_nop 0
	global_load_lds_dwordx4 v[226:227], off
	v_mfma_f32_16x16x32_bf16 v[4:7], v[174:177], v[214:217], v[4:7]
	v_mfma_f32_16x16x32_bf16 v[0:3], v[182:185], v[214:217], v[0:3]
	v_mfma_f32_16x16x32_bf16 v[52:55], v[178:181], v[194:197], v[52:55]
	v_mfma_f32_16x16x32_bf16 v[48:51], v[186:189], v[194:197], v[48:51]
	v_mfma_f32_16x16x32_bf16 v[36:39], v[178:181], v[202:205], v[36:39]
	v_mfma_f32_16x16x32_bf16 v[32:35], v[186:189], v[202:205], v[32:35]
	v_mfma_f32_16x16x32_bf16 v[20:23], v[178:181], v[210:213], v[20:23]
	v_mfma_f32_16x16x32_bf16 v[16:19], v[186:189], v[210:213], v[16:19]
	v_mfma_f32_16x16x32_bf16 v[4:7], v[178:181], v[218:221], v[4:7]
	v_mfma_f32_16x16x32_bf16 v[0:3], v[186:189], v[218:221], v[0:3]
	s_setprio 0
	s_barrier
	s_add_i32 s74, 0, 0x18000
	s_add_i32 s75, 0, 0x1c000
	v_add_u32_e32 v170, s74, v151
	v_add_u32_e32 v186, s75, v151
	ds_read_b128 v[144:147], v170
	ds_read_b128 v[162:165], v170 offset:1024
	ds_read_b128 v[166:169], v170 offset:2048
	ds_read_b128 v[170:173], v170 offset:3072
	ds_read_b128 v[174:177], v186
	ds_read_b128 v[178:181], v186 offset:1024
	ds_read_b128 v[182:185], v186 offset:2048
	ds_read_b128 v[186:189], v186 offset:3072
	s_add_u32 s46, s46, 0xb0000
	s_addc_u32 s47, s47, 0
	s_mov_b32 m0, s50
	v_lshl_add_u64 v[228:229], s[46:47], 0, v[128:129]
	ds_read_b128 v[190:193], v156 offset:32768
	ds_read_b128 v[194:197], v156 offset:33792
	ds_read_b128 v[198:201], v156 offset:34816
	ds_read_b128 v[202:205], v156 offset:35840
	ds_read_b128 v[206:209], v156 offset:36864
	ds_read_b128 v[210:213], v156 offset:37888
	ds_read_b128 v[214:217], v156 offset:38912
	ds_read_b128 v[218:221], v156 offset:39936
	global_load_lds_dwordx4 v[228:229], off
	v_lshl_add_u64 v[228:229], s[46:47], 0, v[132:133]
	s_mov_b32 m0, s51
	s_nop 0
	global_load_lds_dwordx4 v[228:229], off
	s_waitcnt vmcnt(8)
	s_waitcnt lgkmcnt(0)
	s_barrier
	s_setprio 1
	s_waitcnt lgkmcnt(0)
	v_mfma_f32_16x16x32_bf16 v[124:127], v[144:147], v[190:193], v[124:127]
	v_mfma_f32_16x16x32_bf16 v[120:123], v[166:169], v[190:193], v[120:123]
	v_mfma_f32_16x16x32_bf16 v[104:107], v[144:147], v[198:201], v[104:107]
	v_mfma_f32_16x16x32_bf16 v[108:111], v[166:169], v[198:201], v[108:111]
	v_mfma_f32_16x16x32_bf16 v[88:91], v[144:147], v[206:209], v[88:91]
	v_mfma_f32_16x16x32_bf16 v[92:95], v[166:169], v[206:209], v[92:95]
	v_mfma_f32_16x16x32_bf16 v[72:75], v[144:147], v[214:217], v[72:75]
	v_mfma_f32_16x16x32_bf16 v[76:79], v[166:169], v[214:217], v[76:79]
	v_mfma_f32_16x16x32_bf16 v[124:127], v[162:165], v[194:197], v[124:127]
	v_mfma_f32_16x16x32_bf16 v[120:123], v[170:173], v[194:197], v[120:123]
	v_mfma_f32_16x16x32_bf16 v[104:107], v[162:165], v[202:205], v[104:107]
	v_mfma_f32_16x16x32_bf16 v[108:111], v[170:173], v[202:205], v[108:111]
	v_mfma_f32_16x16x32_bf16 v[88:91], v[162:165], v[210:213], v[88:91]
	v_mfma_f32_16x16x32_bf16 v[92:95], v[170:173], v[210:213], v[92:95]
	v_mfma_f32_16x16x32_bf16 v[72:75], v[162:165], v[218:221], v[72:75]
	v_mfma_f32_16x16x32_bf16 v[76:79], v[170:173], v[218:221], v[76:79]
	s_setprio 0
	s_setprio 1
	v_mfma_f32_16x16x32_bf16 v[116:119], v[174:177], v[190:193], v[116:119]
	v_mfma_f32_16x16x32_bf16 v[112:115], v[182:185], v[190:193], v[112:115]
	v_mfma_f32_16x16x32_bf16 v[100:103], v[174:177], v[198:201], v[100:103]
	v_mfma_f32_16x16x32_bf16 v[96:99], v[182:185], v[198:201], v[96:99]
	v_mfma_f32_16x16x32_bf16 v[84:87], v[174:177], v[206:209], v[84:87]
	v_mfma_f32_16x16x32_bf16 v[80:83], v[182:185], v[206:209], v[80:83]
	v_mfma_f32_16x16x32_bf16 v[68:71], v[174:177], v[214:217], v[68:71]
	v_mfma_f32_16x16x32_bf16 v[64:67], v[182:185], v[214:217], v[64:67]
	v_mfma_f32_16x16x32_bf16 v[116:119], v[178:181], v[194:197], v[116:119]
	v_mfma_f32_16x16x32_bf16 v[112:115], v[186:189], v[194:197], v[112:115]
	v_mfma_f32_16x16x32_bf16 v[100:103], v[178:181], v[202:205], v[100:103]
	v_mfma_f32_16x16x32_bf16 v[96:99], v[186:189], v[202:205], v[96:99]
	v_mfma_f32_16x16x32_bf16 v[84:87], v[178:181], v[210:213], v[84:87]
	v_mfma_f32_16x16x32_bf16 v[80:83], v[186:189], v[210:213], v[80:83]
	v_mfma_f32_16x16x32_bf16 v[68:71], v[178:181], v[218:221], v[68:71]
	v_mfma_f32_16x16x32_bf16 v[64:67], v[186:189], v[218:221], v[64:67]
	s_setprio 0
	s_barrier
; #define PG8_STAGE(bufoff, gbase, voff) do { _Pragma("unroll") for (int _i = 0; _i < 2; ++_i) \
;         __builtin_amdgcn_global_load_lds((const unsigned*)((const char*)(gbase) + (voff)[_i]), (PG8_LAS unsigned*)(lds + (bufoff) + ldsw + _i * 8192), 16, 0, 0); } while (0)
; #define PG8_LDA(dst, b, h) do { _Pragma("unroll") for (int m = 0; m < 4; ++m) _Pragma("unroll") for (int k = 0; k < 2; ++k) dst[m][k] = *(const PG8_LAS bf16x8*)(lds + PG8_SA(b, h) + aoff + m * 2048 + k * 1024); } while (0)
; #define PG8_MMA(ai, bj, At, Bt) do { __builtin_amdgcn_s_setprio(1); _Pragma("unroll") for (int m = 0; m < 4; ++m) _Pragma("unroll") for (int n = 0; n < 2; ++n) _Pragma("unroll") for (int k = 0; k < 2; ++k) \
;         acc[ai][bj][m][n] = __builtin_amdgcn_mfma_f32_16x16x32_bf16(Bt[n][k], At[m][k], acc[ai][bj][m][n], 0, 0, 0); __builtin_amdgcn_s_setprio(0); } while (0)
; #define PG8_WAIT_V(n) asm volatile("s_waitcnt vmcnt(" #n ")" ::: "memory")
; #define PG8_WAIT_L(n) asm volatile("s_waitcnt lgkmcnt(" #n ")" ::: "memory")
; #define PG8_BAR __builtin_amdgcn_s_barrier()
; #define PG8_SCHED __builtin_amdgcn_sched_barrier(0)
; template <class Epi, class Sched, bool ALIGN_EPI = false, bool SP2 = false>
; __device__ __forceinline__ void gemm_phase(PG8_LAS unsigned char* lds, const Gemm g, const Sched& S, const Epi& E) {
;     ...
;             PG8_LDA(At, 1, 1); PG8_STAGE(PG8_SB(1, 0), b3, voffB); PG8_STAGE(PG8_SB(1, 1), b3 + hstep, voffB); PG8_STAGE(PG8_SA(1, 0), a3, voffA);
;             PG8_WAIT_V(8); PG8_WAIT_L(0); PG8_BAR; PG8_MMA(1, 0, At, B0); PG8_MMA(1, 1, At, B1); PG8_BAR; PG8_SCHED;
	s_add_i32 s46, s74, s33
	v_lshl_add_u64 v[148:149], v[148:149], 0, s[12:13]
	s_mov_b32 m0, s46
	ds_read_b128 v[190:193], v156 offset:49152
	ds_read_b128 v[194:197], v156 offset:50176
	ds_read_b128 v[198:201], v156 offset:51200
	ds_read_b128 v[202:205], v156 offset:52224
	ds_read_b128 v[206:209], v156 offset:53248
	ds_read_b128 v[210:213], v156 offset:54272
	ds_read_b128 v[214:217], v156 offset:55296
	ds_read_b128 v[218:221], v156 offset:56320
	global_load_lds_dwordx4 v[148:149], off
	s_add_i32 m0, s46, 0x2000
	s_add_u32 s44, s44, 0xb0080
	v_lshl_add_u64 v[148:149], v[222:223], 0, s[12:13]
	s_addc_u32 s45, s45, 0
	s_add_i32 s46, s75, s33
	global_load_lds_dwordx4 v[148:149], off
	v_lshl_add_u64 v[148:149], s[44:45], 0, v[130:131]
	s_mov_b32 m0, s46
	s_nop 0
	global_load_lds_dwordx4 v[148:149], off
	v_lshl_add_u64 v[148:149], s[44:45], 0, v[134:135]
	s_add_i32 m0, s46, 0x2000
	s_nop 0
	global_load_lds_dwordx4 v[148:149], off
	s_waitcnt vmcnt(6)
	s_waitcnt lgkmcnt(0)
	s_barrier
	s_setprio 1
	s_waitcnt lgkmcnt(0)
	v_mfma_f32_16x16x32_bf16 v[56:59], v[144:147], v[190:193], v[56:59]
	v_mfma_f32_16x16x32_bf16 v[60:63], v[166:169], v[190:193], v[60:63]
	v_mfma_f32_16x16x32_bf16 v[40:43], v[144:147], v[198:201], v[40:43]
	v_mfma_f32_16x16x32_bf16 v[44:47], v[166:169], v[198:201], v[44:47]
	v_mfma_f32_16x16x32_bf16 v[24:27], v[144:147], v[206:209], v[24:27]
	v_mfma_f32_16x16x32_bf16 v[28:31], v[166:169], v[206:209], v[28:31]
	v_lshl_add_u64 v[148:149], v[224:225], 0, s[12:13]
	s_mov_b32 m0, s53
	s_nop 0
	global_load_lds_dwordx4 v[148:149], off
	v_mfma_f32_16x16x32_bf16 v[8:11], v[144:147], v[214:217], v[8:11]
	v_mfma_f32_16x16x32_bf16 v[12:15], v[166:169], v[214:217], v[12:15]
	v_mfma_f32_16x16x32_bf16 v[56:59], v[162:165], v[194:197], v[56:59]
	v_mfma_f32_16x16x32_bf16 v[60:63], v[170:173], v[194:197], v[60:63]
	v_mfma_f32_16x16x32_bf16 v[40:43], v[162:165], v[202:205], v[40:43]
	v_mfma_f32_16x16x32_bf16 v[44:47], v[170:173], v[202:205], v[44:47]
	v_mfma_f32_16x16x32_bf16 v[24:27], v[162:165], v[210:213], v[24:27]
	v_mfma_f32_16x16x32_bf16 v[28:31], v[170:173], v[210:213], v[28:31]
	v_mfma_f32_16x16x32_bf16 v[8:11], v[162:165], v[218:221], v[8:11]
	v_mfma_f32_16x16x32_bf16 v[12:15], v[170:173], v[218:221], v[12:15]
	s_setprio 0
	s_setprio 1
	v_mfma_f32_16x16x32_bf16 v[52:55], v[174:177], v[190:193], v[52:55]
	v_mfma_f32_16x16x32_bf16 v[48:51], v[182:185], v[190:193], v[48:51]
	v_mfma_f32_16x16x32_bf16 v[36:39], v[174:177], v[198:201], v[36:39]
	v_mfma_f32_16x16x32_bf16 v[32:35], v[182:185], v[198:201], v[32:35]
	v_mfma_f32_16x16x32_bf16 v[20:23], v[174:177], v[206:209], v[20:23]
	v_mfma_f32_16x16x32_bf16 v[16:19], v[182:185], v[206:209], v[16:19]
	v_lshl_add_u64 v[148:149], v[226:227], 0, s[12:13]
	s_mov_b32 m0, s60
	s_nop 0
	global_load_lds_dwordx4 v[148:149], off
	v_mfma_f32_16x16x32_bf16 v[4:7], v[174:177], v[214:217], v[4:7]
	v_mfma_f32_16x16x32_bf16 v[0:3], v[182:185], v[214:217], v[0:3]
	v_mfma_f32_16x16x32_bf16 v[52:55], v[178:181], v[194:197], v[52:55]
	v_mfma_f32_16x16x32_bf16 v[48:51], v[186:189], v[194:197], v[48:51]
	v_mfma_f32_16x16x32_bf16 v[36:39], v[178:181], v[202:205], v[36:39]
	v_mfma_f32_16x16x32_bf16 v[32:35], v[186:189], v[202:205], v[32:35]
	v_mfma_f32_16x16x32_bf16 v[20:23], v[178:181], v[210:213], v[20:23]
	v_mfma_f32_16x16x32_bf16 v[16:19], v[186:189], v[210:213], v[16:19]
	v_mfma_f32_16x16x32_bf16 v[4:7], v[178:181], v[218:221], v[4:7]
	v_mfma_f32_16x16x32_bf16 v[0:3], v[186:189], v[218:221], v[0:3]
	s_setprio 0
	s_barrier
	s_add_i32 s73, s73, 2
	s_add_u32 s4, s4, 0x100
	s_addc_u32 s5, s5, 0
	s_add_u32 s43, s43, 0x100
	s_addc_u32 s72, s72, 0
	s_cmp_gt_u32 s73, 41
	s_cbranch_scc0 .LBB0_970
	s_and_b64 vcc, exec, s[14:15]
	s_cbranch_vccz .LBB0_973
	s_barrier
